# remaining first fragment reads of the next tile moved to the end of the epilogue (all 16 super-phase-0 reads now issued before the tile header)
# baseline (speedup 1.0000x reference)
; #define PG8_STAGE(bufoff, gbase, voff) do { _Pragma("unroll") for (int _i = 0; _i < 2; ++_i) \
;         __builtin_amdgcn_global_load_lds((const unsigned*)((const char*)(gbase) + (voff)[_i]), (PG8_LAS unsigned*)(lds + (bufoff) + ldsw + _i * 8192), 16, 0, 0); } while (0)
; #define PG8_WAIT_V(n) asm volatile("s_waitcnt vmcnt(" #n ")" ::: "memory")
; #define PG8_BAR __builtin_amdgcn_s_barrier()
; template <class Epi, class Sched, bool ALIGN_EPI = false, bool SP2 = false>
; __device__ __forceinline__ void gemm_phase(PG8_LAS unsigned char* lds, const Gemm g, const Sched& S, const Epi& E) {
;     ...
;     const int tid = tid_, wid = __builtin_amdgcn_readfirstlane(tid >> 6), lane = tid & 63, wr = wid >> 2, wc = wid & 3, fr = lane & 15, fq = lane >> 4;
;     const int K = g.K, nt = K / BK;
;     unsigned voffA[2], voffB[2];
; #pragma unroll
;     for (int i = 0; i < 2; ++i) { int R, C; stage_rc(tid * 16 + i * 8192, R, C); const int Rb = Epi::PERM ? ((R & ~31) + perm32(R & 31)) : R;
;         voffA[i] = (unsigned)(R * K + C) * 2u; voffB[i] = (unsigned)(Rb * K + C) * 2u; }
;     const size_t kstep = (size_t)(BK * 2);
;     const size_t hstep = (size_t)HALF * K * 2;
;     const size_t tstep = 2 * hstep;
;     const unsigned ldsw = (unsigned)wid * 1024u;
;     const int aoff = lds_byte(wr * 64 + fr, fq * 8), boff = lds_byte(wc * 32 + fr, fq * 8);
;     ...
;         PG8_STAGE(PG8_SB(0, 0), cB, voffB); PG8_STAGE(PG8_SB(0, 1), cB + hstep, voffB); PG8_STAGE(PG8_SA(0, 0), cA, voffA); PG8_STAGE(PG8_SA(0, 1), cA + hstep, voffA);
;         if (wr == 1) PG8_BAR;
;         PG8_WAIT_V(2); PG8_BAR;
;         PG8_STAGE(PG8_SB(1, 0), cB + kstep, voffB); PG8_STAGE(PG8_SB(1, 1), cB + hstep + kstep, voffB);
;         PG8_WAIT_V(4); PG8_BAR;
.LBB0_202:
	s_add_u32 s94, s36, 0x19000000
	s_addc_u32 s95, s37, 0
	s_lshl_b32 s6, s6, 5
	s_and_b32 s17, s6, 0x60
	s_add_i32 m0, s97, 0x18000
	v_lshl_add_u64 v[0:1], v[0:1], 0, s[26:27]
	s_lshl_b32 s16, s5, 13
	s_lshl_b32 s34, s17, 7
	s_waitcnt vmcnt(2)
	s_barrier
	global_load_lds_dwordx4 v[0:1], off
	s_add_i32 m0, s97, 0x1a000
	s_add_u32 s6, s10, 0x80080
	v_lshl_add_u64 v[0:1], v[2:3], 0, s[26:27]
	s_addc_u32 s7, s11, 0
	global_load_lds_dwordx4 v[0:1], off
	s_add_i32 m0, s97, 0x1c000
	v_lshl_add_u64 v[0:1], s[6:7], 0, v[204:205]
	global_load_lds_dwordx4 v[0:1], off
	v_lshl_add_u64 v[0:1], s[6:7], 0, v[128:129]
	s_add_i32 m0, s97, 0x1e000
	s_cmpk_lt_u32 s4, 0x100
	global_load_lds_dwordx4 v[0:1], off
	v_lshrrev_b32_e32 v1, 1, v5
	v_and_b32_e32 v1, 24, v1
	v_and_b32_e32 v0, 15, v5
	v_lshlrev_b32_e32 v2, 1, v1
	v_lshl_or_b32 v146, s5, 6, v0
	v_lshl_or_b32 v0, v0, 6, v2
	v_lshlrev_b32_e32 v2, 2, v5
	v_and_b32_e32 v2, 32, v2
	v_bitop3_b32 v3, v0, s16, v2 bitop3:0xde
	v_bitop3_b32 v147, v0, s34, v2 bitop3:0xde
	v_lshlrev_b32_e32 v0, 15, v9
	v_and_b32_e32 v0, 0xffff0000, v0
	v_or_b32_e32 v148, s17, v1
	v_lshl_add_u32 v0, v8, 12, v0
	v_and_b32_e32 v1, 1, v9
	v_lshl_or_b32 v0, v1, 6, v0
	v_lshl_add_u32 v134, v10, 1, v0
	v_lshlrev_b32_e32 v0, 15, v4
	v_and_b32_e32 v0, 0xffff0000, v0
	s_waitcnt vmcnt(4)
	v_lshl_add_u32 v0, v6, 12, v0
	v_and_b32_e32 v1, 1, v4
	v_lshl_or_b32 v0, v1, 6, v0
	v_readlane_b32 s4, v254, 61
	v_mov_b32_e32 v133, v205
	v_mov_b32_e32 v131, v205
	s_cselect_b64 s[76:77], -1, 0
	v_mov_b32_e32 v135, v205
	v_lshl_add_u32 v136, v7, 1, v0
	v_mov_b32_e32 v137, v205
	s_mov_b32 s84, 0
	v_add_u32_e32 v149, 0, v3
	v_readlane_b32 s34, v254, 54
	s_mov_b32 s35, s4
	s_barrier
	v_readlane_b32 s5, v254, 62
	v_add_u32_e32 v174, 0x14000, v147
	ds_read_b128 v[162:165], v174
	ds_read_b128 v[166:169], v174 offset:1024
	ds_read_b128 v[170:173], v174 offset:2048
	ds_read_b128 v[174:177], v174 offset:3072
	ds_read_b128 v[178:181], v149
	ds_read_b128 v[182:185], v149 offset:1024
	ds_read_b128 v[186:189], v149 offset:2048
	ds_read_b128 v[190:193], v149 offset:3072
	ds_read_b128 v[194:197], v149 offset:4096
	ds_read_b128 v[198:201], v149 offset:5120
	ds_read_b128 v[218:221], v149 offset:6144
	ds_read_b128 v[232:235], v149 offset:7168
	v_add_u32_e32 v158, 0x10000, v147
	ds_read_b128 v[142:145], v158
	ds_read_b128 v[150:153], v158 offset:1024
	ds_read_b128 v[154:157], v158 offset:2048
	ds_read_b128 v[158:161], v158 offset:3072
	s_branch .LBB0_205

; #define PG8_STAGE(bufoff, gbase, voff) do { _Pragma("unroll") for (int _i = 0; _i < 2; ++_i) \
;         __builtin_amdgcn_global_load_lds((const unsigned*)((const char*)(gbase) + (voff)[_i]), (PG8_LAS unsigned*)(lds + (bufoff) + ldsw + _i * 8192), 16, 0, 0); } while (0)
; #define PG8_LDA(dst, b, h) do { _Pragma("unroll") for (int m = 0; m < 4; ++m) _Pragma("unroll") for (int k = 0; k < 2; ++k) dst[m][k] = *(const PG8_LAS bf16x8*)(lds + PG8_SA(b, h) + aoff + m * 2048 + k * 1024); } while (0)
; #define PG8_LDB(dst, b, h) do { _Pragma("unroll") for (int n = 0; n < 2; ++n) _Pragma("unroll") for (int k = 0; k < 2; ++k) dst[n][k] = *(const PG8_LAS bf16x8*)(lds + PG8_SB(b, h) + boff + n * 2048 + k * 1024); } while (0)
; #define PG8_MMA(ai, bj, At, Bt) do { __builtin_amdgcn_s_setprio(1); _Pragma("unroll") for (int m = 0; m < 4; ++m) _Pragma("unroll") for (int n = 0; n < 2; ++n) _Pragma("unroll") for (int k = 0; k < 2; ++k) \
;         acc[ai][bj][m][n] = __builtin_amdgcn_mfma_f32_16x16x32_bf16(Bt[n][k], At[m][k], acc[ai][bj][m][n], 0, 0, 0); __builtin_amdgcn_s_setprio(0); } while (0)
; #define PG8_WAIT_V(n) asm volatile("s_waitcnt vmcnt(" #n ")" ::: "memory")
; #define PG8_WAIT_L(n) asm volatile("s_waitcnt lgkmcnt(" #n ")" ::: "memory")
; template <class Epi, class Sched, bool ALIGN_EPI = false, bool SP2 = false>
; __device__ __forceinline__ void gemm_phase(PG8_LAS unsigned char* lds, const Gemm g, const Sched& S, const Epi& E) {
;     ...
;         const bool has_next = S.next(ui + 1, nxt);
;         const char* nA = has_next ? (const char*)g.A + (size_t)nxt.pm * tstep : cA; const char* nB = has_next ? (const char*)g.Bt + (size_t)nxt.pn * tstep : cB;
;         for (int t = 0; t < nt; t += 2) {
;             const bool last = (t == nt - 2);
;             const char* a1 = cA + (size_t)(t + 1) * kstep;
;             const char* a2 = last ? nA : cA + (size_t)(t + 2) * kstep; const char* b2 = last ? nB : cB + (size_t)(t + 2) * kstep;
;             const char* a3 = a2 + kstep; const char* b3 = b2 + kstep;
;             if (last && has_next) S.a_ready(nxt);
;             if constexpr (SP2) {
;             PG8_LDB(B0, 0, 0); PG8_LDB(B1, 0, 1); PG8_SCHED; PG8_LDA(At, 0, 0); PG8_STAGE(PG8_SA(1, 0), a1, voffA); PG8_STAGE(PG8_SA(1, 1), a1 + hstep, voffA);
;             PG8_WAIT_V(8); PG8_WAIT_L(0); PG8_BAR; PG8_MMA(0, 0, At, B0); PG8_MMA(0, 1, At, B1); PG8_BAR; PG8_SCHED;
.LBB0_211:
	s_ashr_i32 s89, s88, 31
	s_lshl_b64 s[4:5], s[88:89], 20
	s_add_u32 s4, s22, s4
	s_addc_u32 s5, s75, s5
	s_and_b64 s[6:7], s[38:39], exec
	s_cselect_b32 s89, s5, s9
	s_cselect_b32 vcc_lo, s4, s8
	s_ashr_i32 s73, s72, 31
	s_lshl_b64 s[6:7], s[72:73], 20
	s_add_u32 s6, s68, s6
	s_addc_u32 s7, s69, s7
	s_and_b64 s[16:17], s[38:39], exec
	s_cselect_b32 s70, s7, s11
	s_cselect_b32 s71, s6, s10
	s_add_u32 s73, s10, 0x100
	s_addc_u32 vcc_hi, s11, 0
	s_mov_b32 s52, -2
	s_mov_b64 s[10:11], 0
	v_lshl_add_u64 v[138:139], s[8:9], 0, v[134:135]
	v_lshl_add_u64 v[140:141], s[8:9], 0, v[136:137]
	v_lshl_add_u32 v240, s35, 8, v146
	v_ashrrev_i32_e32 v241, 31, v240
	v_lshl_add_u64 v[240:241], v[240:241], 2, s[42:43]
	global_load_dword v242, v[240:241], off
	global_load_dword v243, v[240:241], off offset:64
	global_load_dword v244, v[240:241], off offset:128
	global_load_dword v245, v[240:241], off offset:192
	global_load_dword v246, v[240:241], off offset:512
	global_load_dword v247, v[240:241], off offset:576
	global_load_dword v248, v[240:241], off offset:640
	global_load_dword v249, v[240:241], off offset:704
	s_add_u32 s16, s8, s10
	s_addc_u32 s17, s9, s11
	s_add_u32 s44, s16, 0x100
	s_addc_u32 s45, s17, 0
	s_add_u32 s16, s73, s10
	s_addc_u32 s17, vcc_hi, s11
	s_add_i32 s53, 0, 0x10000
	s_cmpk_eq_i32 s10, 0xf00
	s_cselect_b32 s17, s70, s17
	s_cselect_b32 s16, s71, s16
	s_cselect_b32 s45, s89, s45
	s_cselect_b32 s44, vcc_lo, s44
	s_add_i32 s92, 0, 0x14000
	v_lshl_add_u64 v[202:203], v[138:139], 0, s[10:11]
	v_lshl_add_u64 v[206:207], v[202:203], 0, s[26:27]
	s_add_i32 m0, s97, 0x8000
	global_load_lds_dwordx4 v[206:207], off
	v_lshl_add_u64 v[206:207], v[140:141], 0, s[10:11]
	v_lshl_add_u64 v[208:209], v[206:207], 0, s[26:27]
	s_add_i32 m0, s97, 0xa000
	v_lshl_add_u64 v[202:203], v[202:203], 0, s[28:29]
	global_load_lds_dwordx4 v[208:209], off
	s_add_i32 m0, s97, 0xc000
	s_nop 0
	global_load_lds_dwordx4 v[202:203], off
	v_lshl_add_u64 v[202:203], v[206:207], 0, s[28:29]
	s_add_i32 m0, s97, 0xe000
	s_nop 0
	global_load_lds_dwordx4 v[202:203], off
	s_waitcnt vmcnt(8)
	s_waitcnt lgkmcnt(0)
	s_barrier
	v_mfma_f32_16x16x32_bf16 v[124:127], v[142:145], v[178:181], 0
	v_mfma_f32_16x16x32_bf16 v[120:123], v[154:157], v[178:181], 0
	v_mfma_f32_16x16x32_bf16 v[108:111], v[142:145], v[186:189], 0
	v_mfma_f32_16x16x32_bf16 v[104:107], v[154:157], v[186:189], 0
	v_mfma_f32_16x16x32_bf16 v[92:95], v[142:145], v[194:197], 0
	v_mfma_f32_16x16x32_bf16 v[88:91], v[154:157], v[194:197], 0
	v_mfma_f32_16x16x32_bf16 v[76:79], v[142:145], v[218:221], 0
	v_mfma_f32_16x16x32_bf16 v[72:75], v[154:157], v[218:221], 0
	v_mfma_f32_16x16x32_bf16 v[124:127], v[150:153], v[182:185], v[124:127]
	v_mfma_f32_16x16x32_bf16 v[120:123], v[158:161], v[182:185], v[120:123]
	v_mfma_f32_16x16x32_bf16 v[108:111], v[150:153], v[190:193], v[108:111]
	v_mfma_f32_16x16x32_bf16 v[104:107], v[158:161], v[190:193], v[104:107]
	v_mfma_f32_16x16x32_bf16 v[92:95], v[150:153], v[198:201], v[92:95]
	v_mfma_f32_16x16x32_bf16 v[88:91], v[158:161], v[198:201], v[88:91]
	v_mfma_f32_16x16x32_bf16 v[76:79], v[150:153], v[232:235], v[76:79]
	v_mfma_f32_16x16x32_bf16 v[72:75], v[158:161], v[232:235], v[72:75]
	v_mfma_f32_16x16x32_bf16 v[116:119], v[162:165], v[178:181], 0
	v_mfma_f32_16x16x32_bf16 v[112:115], v[170:173], v[178:181], 0
	v_mfma_f32_16x16x32_bf16 v[100:103], v[162:165], v[186:189], 0
	v_mfma_f32_16x16x32_bf16 v[96:99], v[170:173], v[186:189], 0
	v_mfma_f32_16x16x32_bf16 v[84:87], v[162:165], v[194:197], 0
	v_mfma_f32_16x16x32_bf16 v[80:83], v[170:173], v[194:197], 0
	v_mfma_f32_16x16x32_bf16 v[68:71], v[162:165], v[218:221], 0
	v_mfma_f32_16x16x32_bf16 v[64:67], v[170:173], v[218:221], 0
	v_mfma_f32_16x16x32_bf16 v[116:119], v[166:169], v[182:185], v[116:119]
	v_mfma_f32_16x16x32_bf16 v[112:115], v[174:177], v[182:185], v[112:115]
	v_mfma_f32_16x16x32_bf16 v[100:103], v[166:169], v[190:193], v[100:103]
	v_mfma_f32_16x16x32_bf16 v[96:99], v[174:177], v[190:193], v[96:99]
	v_mfma_f32_16x16x32_bf16 v[84:87], v[166:169], v[198:201], v[84:87]
	v_mfma_f32_16x16x32_bf16 v[80:83], v[174:177], v[198:201], v[80:83]
	v_mfma_f32_16x16x32_bf16 v[68:71], v[166:169], v[232:235], v[68:71]
	v_mfma_f32_16x16x32_bf16 v[64:67], v[174:177], v[232:235], v[64:67]
	s_barrier
; #define PG8_STAGE(bufoff, gbase, voff) do { _Pragma("unroll") for (int _i = 0; _i < 2; ++_i) \
;         __builtin_amdgcn_global_load_lds((const unsigned*)((const char*)(gbase) + (voff)[_i]), (PG8_LAS unsigned*)(lds + (bufoff) + ldsw + _i * 8192), 16, 0, 0); } while (0)
; #define PG8_LDA(dst, b, h) do { _Pragma("unroll") for (int m = 0; m < 4; ++m) _Pragma("unroll") for (int k = 0; k < 2; ++k) dst[m][k] = *(const PG8_LAS bf16x8*)(lds + PG8_SA(b, h) + aoff + m * 2048 + k * 1024); } while (0)
; #define PG8_MMA(ai, bj, At, Bt) do { __builtin_amdgcn_s_setprio(1); _Pragma("unroll") for (int m = 0; m < 4; ++m) _Pragma("unroll") for (int n = 0; n < 2; ++n) _Pragma("unroll") for (int k = 0; k < 2; ++k) \
;         acc[ai][bj][m][n] = __builtin_amdgcn_mfma_f32_16x16x32_bf16(Bt[n][k], At[m][k], acc[ai][bj][m][n], 0, 0, 0); __builtin_amdgcn_s_setprio(0); } while (0)
; #define PG8_WAIT_V(n) asm volatile("s_waitcnt vmcnt(" #n ")" ::: "memory")
; #define PG8_WAIT_L(n) asm volatile("s_waitcnt lgkmcnt(" #n ")" ::: "memory")
; #define PG8_BAR __builtin_amdgcn_s_barrier()
; #define PG8_SCHED __builtin_amdgcn_sched_barrier(0)
; template <class Epi, class Sched, bool ALIGN_EPI = false, bool SP2 = false>
; __device__ __forceinline__ void gemm_phase(PG8_LAS unsigned char* lds, const Gemm g, const Sched& S, const Epi& E) {
;     ...
;             PG8_LDA(At, 0, 1); PG8_STAGE(PG8_SB(0, 0), b2, voffB); PG8_STAGE(PG8_SB(0, 1), b2 + hstep, voffB);
;             PG8_WAIT_V(6); PG8_WAIT_L(0); PG8_BAR; PG8_MMA(1, 0, At, B0); PG8_MMA(1, 1, At, B1); PG8_BAR; PG8_SCHED;
	s_add_i32 s53, s53, s23
	v_lshl_add_u64 v[202:203], s[16:17], 0, v[204:205]
	s_mov_b32 m0, s53
	ds_read_b128 v[178:181], v149 offset:16384
	ds_read_b128 v[182:185], v149 offset:17408
	ds_read_b128 v[186:189], v149 offset:18432
	ds_read_b128 v[190:193], v149 offset:19456
	ds_read_b128 v[194:197], v149 offset:20480
	ds_read_b128 v[198:201], v149 offset:21504
	ds_read_b128 v[218:221], v149 offset:22528
	ds_read_b128 v[232:235], v149 offset:23552
	global_load_lds_dwordx4 v[202:203], off
	s_add_i32 m0, s53, 0x2000
	s_add_u32 s78, s16, 0x80000
	v_lshl_add_u64 v[206:207], s[16:17], 0, v[128:129]
	s_addc_u32 s79, s17, 0
	s_add_i32 s53, s92, s23
	global_load_lds_dwordx4 v[206:207], off
	v_lshl_add_u64 v[208:209], s[78:79], 0, v[204:205]
	s_mov_b32 m0, s53
	s_nop 0
	global_load_lds_dwordx4 v[208:209], off
	v_lshl_add_u64 v[208:209], s[78:79], 0, v[128:129]
	s_add_i32 m0, s53, 0x2000
	s_nop 0
	global_load_lds_dwordx4 v[208:209], off
	s_waitcnt vmcnt(6)
	s_waitcnt lgkmcnt(0)
	s_barrier
	v_mfma_f32_16x16x32_bf16 v[60:63], v[142:145], v[178:181], 0
	v_mfma_f32_16x16x32_bf16 v[56:59], v[154:157], v[178:181], 0
	v_mfma_f32_16x16x32_bf16 v[44:47], v[142:145], v[186:189], 0
	v_mfma_f32_16x16x32_bf16 v[40:43], v[154:157], v[186:189], 0
	v_mfma_f32_16x16x32_bf16 v[28:31], v[142:145], v[194:197], 0
	v_mfma_f32_16x16x32_bf16 v[24:27], v[154:157], v[194:197], 0
	v_mfma_f32_16x16x32_bf16 v[12:15], v[142:145], v[218:221], 0
	v_mfma_f32_16x16x32_bf16 v[8:11], v[154:157], v[218:221], 0
	v_mfma_f32_16x16x32_bf16 v[60:63], v[150:153], v[182:185], v[60:63]
	v_mfma_f32_16x16x32_bf16 v[56:59], v[158:161], v[182:185], v[56:59]
	v_mfma_f32_16x16x32_bf16 v[44:47], v[150:153], v[190:193], v[44:47]
	v_mfma_f32_16x16x32_bf16 v[40:43], v[158:161], v[190:193], v[40:43]
	v_mfma_f32_16x16x32_bf16 v[28:31], v[150:153], v[198:201], v[28:31]
	v_mfma_f32_16x16x32_bf16 v[24:27], v[158:161], v[198:201], v[24:27]
	v_mfma_f32_16x16x32_bf16 v[12:15], v[150:153], v[232:235], v[12:15]
	v_mfma_f32_16x16x32_bf16 v[8:11], v[158:161], v[232:235], v[8:11]
	v_mfma_f32_16x16x32_bf16 v[52:55], v[162:165], v[178:181], 0
	v_mfma_f32_16x16x32_bf16 v[48:51], v[170:173], v[178:181], 0
	v_mfma_f32_16x16x32_bf16 v[36:39], v[162:165], v[186:189], 0
	v_mfma_f32_16x16x32_bf16 v[32:35], v[170:173], v[186:189], 0
	v_mfma_f32_16x16x32_bf16 v[20:23], v[162:165], v[194:197], 0
	v_mfma_f32_16x16x32_bf16 v[16:19], v[170:173], v[194:197], 0
	v_mfma_f32_16x16x32_bf16 v[4:7], v[162:165], v[218:221], 0
	v_mfma_f32_16x16x32_bf16 v[0:3], v[170:173], v[218:221], 0
	v_mfma_f32_16x16x32_bf16 v[52:55], v[166:169], v[182:185], v[52:55]
	v_mfma_f32_16x16x32_bf16 v[48:51], v[174:177], v[182:185], v[48:51]
	v_mfma_f32_16x16x32_bf16 v[36:39], v[166:169], v[190:193], v[36:39]
	v_mfma_f32_16x16x32_bf16 v[32:35], v[174:177], v[190:193], v[32:35]
	v_mfma_f32_16x16x32_bf16 v[20:23], v[166:169], v[198:201], v[20:23]
	v_mfma_f32_16x16x32_bf16 v[16:19], v[174:177], v[198:201], v[16:19]
	v_mfma_f32_16x16x32_bf16 v[4:7], v[166:169], v[232:235], v[4:7]
	v_mfma_f32_16x16x32_bf16 v[0:3], v[174:177], v[232:235], v[0:3]
	s_barrier
	s_branch .Lpl_qk

; __device__ __forceinline__ unsigned cvt_pk_bf16(float lo, float hi) { unsigned r; asm volatile("v_cvt_pk_bf16_f32 %0, %1, %2" : "=v"(r) : "v"(lo), "v"(hi)); return r; }
;     __device__ __forceinline__ void operator()(const f32x4 (&acc)[2][2][4][2], const Unit& u, int wr, int wc, int fr, int fq) const {
;         const int row0 = u.pm * BM + wr * 64 + fr; const int colt = u.pn * BM;
;         const float sc = (colt < scale_cols) ? scale0 : 1.f;
;         const int col0 = colt + wc * 32 + 8 * fq;
;         f32x4 cs[2][2];
; #pragma unroll
;         for (int bj = 0; bj < 2; ++bj) { cs[bj][0] = (f32x4){1.f, 1.f, 1.f, 1.f}; cs[bj][1] = cs[bj][0]; if (rsmode == 2) { cs[bj][0] = *(const f32x4*)(rs + col0 + bj * HALF); cs[bj][1] = *(const f32x4*)(rs + col0 + bj * HALF + 4); } }
; #pragma unroll
;         for (int ai = 0; ai < 2; ++ai)
; #pragma unroll
;             for (int m = 0; m < 4; ++m) { bf16_t* rowp = O + (size_t)(row0 + ai * HALF + m * 16) * ldc + col0;
;                 float rsc = sc; if (rsmode == 1) { const float r_ = rs[row0 + ai * HALF + m * 16]; rsc = sc * (ACT == 2 ? r_ * r_ : r_); }
; #pragma unroll
;                 for (int bj = 0; bj < 2; ++bj) { f32x4 v0 = acc[ai][bj][m][0], v1 = acc[ai][bj][m][1];
;                     if (ACT == 2) {
; #pragma unroll
;                         for (int e = 0; e < 4; ++e) { const float a0 = fmaxf(v0[e], 0.f), a1 = fmaxf(v1[e], 0.f); v0[e] = a0 * a0; v1[e] = a1 * a1; } }
;                     v0 = v0 * cs[bj][0] * rsc; v1 = v1 * cs[bj][1] * rsc; u32x4 w; w.x = cvt_pk_bf16(v0[0], v0[1]); w.y = cvt_pk_bf16(v0[2], v0[3]); w.z = cvt_pk_bf16(v1[0], v1[1]); w.w = cvt_pk_bf16(v1[2], v1[3]);
;                     *(u32x4*)(rowp + bj * HALF) = w; } }
.LBB0_215:
	v_add_u32_e32 v174, 0x14000, v147
	ds_read_b128 v[162:165], v174
	ds_read_b128 v[166:169], v174 offset:1024
	ds_read_b128 v[170:173], v174 offset:2048
	ds_read_b128 v[174:177], v174 offset:3072
	ds_read_b128 v[178:181], v149
	ds_read_b128 v[182:185], v149 offset:1024
	ds_read_b128 v[186:189], v149 offset:2048
	ds_read_b128 v[190:193], v149 offset:3072
	ds_read_b128 v[194:197], v149 offset:4096
	ds_read_b128 v[198:201], v149 offset:5120
	ds_read_b128 v[218:221], v149 offset:6144
	ds_read_b128 v[232:235], v149 offset:7168
	v_lshl_add_u32 v142, s35, 8, v146
	v_lshl_or_b32 v138, s34, 8, v148
	v_ashrrev_i32_e32 v143, 31, v142
	v_ashrrev_i32_e32 v139, 31, v138
	v_lshlrev_b64 v[140:141], 13, v[142:143]
	v_lshl_add_u64 v[140:141], s[94:95], 0, v[140:141]
	v_lshlrev_b64 v[144:145], 1, v[138:139]
	v_lshl_add_u64 v[138:139], v[140:141], 0, v[144:145]
	v_lshl_add_u64 v[140:141], v[142:143], 2, s[42:43]
	s_nop 0
	s_cmp_lt_i32 s34, 8
	s_cselect_b64 vcc, -1, 0
	v_cndmask_b32_e32 v150, 1.0, v228, vcc
	s_mov_b32 s8, 0x100000
	v_mul_f32_e32 v152, v150, v242
	v_pk_mul_f32 v[126:127], v[126:127], v[152:153] op_sel_hi:[1,0]
	v_pk_mul_f32 v[124:125], v[124:125], v[152:153] op_sel_hi:[1,0]
	v_pk_mul_f32 v[154:155], v[122:123], v[152:153] op_sel_hi:[1,0]
	v_pk_mul_f32 v[122:123], v[120:121], v[152:153] op_sel_hi:[1,0]
	v_cvt_pk_bf16_f32 v120, v124, v125
	v_cvt_pk_bf16_f32 v121, v126, v127
	v_pk_mul_f32 v[116:117], v[116:117], v[152:153] op_sel_hi:[1,0]
	v_cvt_pk_bf16_f32 v122, v122, v123
	v_cvt_pk_bf16_f32 v123, v154, v155
	global_store_dwordx4 v[138:139], v[120:123], off
	v_pk_mul_f32 v[118:119], v[118:119], v[152:153] op_sel_hi:[1,0]
	s_nop 0
	v_pk_mul_f32 v[120:121], v[114:115], v[152:153] op_sel_hi:[1,0]
	v_pk_mul_f32 v[114:115], v[112:113], v[152:153] op_sel_hi:[1,0]
	v_cvt_pk_bf16_f32 v112, v116, v117
	v_cvt_pk_bf16_f32 v113, v118, v119
	s_nop 0
	v_cvt_pk_bf16_f32 v114, v114, v115
	v_cvt_pk_bf16_f32 v115, v120, v121
	global_store_dwordx4 v[138:139], v[112:115], off offset:256
	s_nop 1
	v_or_b32_e32 v112, 16, v142
	v_ashrrev_i32_e32 v113, 31, v112
	v_lshlrev_b64 v[114:115], 13, v[112:113]
	v_lshl_add_u64 v[112:113], v[112:113], 2, s[42:43]
	s_nop 0
	v_lshl_add_u64 v[114:115], s[94:95], 0, v[114:115]
	v_lshl_add_u64 v[114:115], v[114:115], 0, v[144:145]
	v_mul_f32_e32 v112, v150, v243
	v_pk_mul_f32 v[110:111], v[110:111], v[112:113] op_sel_hi:[1,0]
	v_pk_mul_f32 v[108:109], v[108:109], v[112:113] op_sel_hi:[1,0]
	v_pk_mul_f32 v[116:117], v[106:107], v[112:113] op_sel_hi:[1,0]
	v_pk_mul_f32 v[106:107], v[104:105], v[112:113] op_sel_hi:[1,0]
	v_cvt_pk_bf16_f32 v104, v108, v109
	v_cvt_pk_bf16_f32 v105, v110, v111
	v_pk_mul_f32 v[100:101], v[100:101], v[112:113] op_sel_hi:[1,0]
	v_cvt_pk_bf16_f32 v106, v106, v107
	v_cvt_pk_bf16_f32 v107, v116, v117
	global_store_dwordx4 v[114:115], v[104:107], off
	v_pk_mul_f32 v[102:103], v[102:103], v[112:113] op_sel_hi:[1,0]
	s_nop 0
	v_pk_mul_f32 v[104:105], v[98:99], v[112:113] op_sel_hi:[1,0]
	v_pk_mul_f32 v[98:99], v[96:97], v[112:113] op_sel_hi:[1,0]
	v_cvt_pk_bf16_f32 v96, v100, v101
	v_cvt_pk_bf16_f32 v97, v102, v103
	s_nop 0
	v_cvt_pk_bf16_f32 v98, v98, v99
	v_cvt_pk_bf16_f32 v99, v104, v105
	global_store_dwordx4 v[114:115], v[96:99], off offset:256
	s_nop 1
	v_or_b32_e32 v96, 32, v142
	v_ashrrev_i32_e32 v97, 31, v96
	v_lshlrev_b64 v[98:99], 13, v[96:97]
	v_lshl_add_u64 v[96:97], v[96:97], 2, s[42:43]
	s_nop 0
	v_lshl_add_u64 v[98:99], s[94:95], 0, v[98:99]
	v_lshl_add_u64 v[98:99], v[98:99], 0, v[144:145]
	v_mul_f32_e32 v96, v150, v244
	v_pk_mul_f32 v[94:95], v[94:95], v[96:97] op_sel_hi:[1,0]
	v_pk_mul_f32 v[92:93], v[92:93], v[96:97] op_sel_hi:[1,0]
	v_pk_mul_f32 v[100:101], v[90:91], v[96:97] op_sel_hi:[1,0]
	v_pk_mul_f32 v[90:91], v[88:89], v[96:97] op_sel_hi:[1,0]
	v_cvt_pk_bf16_f32 v88, v92, v93
	v_cvt_pk_bf16_f32 v89, v94, v95
	v_pk_mul_f32 v[84:85], v[84:85], v[96:97] op_sel_hi:[1,0]
	v_cvt_pk_bf16_f32 v90, v90, v91
	v_cvt_pk_bf16_f32 v91, v100, v101
	global_store_dwordx4 v[98:99], v[88:91], off
	v_pk_mul_f32 v[86:87], v[86:87], v[96:97] op_sel_hi:[1,0]
	s_nop 0
	v_pk_mul_f32 v[88:89], v[82:83], v[96:97] op_sel_hi:[1,0]
	v_pk_mul_f32 v[82:83], v[80:81], v[96:97] op_sel_hi:[1,0]
	v_cvt_pk_bf16_f32 v80, v84, v85
	v_cvt_pk_bf16_f32 v81, v86, v87
	s_nop 0
	v_cvt_pk_bf16_f32 v82, v82, v83
	v_cvt_pk_bf16_f32 v83, v88, v89
	global_store_dwordx4 v[98:99], v[80:83], off offset:256
	s_nop 1
	v_or_b32_e32 v80, 48, v142
	v_ashrrev_i32_e32 v81, 31, v80
	v_lshlrev_b64 v[82:83], 13, v[80:81]
	v_lshl_add_u64 v[80:81], v[80:81], 2, s[42:43]
	s_nop 0
	v_lshl_add_u64 v[82:83], s[94:95], 0, v[82:83]
	v_lshl_add_u64 v[82:83], v[82:83], 0, v[144:145]
	v_mul_f32_e32 v80, v150, v245
	v_pk_mul_f32 v[78:79], v[78:79], v[80:81] op_sel_hi:[1,0]
	v_pk_mul_f32 v[76:77], v[76:77], v[80:81] op_sel_hi:[1,0]
	v_pk_mul_f32 v[84:85], v[74:75], v[80:81] op_sel_hi:[1,0]
	v_pk_mul_f32 v[74:75], v[72:73], v[80:81] op_sel_hi:[1,0]
	v_cvt_pk_bf16_f32 v72, v76, v77
	v_cvt_pk_bf16_f32 v73, v78, v79
	v_pk_mul_f32 v[70:71], v[70:71], v[80:81] op_sel_hi:[1,0]
	v_cvt_pk_bf16_f32 v74, v74, v75
; __device__ __forceinline__ unsigned cvt_pk_bf16(float lo, float hi) { unsigned r; asm volatile("v_cvt_pk_bf16_f32 %0, %1, %2" : "=v"(r) : "v"(lo), "v"(hi)); return r; }
; #define PG8_STAGE(bufoff, gbase, voff) do { _Pragma("unroll") for (int _i = 0; _i < 2; ++_i) \
;         __builtin_amdgcn_global_load_lds((const unsigned*)((const char*)(gbase) + (voff)[_i]), (PG8_LAS unsigned*)(lds + (bufoff) + ldsw + _i * 8192), 16, 0, 0); } while (0)
; #define PG8_LDA(dst, b, h) do { _Pragma("unroll") for (int m = 0; m < 4; ++m) _Pragma("unroll") for (int k = 0; k < 2; ++k) dst[m][k] = *(const PG8_LAS bf16x8*)(lds + PG8_SA(b, h) + aoff + m * 2048 + k * 1024); } while (0)
; #define PG8_LDB(dst, b, h) do { _Pragma("unroll") for (int n = 0; n < 2; ++n) _Pragma("unroll") for (int k = 0; k < 2; ++k) dst[n][k] = *(const PG8_LAS bf16x8*)(lds + PG8_SB(b, h) + boff + n * 2048 + k * 1024); } while (0)
; #define PG8_SCHED __builtin_amdgcn_sched_barrier(0)
;     __device__ __forceinline__ void operator()(const f32x4 (&acc)[2][2][4][2], const Unit& u, int wr, int wc, int fr, int fq) const {
;     ...
;             for (int m = 0; m < 4; ++m) { bf16_t* rowp = O + (size_t)(row0 + ai * HALF + m * 16) * ldc + col0;
;                 float rsc = sc; if (rsmode == 1) { const float r_ = rs[row0 + ai * HALF + m * 16]; rsc = sc * (ACT == 2 ? r_ * r_ : r_); }
; #pragma unroll
;                 for (int bj = 0; bj < 2; ++bj) { f32x4 v0 = acc[ai][bj][m][0], v1 = acc[ai][bj][m][1];
;                     if (ACT == 2) {
; #pragma unroll
;                         for (int e = 0; e < 4; ++e) { const float a0 = fmaxf(v0[e], 0.f), a1 = fmaxf(v1[e], 0.f); v0[e] = a0 * a0; v1[e] = a1 * a1; } }
;                     v0 = v0 * cs[bj][0] * rsc; v1 = v1 * cs[bj][1] * rsc; u32x4 w; w.x = cvt_pk_bf16(v0[0], v0[1]); w.y = cvt_pk_bf16(v0[2], v0[3]); w.z = cvt_pk_bf16(v1[0], v1[1]); w.w = cvt_pk_bf16(v1[2], v1[3]);
;                     *(u32x4*)(rowp + bj * HALF) = w; } }
; template <class Epi, class Sched, bool ALIGN_EPI = false, bool SP2 = false>
; __device__ __forceinline__ void gemm_phase(PG8_LAS unsigned char* lds, const Gemm g, const Sched& S, const Epi& E) {
;     ...
;             PG8_LDB(B0, 0, 0); PG8_LDB(B1, 0, 1); PG8_SCHED; PG8_LDA(At, 0, 0); PG8_STAGE(PG8_SA(1, 0), a1, voffA); PG8_STAGE(PG8_SA(1, 1), a1 + hstep, voffA);
	v_cvt_pk_bf16_f32 v75, v84, v85
	global_store_dwordx4 v[82:83], v[72:75], off
	v_pk_mul_f32 v[68:69], v[68:69], v[80:81] op_sel_hi:[1,0]
	s_nop 0
	v_pk_mul_f32 v[72:73], v[66:67], v[80:81] op_sel_hi:[1,0]
	v_pk_mul_f32 v[66:67], v[64:65], v[80:81] op_sel_hi:[1,0]
	v_cvt_pk_bf16_f32 v64, v68, v69
	v_cvt_pk_bf16_f32 v65, v70, v71
	s_nop 0
	v_cvt_pk_bf16_f32 v66, v66, v67
	v_cvt_pk_bf16_f32 v67, v72, v73
	global_store_dwordx4 v[82:83], v[64:67], off offset:256
	s_nop 0
	s_nop 0
	v_lshl_add_u64 v[64:65], v[138:139], 0, s[30:31]
	v_mul_f32_e32 v66, v150, v246
	v_pk_mul_f32 v[60:61], v[60:61], v[66:67] op_sel_hi:[1,0]
	v_pk_mul_f32 v[68:69], v[58:59], v[66:67] op_sel_hi:[1,0]
	v_pk_mul_f32 v[58:59], v[56:57], v[66:67] op_sel_hi:[1,0]
	v_cvt_pk_bf16_f32 v56, v60, v61
	v_add_co_u32_e32 v60, vcc, s8, v138
	v_pk_mul_f32 v[62:63], v[62:63], v[66:67] op_sel_hi:[1,0]
	s_nop 0
	v_addc_co_u32_e32 v61, vcc, 0, v139, vcc
	v_cvt_pk_bf16_f32 v57, v62, v63
	v_cvt_pk_bf16_f32 v58, v58, v59
	v_cvt_pk_bf16_f32 v59, v68, v69
	global_store_dwordx4 v[60:61], v[56:59], off
	v_pk_mul_f32 v[54:55], v[54:55], v[66:67] op_sel_hi:[1,0]
	v_pk_mul_f32 v[52:53], v[52:53], v[66:67] op_sel_hi:[1,0]
	v_pk_mul_f32 v[56:57], v[50:51], v[66:67] op_sel_hi:[1,0]
	v_pk_mul_f32 v[50:51], v[48:49], v[66:67] op_sel_hi:[1,0]
	v_cvt_pk_bf16_f32 v48, v52, v53
	v_cvt_pk_bf16_f32 v49, v54, v55
	s_mov_b64 s[8:9], 0x120000
	v_cvt_pk_bf16_f32 v50, v50, v51
	v_cvt_pk_bf16_f32 v51, v56, v57
	global_store_dwordx4 v[64:65], v[48:51], off offset:256
	s_nop 0
	s_nop 0
	v_lshl_add_u64 v[48:49], v[138:139], 0, s[8:9]
	s_mov_b32 s8, 0x120000
	v_mul_f32_e32 v50, v150, v247
	v_pk_mul_f32 v[44:45], v[44:45], v[50:51] op_sel_hi:[1,0]
	v_pk_mul_f32 v[52:53], v[42:43], v[50:51] op_sel_hi:[1,0]
	v_pk_mul_f32 v[42:43], v[40:41], v[50:51] op_sel_hi:[1,0]
	v_cvt_pk_bf16_f32 v40, v44, v45
	v_add_co_u32_e32 v44, vcc, s8, v138
	v_pk_mul_f32 v[46:47], v[46:47], v[50:51] op_sel_hi:[1,0]
	s_nop 0
	v_addc_co_u32_e32 v45, vcc, 0, v139, vcc
	v_cvt_pk_bf16_f32 v41, v46, v47
	v_cvt_pk_bf16_f32 v42, v42, v43
	v_cvt_pk_bf16_f32 v43, v52, v53
	global_store_dwordx4 v[44:45], v[40:43], off
	v_pk_mul_f32 v[38:39], v[38:39], v[50:51] op_sel_hi:[1,0]
	v_pk_mul_f32 v[36:37], v[36:37], v[50:51] op_sel_hi:[1,0]
	v_pk_mul_f32 v[40:41], v[34:35], v[50:51] op_sel_hi:[1,0]
	v_pk_mul_f32 v[34:35], v[32:33], v[50:51] op_sel_hi:[1,0]
	v_cvt_pk_bf16_f32 v32, v36, v37
	v_cvt_pk_bf16_f32 v33, v38, v39
	s_mov_b64 s[8:9], 0x140000
	v_cvt_pk_bf16_f32 v34, v34, v35
	v_cvt_pk_bf16_f32 v35, v40, v41
	global_store_dwordx4 v[48:49], v[32:35], off offset:256
	s_nop 0
	s_nop 0
	v_lshl_add_u64 v[32:33], v[138:139], 0, s[8:9]
	s_mov_b32 s8, 0x140000
	v_mul_f32_e32 v34, v150, v248
	v_pk_mul_f32 v[28:29], v[28:29], v[34:35] op_sel_hi:[1,0]
	v_pk_mul_f32 v[36:37], v[26:27], v[34:35] op_sel_hi:[1,0]
	v_pk_mul_f32 v[26:27], v[24:25], v[34:35] op_sel_hi:[1,0]
	v_cvt_pk_bf16_f32 v24, v28, v29
	v_add_co_u32_e32 v28, vcc, s8, v138
	v_pk_mul_f32 v[30:31], v[30:31], v[34:35] op_sel_hi:[1,0]
	s_nop 0
	v_addc_co_u32_e32 v29, vcc, 0, v139, vcc
	v_cvt_pk_bf16_f32 v25, v30, v31
	v_cvt_pk_bf16_f32 v26, v26, v27
	v_cvt_pk_bf16_f32 v27, v36, v37
	global_store_dwordx4 v[28:29], v[24:27], off
	v_pk_mul_f32 v[22:23], v[22:23], v[34:35] op_sel_hi:[1,0]
	v_pk_mul_f32 v[20:21], v[20:21], v[34:35] op_sel_hi:[1,0]
	v_pk_mul_f32 v[24:25], v[18:19], v[34:35] op_sel_hi:[1,0]
	v_pk_mul_f32 v[18:19], v[16:17], v[34:35] op_sel_hi:[1,0]
	v_cvt_pk_bf16_f32 v16, v20, v21
	v_cvt_pk_bf16_f32 v17, v22, v23
	s_mov_b64 s[8:9], 0x160000
	v_cvt_pk_bf16_f32 v18, v18, v19
	v_cvt_pk_bf16_f32 v19, v24, v25
	global_store_dwordx4 v[32:33], v[16:19], off offset:256
	s_nop 0
	s_nop 0
	v_lshl_add_u64 v[18:19], v[138:139], 0, s[8:9]
	s_mov_b32 s8, 0x160000
	v_mul_f32_e32 v16, v150, v249
	v_pk_mul_f32 v[12:13], v[12:13], v[16:17] op_sel_hi:[1,0]
	v_pk_mul_f32 v[20:21], v[10:11], v[16:17] op_sel_hi:[1,0]
	v_pk_mul_f32 v[10:11], v[8:9], v[16:17] op_sel_hi:[1,0]
	v_cvt_pk_bf16_f32 v8, v12, v13
	v_add_co_u32_e32 v12, vcc, s8, v138
	v_pk_mul_f32 v[14:15], v[14:15], v[16:17] op_sel_hi:[1,0]
	s_nop 0
	v_addc_co_u32_e32 v13, vcc, 0, v139, vcc
	v_cvt_pk_bf16_f32 v9, v14, v15
	v_cvt_pk_bf16_f32 v10, v10, v11
	v_cvt_pk_bf16_f32 v11, v20, v21
	global_store_dwordx4 v[12:13], v[8:11], off
	s_mov_b64 s[8:9], -1
	s_andn2_b64 vcc, exec, s[38:39]
	v_pk_mul_f32 v[8:9], v[2:3], v[16:17] op_sel_hi:[1,0]
	v_pk_mul_f32 v[2:3], v[0:1], v[16:17] op_sel_hi:[1,0]
	v_pk_mul_f32 v[6:7], v[6:7], v[16:17] op_sel_hi:[1,0]
	v_pk_mul_f32 v[4:5], v[4:5], v[16:17] op_sel_hi:[1,0]
	s_nop 0
	v_cvt_pk_bf16_f32 v0, v4, v5
	v_cvt_pk_bf16_f32 v1, v6, v7
	v_cvt_pk_bf16_f32 v2, v2, v3
	v_cvt_pk_bf16_f32 v3, v8, v9
	global_store_dwordx4 v[18:19], v[0:3], off offset:256
	v_add_u32_e32 v158, 0x10000, v147
	ds_read_b128 v[142:145], v158
	ds_read_b128 v[150:153], v158 offset:1024
	ds_read_b128 v[154:157], v158 offset:2048
	ds_read_b128 v[158:161], v158 offset:3072
	s_cbranch_vccnz .LBB0_204
	s_andn2_b64 vcc, exec, s[46:47]
	s_cbranch_vccnz .LBB0_203
	s_barrier
	s_branch .LBB0_203

; #define PG8_STAGE(bufoff, gbase, voff) do { _Pragma("unroll") for (int _i = 0; _i < 2; ++_i) \
;         __builtin_amdgcn_global_load_lds((const unsigned*)((const char*)(gbase) + (voff)[_i]), (PG8_LAS unsigned*)(lds + (bufoff) + ldsw + _i * 8192), 16, 0, 0); } while (0)
; #define PG8_WAIT_V(n) asm volatile("s_waitcnt vmcnt(" #n ")" ::: "memory")
; #define PG8_BAR __builtin_amdgcn_s_barrier()
; template <class Epi, class Sched, bool ALIGN_EPI = false, bool SP2 = false>
; __device__ __forceinline__ void gemm_phase(PG8_LAS unsigned char* lds, const Gemm g, const Sched& S, const Epi& E) {
;     ...
;     const int tid = tid_, wid = __builtin_amdgcn_readfirstlane(tid >> 6), lane = tid & 63, wr = wid >> 2, wc = wid & 3, fr = lane & 15, fq = lane >> 4;
;     const int K = g.K, nt = K / BK;
;     unsigned voffA[2], voffB[2];
; #pragma unroll
;     for (int i = 0; i < 2; ++i) { int R, C; stage_rc(tid * 16 + i * 8192, R, C); const int Rb = Epi::PERM ? ((R & ~31) + perm32(R & 31)) : R;
;         voffA[i] = (unsigned)(R * K + C) * 2u; voffB[i] = (unsigned)(Rb * K + C) * 2u; }
;     const size_t kstep = (size_t)(BK * 2);
;     const size_t hstep = (size_t)HALF * K * 2;
;     const size_t tstep = 2 * hstep;
;     const unsigned ldsw = (unsigned)wid * 1024u;
;     const int aoff = lds_byte(wr * 64 + fr, fq * 8), boff = lds_byte(wc * 32 + fr, fq * 8);
;     ...
;         PG8_STAGE(PG8_SB(0, 0), cB, voffB); PG8_STAGE(PG8_SB(0, 1), cB + hstep, voffB); PG8_STAGE(PG8_SA(0, 0), cA, voffA); PG8_STAGE(PG8_SA(0, 1), cA + hstep, voffA);
;         if (wr == 1) PG8_BAR;
;         PG8_WAIT_V(2); PG8_BAR;
;         PG8_STAGE(PG8_SB(1, 0), cB + kstep, voffB); PG8_STAGE(PG8_SB(1, 1), cB + hstep + kstep, voffB);
;         PG8_WAIT_V(4); PG8_BAR;
.LBB0_222:
	v_lshrrev_b32_e32 v12, 1, v10
	v_and_b32_e32 v12, 24, v12
	s_lshl_b32 s6, s6, 5
	v_and_b32_e32 v11, 15, v10
	v_lshlrev_b32_e32 v13, 1, v12
	v_lshlrev_b32_e32 v10, 2, v10
	s_and_b32 s35, s6, 0x60
	v_lshl_or_b32 v160, s7, 6, v11
	v_lshl_or_b32 v11, v11, 6, v13
	s_lshl_b32 s7, s7, 13
	v_and_b32_e32 v10, 32, v10
	s_lshl_b32 s6, s35, 7
	v_bitop3_b32 v161, v11, s6, v10 bitop3:0xde
	s_add_u32 s6, s36, 0x21000000
	v_bitop3_b32 v13, v11, s7, v10 bitop3:0xde
	s_addc_u32 s7, s37, 0
	s_add_i32 m0, s57, 0x18000
	v_lshl_add_u64 v[0:1], v[0:1], 0, s[26:27]
	s_waitcnt vmcnt(2)
	s_barrier
	global_load_lds_dwordx4 v[0:1], off
	s_add_i32 m0, s57, 0x1a000
	s_add_u32 s10, s44, 0x80080
	v_lshl_add_u64 v[0:1], v[2:3], 0, s[26:27]
	s_addc_u32 s11, s45, 0
	global_load_lds_dwordx4 v[0:1], off
	s_add_i32 m0, s57, 0x1c000
	v_lshl_add_u64 v[0:1], s[10:11], 0, v[204:205]
	global_load_lds_dwordx4 v[0:1], off
	v_lshl_add_u64 v[0:1], s[10:11], 0, v[144:145]
	s_add_i32 m0, s57, 0x1e000
	s_cmpk_lt_u32 s8, 0x100
	global_load_lds_dwordx4 v[0:1], off
	v_lshlrev_b32_e32 v0, 15, v8
	v_and_b32_e32 v0, 0xffff0000, v0
	v_lshl_add_u32 v0, v7, 12, v0
	v_and_b32_e32 v1, 1, v8
	v_lshl_or_b32 v0, v1, 6, v0
	v_lshl_add_u32 v150, v9, 1, v0
	v_lshlrev_b32_e32 v0, 15, v4
	v_and_b32_e32 v0, 0xffff0000, v0
	s_waitcnt vmcnt(4)
	v_lshl_add_u32 v0, v5, 12, v0
	v_and_b32_e32 v1, 1, v4
	v_lshl_or_b32 v0, v1, 6, v0
	v_readlane_b32 s10, v255, 1
	v_mov_b32_e32 v149, v205
	v_mov_b32_e32 v147, v205
	s_cselect_b64 s[8:9], -1, 0
	v_or_b32_e32 v162, s35, v12
	v_mov_b32_e32 v151, v205
	v_lshl_add_u32 v152, v6, 1, v0
	v_mov_b32_e32 v153, v205
	s_mov_b32 s35, 0
	v_add_u32_e32 v163, 0, v13
	v_readlane_b32 s37, v254, 57
	s_mov_b32 s36, s10
	s_barrier
	v_readlane_b32 s11, v255, 2
	ds_read_b128 v[180:183], v163
	ds_read_b128 v[184:187], v163 offset:1024
	ds_read_b128 v[188:191], v163 offset:2048
	ds_read_b128 v[192:195], v163 offset:3072
	ds_read_b128 v[196:199], v163 offset:4096
	ds_read_b128 v[200:203], v163 offset:5120
	ds_read_b128 v[218:221], v163 offset:6144
	ds_read_b128 v[232:235], v163 offset:7168
	v_add_u32_e32 v154, 0x10000, v161
	v_add_u32_e32 v158, 0x14000, v161
	ds_read_b128 v[100:103], v154
	ds_read_b128 v[104:107], v154 offset:1024
	ds_read_b128 v[108:111], v154 offset:2048
	ds_read_b128 v[154:157], v154 offset:3072
	ds_read_b128 v[164:167], v158
	ds_read_b128 v[168:171], v158 offset:1024
	ds_read_b128 v[172:175], v158 offset:2048
	ds_read_b128 v[176:179], v158 offset:3072
	s_branch .LBB0_225

; #define PG8_STAGE(bufoff, gbase, voff) do { _Pragma("unroll") for (int _i = 0; _i < 2; ++_i) \
;         __builtin_amdgcn_global_load_lds((const unsigned*)((const char*)(gbase) + (voff)[_i]), (PG8_LAS unsigned*)(lds + (bufoff) + ldsw + _i * 8192), 16, 0, 0); } while (0)
; #define PG8_LDA(dst, b, h) do { _Pragma("unroll") for (int m = 0; m < 4; ++m) _Pragma("unroll") for (int k = 0; k < 2; ++k) dst[m][k] = *(const PG8_LAS bf16x8*)(lds + PG8_SA(b, h) + aoff + m * 2048 + k * 1024); } while (0)
; #define PG8_LDB(dst, b, h) do { _Pragma("unroll") for (int n = 0; n < 2; ++n) _Pragma("unroll") for (int k = 0; k < 2; ++k) dst[n][k] = *(const PG8_LAS bf16x8*)(lds + PG8_SB(b, h) + boff + n * 2048 + k * 1024); } while (0)
; #define PG8_MMA(ai, bj, At, Bt) do { __builtin_amdgcn_s_setprio(1); _Pragma("unroll") for (int m = 0; m < 4; ++m) _Pragma("unroll") for (int n = 0; n < 2; ++n) _Pragma("unroll") for (int k = 0; k < 2; ++k) \
;         acc[ai][bj][m][n] = __builtin_amdgcn_mfma_f32_16x16x32_bf16(Bt[n][k], At[m][k], acc[ai][bj][m][n], 0, 0, 0); __builtin_amdgcn_s_setprio(0); } while (0)
; #define PG8_WAIT_V(n) asm volatile("s_waitcnt vmcnt(" #n ")" ::: "memory")
; #define PG8_WAIT_L(n) asm volatile("s_waitcnt lgkmcnt(" #n ")" ::: "memory")
; template <class Epi, class Sched, bool ALIGN_EPI = false, bool SP2 = false>
; __device__ __forceinline__ void gemm_phase(PG8_LAS unsigned char* lds, const Gemm g, const Sched& S, const Epi& E) {
;     ...
;         const bool has_next = S.next(ui + 1, nxt);
;         const char* nA = has_next ? (const char*)g.A + (size_t)nxt.pm * tstep : cA; const char* nB = has_next ? (const char*)g.Bt + (size_t)nxt.pn * tstep : cB;
;         for (int t = 0; t < nt; t += 2) {
;             const bool last = (t == nt - 2);
;             const char* a1 = cA + (size_t)(t + 1) * kstep;
;             const char* a2 = last ? nA : cA + (size_t)(t + 2) * kstep; const char* b2 = last ? nB : cB + (size_t)(t + 2) * kstep;
;             const char* a3 = a2 + kstep; const char* b3 = b2 + kstep;
;             if (last && has_next) S.a_ready(nxt);
;             if constexpr (SP2) {
;             PG8_LDB(B0, 0, 0); PG8_LDB(B1, 0, 1); PG8_SCHED; PG8_LDA(At, 0, 0); PG8_STAGE(PG8_SA(1, 0), a1, voffA); PG8_STAGE(PG8_SA(1, 1), a1 + hstep, voffA);
;             PG8_WAIT_V(8); PG8_WAIT_L(0); PG8_BAR; PG8_MMA(0, 0, At, B0); PG8_MMA(0, 1, At, B1); PG8_BAR; PG8_SCHED;
.LBB0_231:
	s_ashr_i32 s47, s46, 31
	s_lshl_b64 s[52:53], s[46:47], 20
	s_add_u32 s72, s20, s52
	s_addc_u32 s73, s21, s53
	s_and_b64 s[52:53], s[38:39], exec
	s_cselect_b32 s47, s73, s17
	s_cselect_b32 s68, s72, s16
	s_ashr_i32 s11, s10, 31
	s_lshl_b64 s[52:53], s[10:11], 20
	s_add_u32 s76, s22, s52
	s_addc_u32 s77, s75, s53
	s_and_b64 s[52:53], s[38:39], exec
	s_cselect_b32 s11, s77, s45
	s_cselect_b32 s69, s76, s44
	s_add_u32 s70, s44, 0x100
	s_addc_u32 s71, s45, 0
	v_lshl_add_u64 v[96:97], s[16:17], 0, v[150:151]
	v_lshl_add_u64 v[98:99], s[16:17], 0, v[152:153]
	s_mov_b32 s52, -2
	s_mov_b64 s[88:89], 0
	s_add_u32 s44, s16, s88
	s_addc_u32 s45, s17, s89
	s_add_u32 s53, s44, 0x100
	s_addc_u32 s78, s45, 0
	s_add_u32 s44, s70, s88
	s_addc_u32 s45, s71, s89
	s_add_i32 s79, 0, 0x10000
	s_cmpk_eq_i32 s88, 0xf00
	s_cselect_b32 s45, s11, s45
	s_cselect_b32 s44, s69, s44
	s_cselect_b32 s95, s47, s78
	s_cselect_b32 s94, s68, s53
	s_add_i32 s53, 0, 0x14000
	v_lshl_add_u64 v[158:159], v[96:97], 0, s[88:89]
	v_lshl_add_u64 v[206:207], v[158:159], 0, s[26:27]
	s_add_i32 m0, s57, 0x8000
	global_load_lds_dwordx4 v[206:207], off
	v_lshl_add_u64 v[206:207], v[98:99], 0, s[88:89]
	v_lshl_add_u64 v[208:209], v[206:207], 0, s[26:27]
	s_add_i32 m0, s57, 0xa000
	v_lshl_add_u64 v[158:159], v[158:159], 0, s[28:29]
	global_load_lds_dwordx4 v[208:209], off
	s_add_i32 m0, s57, 0xc000
	s_nop 0
	global_load_lds_dwordx4 v[158:159], off
	v_lshl_add_u64 v[158:159], v[206:207], 0, s[28:29]
	s_add_i32 m0, s57, 0xe000
	s_nop 0
	global_load_lds_dwordx4 v[158:159], off
	s_waitcnt vmcnt(8)
	s_waitcnt lgkmcnt(0)
	s_barrier
	v_mfma_f32_16x16x32_bf16 v[140:143], v[100:103], v[180:183], 0
	v_mfma_f32_16x16x32_bf16 v[136:139], v[108:111], v[180:183], 0
	v_mfma_f32_16x16x32_bf16 v[124:127], v[100:103], v[188:191], 0
	v_mfma_f32_16x16x32_bf16 v[120:123], v[108:111], v[188:191], 0
	v_mfma_f32_16x16x32_bf16 v[92:95], v[100:103], v[196:199], 0
	v_mfma_f32_16x16x32_bf16 v[88:91], v[108:111], v[196:199], 0
	v_mfma_f32_16x16x32_bf16 v[76:79], v[100:103], v[218:221], 0
	v_mfma_f32_16x16x32_bf16 v[72:75], v[108:111], v[218:221], 0
	v_mfma_f32_16x16x32_bf16 v[140:143], v[104:107], v[184:187], v[140:143]
	v_mfma_f32_16x16x32_bf16 v[136:139], v[154:157], v[184:187], v[136:139]
	v_mfma_f32_16x16x32_bf16 v[124:127], v[104:107], v[192:195], v[124:127]
	v_mfma_f32_16x16x32_bf16 v[120:123], v[154:157], v[192:195], v[120:123]
	v_mfma_f32_16x16x32_bf16 v[92:95], v[104:107], v[200:203], v[92:95]
	v_mfma_f32_16x16x32_bf16 v[88:91], v[154:157], v[200:203], v[88:91]
	v_mfma_f32_16x16x32_bf16 v[76:79], v[104:107], v[232:235], v[76:79]
	v_mfma_f32_16x16x32_bf16 v[72:75], v[154:157], v[232:235], v[72:75]
	v_mfma_f32_16x16x32_bf16 v[132:135], v[164:167], v[180:183], 0
	v_mfma_f32_16x16x32_bf16 v[128:131], v[172:175], v[180:183], 0
	v_mfma_f32_16x16x32_bf16 v[116:119], v[164:167], v[188:191], 0
	v_mfma_f32_16x16x32_bf16 v[112:115], v[172:175], v[188:191], 0
	v_mfma_f32_16x16x32_bf16 v[84:87], v[164:167], v[196:199], 0
	v_mfma_f32_16x16x32_bf16 v[80:83], v[172:175], v[196:199], 0
	v_mfma_f32_16x16x32_bf16 v[68:71], v[164:167], v[218:221], 0
	v_mfma_f32_16x16x32_bf16 v[64:67], v[172:175], v[218:221], 0
	v_mfma_f32_16x16x32_bf16 v[132:135], v[168:171], v[184:187], v[132:135]
	v_mfma_f32_16x16x32_bf16 v[128:131], v[176:179], v[184:187], v[128:131]
	v_mfma_f32_16x16x32_bf16 v[116:119], v[168:171], v[192:195], v[116:119]
	v_mfma_f32_16x16x32_bf16 v[112:115], v[176:179], v[192:195], v[112:115]
	v_mfma_f32_16x16x32_bf16 v[84:87], v[168:171], v[200:203], v[84:87]
	v_mfma_f32_16x16x32_bf16 v[80:83], v[176:179], v[200:203], v[80:83]
	v_mfma_f32_16x16x32_bf16 v[68:71], v[168:171], v[232:235], v[68:71]
	v_mfma_f32_16x16x32_bf16 v[64:67], v[176:179], v[232:235], v[64:67]
	s_barrier
	s_add_i32 s78, s79, s23
	v_lshl_add_u64 v[158:159], s[44:45], 0, v[204:205]
	s_mov_b32 m0, s78
	ds_read_b128 v[180:183], v163 offset:16384
	ds_read_b128 v[184:187], v163 offset:17408
	ds_read_b128 v[188:191], v163 offset:18432
	ds_read_b128 v[192:195], v163 offset:19456
	ds_read_b128 v[196:199], v163 offset:20480
	ds_read_b128 v[200:203], v163 offset:21504
	ds_read_b128 v[218:221], v163 offset:22528
	ds_read_b128 v[232:235], v163 offset:23552
	global_load_lds_dwordx4 v[158:159], off
	s_add_i32 m0, s78, 0x2000
	s_add_u32 s78, s44, 0x80000
	v_lshl_add_u64 v[206:207], s[44:45], 0, v[144:145]
	s_addc_u32 s79, s45, 0
	s_add_i32 s53, s53, s23
	global_load_lds_dwordx4 v[206:207], off
	v_lshl_add_u64 v[208:209], s[78:79], 0, v[204:205]
	s_mov_b32 m0, s53
	s_nop 0
	global_load_lds_dwordx4 v[208:209], off
	v_lshl_add_u64 v[208:209], s[78:79], 0, v[144:145]
	s_add_i32 m0, s53, 0x2000
	s_nop 0
	global_load_lds_dwordx4 v[208:209], off
	s_waitcnt vmcnt(6)
	s_waitcnt lgkmcnt(0)
	s_barrier
	v_mfma_f32_16x16x32_bf16 v[60:63], v[100:103], v[180:183], 0
	v_mfma_f32_16x16x32_bf16 v[56:59], v[108:111], v[180:183], 0
	v_mfma_f32_16x16x32_bf16 v[48:51], v[100:103], v[188:191], 0
	v_mfma_f32_16x16x32_bf16 v[40:43], v[108:111], v[188:191], 0
	v_mfma_f32_16x16x32_bf16 v[32:35], v[100:103], v[196:199], 0
	v_mfma_f32_16x16x32_bf16 v[24:27], v[108:111], v[196:199], 0
	v_mfma_f32_16x16x32_bf16 v[16:19], v[100:103], v[218:221], 0
	v_mfma_f32_16x16x32_bf16 v[8:11], v[108:111], v[218:221], 0
	v_mfma_f32_16x16x32_bf16 v[60:63], v[104:107], v[184:187], v[60:63]
	v_mfma_f32_16x16x32_bf16 v[56:59], v[154:157], v[184:187], v[56:59]
	v_mfma_f32_16x16x32_bf16 v[48:51], v[104:107], v[192:195], v[48:51]
	v_mfma_f32_16x16x32_bf16 v[40:43], v[154:157], v[192:195], v[40:43]
	v_mfma_f32_16x16x32_bf16 v[32:35], v[104:107], v[200:203], v[32:35]
	v_mfma_f32_16x16x32_bf16 v[24:27], v[154:157], v[200:203], v[24:27]
	v_mfma_f32_16x16x32_bf16 v[16:19], v[104:107], v[232:235], v[16:19]
	v_mfma_f32_16x16x32_bf16 v[8:11], v[154:157], v[232:235], v[8:11]
	v_mfma_f32_16x16x32_bf16 v[52:55], v[164:167], v[180:183], 0
	v_mfma_f32_16x16x32_bf16 v[44:47], v[172:175], v[180:183], 0
	v_mfma_f32_16x16x32_bf16 v[36:39], v[164:167], v[188:191], 0
	v_mfma_f32_16x16x32_bf16 v[28:31], v[172:175], v[188:191], 0
	v_mfma_f32_16x16x32_bf16 v[20:23], v[164:167], v[196:199], 0
	v_mfma_f32_16x16x32_bf16 v[12:15], v[172:175], v[196:199], 0
	v_mfma_f32_16x16x32_bf16 v[4:7], v[164:167], v[218:221], 0
	v_mfma_f32_16x16x32_bf16 v[0:3], v[172:175], v[218:221], 0
	v_mfma_f32_16x16x32_bf16 v[52:55], v[168:171], v[184:187], v[52:55]
	v_mfma_f32_16x16x32_bf16 v[44:47], v[176:179], v[184:187], v[44:47]
	v_mfma_f32_16x16x32_bf16 v[36:39], v[168:171], v[192:195], v[36:39]
	v_mfma_f32_16x16x32_bf16 v[28:31], v[176:179], v[192:195], v[28:31]
	v_mfma_f32_16x16x32_bf16 v[20:23], v[168:171], v[200:203], v[20:23]
	v_mfma_f32_16x16x32_bf16 v[12:15], v[176:179], v[200:203], v[12:15]
	v_mfma_f32_16x16x32_bf16 v[4:7], v[168:171], v[232:235], v[4:7]
	v_mfma_f32_16x16x32_bf16 v[0:3], v[176:179], v[232:235], v[0:3]
	s_barrier
	s_branch .Lpl_vt

; __device__ __forceinline__ unsigned cvt_pk_bf16(float lo, float hi) { unsigned r; asm volatile("v_cvt_pk_bf16_f32 %0, %1, %2" : "=v"(r) : "v"(lo), "v"(hi)); return r; }
;     __device__ __forceinline__ void operator()(const f32x4 (&acc)[2][2][4][2], const Unit& u, int wr, int wc, int fr, int fq) const {
;         const int row0 = u.pm * BM + wr * 64 + fr; const int colt = u.pn * BM;
;         const float sc = (colt < scale_cols) ? scale0 : 1.f;
;         const int col0 = colt + wc * 32 + 8 * fq;
;         f32x4 cs[2][2];
; #pragma unroll
;         for (int bj = 0; bj < 2; ++bj) { cs[bj][0] = (f32x4){1.f, 1.f, 1.f, 1.f}; cs[bj][1] = cs[bj][0]; if (rsmode == 2) { cs[bj][0] = *(const f32x4*)(rs + col0 + bj * HALF); cs[bj][1] = *(const f32x4*)(rs + col0 + bj * HALF + 4); } }
; #pragma unroll
;         for (int ai = 0; ai < 2; ++ai)
; #pragma unroll
;             for (int m = 0; m < 4; ++m) { bf16_t* rowp = O + (size_t)(row0 + ai * HALF + m * 16) * ldc + col0;
;                 float rsc = sc; if (rsmode == 1) { const float r_ = rs[row0 + ai * HALF + m * 16]; rsc = sc * (ACT == 2 ? r_ * r_ : r_); }
; #pragma unroll
;                 for (int bj = 0; bj < 2; ++bj) { f32x4 v0 = acc[ai][bj][m][0], v1 = acc[ai][bj][m][1];
;                     if (ACT == 2) {
; #pragma unroll
;                         for (int e = 0; e < 4; ++e) { const float a0 = fmaxf(v0[e], 0.f), a1 = fmaxf(v1[e], 0.f); v0[e] = a0 * a0; v1[e] = a1 * a1; } }
;                     v0 = v0 * cs[bj][0] * rsc; v1 = v1 * cs[bj][1] * rsc; u32x4 w; w.x = cvt_pk_bf16(v0[0], v0[1]); w.y = cvt_pk_bf16(v0[2], v0[3]); w.z = cvt_pk_bf16(v1[0], v1[1]); w.w = cvt_pk_bf16(v1[2], v1[3]);
;                     *(u32x4*)(rowp + bj * HALF) = w; } }
.LBB0_235:
	ds_read_b128 v[180:183], v163
	ds_read_b128 v[184:187], v163 offset:1024
	ds_read_b128 v[188:191], v163 offset:2048
	ds_read_b128 v[192:195], v163 offset:3072
	ds_read_b128 v[196:199], v163 offset:4096
	ds_read_b128 v[200:203], v163 offset:5120
	ds_read_b128 v[218:221], v163 offset:6144
	ds_read_b128 v[232:235], v163 offset:7168
	v_lshl_or_b32 v154, s37, 8, v162
	v_ashrrev_i32_e32 v155, 31, v154
	v_lshl_add_u64 v[100:101], v[154:155], 2, s[42:43]
	global_load_dwordx4 v[104:107], v[100:101], off offset:16
	global_load_dwordx4 v[108:111], v[100:101], off
	global_load_dwordx4 v[96:99], v[100:101], off offset:528
	s_nop 0
	global_load_dwordx4 v[100:103], v[100:101], off offset:512
	v_lshl_add_u32 v158, s36, 8, v160
	v_ashrrev_i32_e32 v159, 31, v158
	v_lshlrev_b64 v[156:157], 15, v[158:159]
	v_lshl_add_u64 v[164:165], s[6:7], 0, v[156:157]
	v_lshlrev_b64 v[156:157], 1, v[154:155]
	v_lshl_add_u64 v[154:155], v[164:165], 0, v[156:157]
	s_mov_b32 s11, 0x400000
	s_mov_b64 s[16:17], 0x400000
	s_waitcnt vmcnt(0)
	v_pk_mul_f32 v[164:165], v[138:139], v[106:107]
	v_pk_mul_f32 v[142:143], v[142:143], v[110:111]
	v_pk_mul_f32 v[140:141], v[140:141], v[108:109]
	v_pk_mul_f32 v[138:139], v[136:137], v[104:105]
	v_cvt_pk_bf16_f32 v136, v140, v141
	v_cvt_pk_bf16_f32 v137, v142, v143
	v_pk_mul_f32 v[132:133], v[132:133], v[100:101]
	v_cvt_pk_bf16_f32 v138, v138, v139
	v_cvt_pk_bf16_f32 v139, v164, v165
	global_store_dwordx4 v[154:155], v[136:139], off
	v_pk_mul_f32 v[134:135], v[134:135], v[102:103]
	v_pk_mul_f32 v[126:127], v[126:127], v[110:111]
	v_pk_mul_f32 v[136:137], v[130:131], v[98:99]
	v_pk_mul_f32 v[130:131], v[128:129], v[96:97]
	v_cvt_pk_bf16_f32 v128, v132, v133
	v_cvt_pk_bf16_f32 v129, v134, v135
	v_pk_mul_f32 v[124:125], v[124:125], v[108:109]
	v_cvt_pk_bf16_f32 v130, v130, v131
	v_cvt_pk_bf16_f32 v131, v136, v137
	global_store_dwordx4 v[154:155], v[128:131], off offset:256
	v_pk_mul_f32 v[116:117], v[116:117], v[100:101]
	v_pk_mul_f32 v[118:119], v[118:119], v[102:103]
	v_or_b32_e32 v128, 16, v158
	v_ashrrev_i32_e32 v129, 31, v128
	v_lshlrev_b64 v[128:129], 15, v[128:129]
	v_lshl_add_u64 v[128:129], s[6:7], 0, v[128:129]
	v_lshl_add_u64 v[128:129], v[128:129], 0, v[156:157]
	v_pk_mul_f32 v[130:131], v[122:123], v[106:107]
	v_pk_mul_f32 v[122:123], v[120:121], v[104:105]
	v_cvt_pk_bf16_f32 v120, v124, v125
	v_cvt_pk_bf16_f32 v121, v126, v127
	v_pk_mul_f32 v[94:95], v[94:95], v[110:111]
	v_cvt_pk_bf16_f32 v122, v122, v123
	v_cvt_pk_bf16_f32 v123, v130, v131
	global_store_dwordx4 v[128:129], v[120:123], off
	v_pk_mul_f32 v[92:93], v[92:93], v[108:109]
	v_pk_mul_f32 v[84:85], v[84:85], v[100:101]
	v_pk_mul_f32 v[120:121], v[114:115], v[98:99]
	v_pk_mul_f32 v[114:115], v[112:113], v[96:97]
	v_cvt_pk_bf16_f32 v112, v116, v117
	v_cvt_pk_bf16_f32 v113, v118, v119
	v_pk_mul_f32 v[86:87], v[86:87], v[102:103]
	v_cvt_pk_bf16_f32 v114, v114, v115
	v_cvt_pk_bf16_f32 v115, v120, v121
	global_store_dwordx4 v[128:129], v[112:115], off offset:256
	v_pk_mul_f32 v[78:79], v[78:79], v[110:111]
	v_pk_mul_f32 v[76:77], v[76:77], v[108:109]
	v_or_b32_e32 v112, 32, v158
	v_ashrrev_i32_e32 v113, 31, v112
	v_lshlrev_b64 v[112:113], 15, v[112:113]
	v_lshl_add_u64 v[112:113], s[6:7], 0, v[112:113]
	v_lshl_add_u64 v[112:113], v[112:113], 0, v[156:157]
	v_pk_mul_f32 v[114:115], v[90:91], v[106:107]
	v_pk_mul_f32 v[90:91], v[88:89], v[104:105]
	v_cvt_pk_bf16_f32 v88, v92, v93
	v_cvt_pk_bf16_f32 v89, v94, v95
	v_pk_mul_f32 v[70:71], v[70:71], v[102:103]
	v_cvt_pk_bf16_f32 v90, v90, v91
	v_cvt_pk_bf16_f32 v91, v114, v115
	global_store_dwordx4 v[112:113], v[88:91], off
	v_pk_mul_f32 v[68:69], v[68:69], v[100:101]
	v_pk_mul_f32 v[60:61], v[60:61], v[108:109]
	v_pk_mul_f32 v[88:89], v[82:83], v[98:99]
	v_pk_mul_f32 v[82:83], v[80:81], v[96:97]
	v_cvt_pk_bf16_f32 v80, v84, v85
	v_cvt_pk_bf16_f32 v81, v86, v87
	v_pk_mul_f32 v[62:63], v[62:63], v[110:111]
	v_cvt_pk_bf16_f32 v82, v82, v83
	v_cvt_pk_bf16_f32 v83, v88, v89
	global_store_dwordx4 v[112:113], v[80:83], off offset:256
	v_pk_mul_f32 v[54:55], v[54:55], v[102:103]
	v_pk_mul_f32 v[52:53], v[52:53], v[100:101]
	v_or_b32_e32 v80, 48, v158
	v_ashrrev_i32_e32 v81, 31, v80
	v_lshlrev_b64 v[80:81], 15, v[80:81]
	v_lshl_add_u64 v[80:81], s[6:7], 0, v[80:81]
	v_lshl_add_u64 v[80:81], v[80:81], 0, v[156:157]
	v_pk_mul_f32 v[82:83], v[74:75], v[106:107]
	v_pk_mul_f32 v[74:75], v[72:73], v[104:105]
	v_cvt_pk_bf16_f32 v72, v76, v77
; __device__ __forceinline__ unsigned cvt_pk_bf16(float lo, float hi) { unsigned r; asm volatile("v_cvt_pk_bf16_f32 %0, %1, %2" : "=v"(r) : "v"(lo), "v"(hi)); return r; }
; #define PG8_STAGE(bufoff, gbase, voff) do { _Pragma("unroll") for (int _i = 0; _i < 2; ++_i) \
;         __builtin_amdgcn_global_load_lds((const unsigned*)((const char*)(gbase) + (voff)[_i]), (PG8_LAS unsigned*)(lds + (bufoff) + ldsw + _i * 8192), 16, 0, 0); } while (0)
; #define PG8_LDA(dst, b, h) do { _Pragma("unroll") for (int m = 0; m < 4; ++m) _Pragma("unroll") for (int k = 0; k < 2; ++k) dst[m][k] = *(const PG8_LAS bf16x8*)(lds + PG8_SA(b, h) + aoff + m * 2048 + k * 1024); } while (0)
; #define PG8_LDB(dst, b, h) do { _Pragma("unroll") for (int n = 0; n < 2; ++n) _Pragma("unroll") for (int k = 0; k < 2; ++k) dst[n][k] = *(const PG8_LAS bf16x8*)(lds + PG8_SB(b, h) + boff + n * 2048 + k * 1024); } while (0)
; #define PG8_SCHED __builtin_amdgcn_sched_barrier(0)
;     __device__ __forceinline__ void operator()(const f32x4 (&acc)[2][2][4][2], const Unit& u, int wr, int wc, int fr, int fq) const {
;     ...
;             for (int m = 0; m < 4; ++m) { bf16_t* rowp = O + (size_t)(row0 + ai * HALF + m * 16) * ldc + col0;
;                 float rsc = sc; if (rsmode == 1) { const float r_ = rs[row0 + ai * HALF + m * 16]; rsc = sc * (ACT == 2 ? r_ * r_ : r_); }
; #pragma unroll
;                 for (int bj = 0; bj < 2; ++bj) { f32x4 v0 = acc[ai][bj][m][0], v1 = acc[ai][bj][m][1];
;                     if (ACT == 2) {
; #pragma unroll
;                         for (int e = 0; e < 4; ++e) { const float a0 = fmaxf(v0[e], 0.f), a1 = fmaxf(v1[e], 0.f); v0[e] = a0 * a0; v1[e] = a1 * a1; } }
;                     v0 = v0 * cs[bj][0] * rsc; v1 = v1 * cs[bj][1] * rsc; u32x4 w; w.x = cvt_pk_bf16(v0[0], v0[1]); w.y = cvt_pk_bf16(v0[2], v0[3]); w.z = cvt_pk_bf16(v1[0], v1[1]); w.w = cvt_pk_bf16(v1[2], v1[3]);
;                     *(u32x4*)(rowp + bj * HALF) = w; } }
; template <class Epi, class Sched, bool ALIGN_EPI = false, bool SP2 = false>
; __device__ __forceinline__ void gemm_phase(PG8_LAS unsigned char* lds, const Gemm g, const Sched& S, const Epi& E) {
;     ...
;             PG8_LDB(B0, 0, 0); PG8_LDB(B1, 0, 1); PG8_SCHED; PG8_LDA(At, 0, 0); PG8_STAGE(PG8_SA(1, 0), a1, voffA); PG8_STAGE(PG8_SA(1, 1), a1 + hstep, voffA);
	v_cvt_pk_bf16_f32 v73, v78, v79
	v_pk_mul_f32 v[48:49], v[48:49], v[108:109]
	v_cvt_pk_bf16_f32 v74, v74, v75
	v_cvt_pk_bf16_f32 v75, v82, v83
	global_store_dwordx4 v[80:81], v[72:75], off
	v_pk_mul_f32 v[38:39], v[38:39], v[102:103]
	v_pk_mul_f32 v[36:37], v[36:37], v[100:101]
	v_pk_mul_f32 v[72:73], v[66:67], v[98:99]
	v_pk_mul_f32 v[66:67], v[64:65], v[96:97]
	v_cvt_pk_bf16_f32 v64, v68, v69
	v_cvt_pk_bf16_f32 v65, v70, v71
	v_pk_mul_f32 v[32:33], v[32:33], v[108:109]
	v_cvt_pk_bf16_f32 v66, v66, v67
	v_cvt_pk_bf16_f32 v67, v72, v73
	global_store_dwordx4 v[80:81], v[64:67], off offset:256
	v_pk_mul_f32 v[22:23], v[22:23], v[102:103]
	v_pk_mul_f32 v[20:21], v[20:21], v[100:101]
	v_pk_mul_f32 v[66:67], v[58:59], v[106:107]
	v_pk_mul_f32 v[58:59], v[56:57], v[104:105]
	v_cvt_pk_bf16_f32 v56, v60, v61
	v_add_co_u32_e32 v60, vcc, s11, v154
	v_cvt_pk_bf16_f32 v57, v62, v63
	v_cvt_pk_bf16_f32 v58, v58, v59
	v_cvt_pk_bf16_f32 v59, v66, v67
	v_lshl_add_u64 v[64:65], v[154:155], 0, s[16:17]
	s_nop 0
	v_addc_co_u32_e32 v61, vcc, 0, v155, vcc
	global_store_dwordx4 v[60:61], v[56:59], off
	s_mov_b32 s11, 0x480000
	s_mov_b64 s[16:17], 0x480000
	v_pk_mul_f32 v[56:57], v[46:47], v[98:99]
	v_pk_mul_f32 v[46:47], v[44:45], v[96:97]
	v_cvt_pk_bf16_f32 v44, v52, v53
	v_cvt_pk_bf16_f32 v45, v54, v55
	v_pk_mul_f32 v[16:17], v[16:17], v[108:109]
	v_cvt_pk_bf16_f32 v46, v46, v47
	v_cvt_pk_bf16_f32 v47, v56, v57
	global_store_dwordx4 v[64:65], v[44:47], off offset:256
	v_pk_mul_f32 v[6:7], v[6:7], v[102:103]
	v_pk_mul_f32 v[4:5], v[4:5], v[100:101]
	v_pk_mul_f32 v[46:47], v[50:51], v[110:111]
	v_pk_mul_f32 v[50:51], v[42:43], v[106:107]
	v_pk_mul_f32 v[42:43], v[40:41], v[104:105]
	v_cvt_pk_bf16_f32 v40, v48, v49
	v_cvt_pk_bf16_f32 v41, v46, v47
	v_add_co_u32_e32 v46, vcc, s11, v154
	v_cvt_pk_bf16_f32 v42, v42, v43
	v_cvt_pk_bf16_f32 v43, v50, v51
	v_lshl_add_u64 v[44:45], v[154:155], 0, s[16:17]
	s_nop 0
	v_addc_co_u32_e32 v47, vcc, 0, v155, vcc
	global_store_dwordx4 v[46:47], v[40:43], off
	s_mov_b32 s11, 0x500000
	s_mov_b64 s[16:17], 0x500000
	v_pk_mul_f32 v[40:41], v[30:31], v[98:99]
	v_pk_mul_f32 v[30:31], v[28:29], v[96:97]
	v_cvt_pk_bf16_f32 v28, v36, v37
	v_cvt_pk_bf16_f32 v29, v38, v39
	s_nop 0
	v_cvt_pk_bf16_f32 v30, v30, v31
	v_cvt_pk_bf16_f32 v31, v40, v41
	global_store_dwordx4 v[44:45], v[28:31], off offset:256
	s_nop 1
	v_pk_mul_f32 v[30:31], v[34:35], v[110:111]
	v_pk_mul_f32 v[34:35], v[26:27], v[106:107]
	v_pk_mul_f32 v[26:27], v[24:25], v[104:105]
	v_cvt_pk_bf16_f32 v24, v32, v33
	v_cvt_pk_bf16_f32 v25, v30, v31
	v_add_co_u32_e32 v30, vcc, s11, v154
	v_cvt_pk_bf16_f32 v26, v26, v27
	v_cvt_pk_bf16_f32 v27, v34, v35
	v_lshl_add_u64 v[28:29], v[154:155], 0, s[16:17]
	s_nop 0
	v_addc_co_u32_e32 v31, vcc, 0, v155, vcc
	global_store_dwordx4 v[30:31], v[24:27], off
	s_mov_b32 s11, 0x580000
	s_mov_b64 s[16:17], 0x580000
	v_pk_mul_f32 v[24:25], v[14:15], v[98:99]
	v_pk_mul_f32 v[14:15], v[12:13], v[96:97]
	v_cvt_pk_bf16_f32 v12, v20, v21
	v_cvt_pk_bf16_f32 v13, v22, v23
	s_nop 0
	v_cvt_pk_bf16_f32 v14, v14, v15
	v_cvt_pk_bf16_f32 v15, v24, v25
	global_store_dwordx4 v[28:29], v[12:15], off offset:256
	s_nop 1
	v_pk_mul_f32 v[14:15], v[18:19], v[110:111]
	v_pk_mul_f32 v[18:19], v[10:11], v[106:107]
	v_pk_mul_f32 v[10:11], v[8:9], v[104:105]
	v_cvt_pk_bf16_f32 v8, v16, v17
	v_cvt_pk_bf16_f32 v9, v14, v15
	v_add_co_u32_e32 v14, vcc, s11, v154
	v_lshl_add_u64 v[12:13], v[154:155], 0, s[16:17]
	s_nop 0
	v_addc_co_u32_e32 v15, vcc, 0, v155, vcc
	v_cvt_pk_bf16_f32 v10, v10, v11
	v_cvt_pk_bf16_f32 v11, v18, v19
	global_store_dwordx4 v[14:15], v[8:11], off
	s_mov_b64 s[16:17], -1
	s_andn2_b64 vcc, exec, s[38:39]
	v_pk_mul_f32 v[8:9], v[2:3], v[98:99]
	v_pk_mul_f32 v[2:3], v[0:1], v[96:97]
	v_cvt_pk_bf16_f32 v0, v4, v5
	v_cvt_pk_bf16_f32 v1, v6, v7
	s_nop 0
	v_cvt_pk_bf16_f32 v2, v2, v3
	v_cvt_pk_bf16_f32 v3, v8, v9
	global_store_dwordx4 v[12:13], v[0:3], off offset:256
	v_add_u32_e32 v154, 0x10000, v161
	v_add_u32_e32 v158, 0x14000, v161
	ds_read_b128 v[100:103], v154
	ds_read_b128 v[104:107], v154 offset:1024
	ds_read_b128 v[108:111], v154 offset:2048
	ds_read_b128 v[154:157], v154 offset:3072
	ds_read_b128 v[164:167], v158
	ds_read_b128 v[168:171], v158 offset:1024
	ds_read_b128 v[172:175], v158 offset:2048
	ds_read_b128 v[176:179], v158 offset:3072
	s_cbranch_vccnz .LBB0_224
	s_andn2_b64 vcc, exec, s[4:5]
	s_cbranch_vccnz .LBB0_223
	s_barrier
	s_branch .LBB0_223

; #define PG8_STAGE(bufoff, gbase, voff) do { _Pragma("unroll") for (int _i = 0; _i < 2; ++_i) \
;         __builtin_amdgcn_global_load_lds((const unsigned*)((const char*)(gbase) + (voff)[_i]), (PG8_LAS unsigned*)(lds + (bufoff) + ldsw + _i * 8192), 16, 0, 0); } while (0)
; #define PG8_WAIT_V(n) asm volatile("s_waitcnt vmcnt(" #n ")" ::: "memory")
; #define PG8_BAR __builtin_amdgcn_s_barrier()
; template <class Epi, class Sched, bool ALIGN_EPI = false, bool SP2 = false>
; __device__ __forceinline__ void gemm_phase(PG8_LAS unsigned char* lds, const Gemm g, const Sched& S, const Epi& E) {
;     ...
;     const int tid = tid_, wid = __builtin_amdgcn_readfirstlane(tid >> 6), lane = tid & 63, wr = wid >> 2, wc = wid & 3, fr = lane & 15, fq = lane >> 4;
;     const int K = g.K, nt = K / BK;
;     unsigned voffA[2], voffB[2];
; #pragma unroll
;     for (int i = 0; i < 2; ++i) { int R, C; stage_rc(tid * 16 + i * 8192, R, C); const int Rb = Epi::PERM ? ((R & ~31) + perm32(R & 31)) : R;
;         voffA[i] = (unsigned)(R * K + C) * 2u; voffB[i] = (unsigned)(Rb * K + C) * 2u; }
;     const size_t kstep = (size_t)(BK * 2);
;     const size_t hstep = (size_t)HALF * K * 2;
;     const size_t tstep = 2 * hstep;
;     const unsigned ldsw = (unsigned)wid * 1024u;
;     const int aoff = lds_byte(wr * 64 + fr, fq * 8), boff = lds_byte(wc * 32 + fr, fq * 8);
;     ...
;         PG8_STAGE(PG8_SB(0, 0), cB, voffB); PG8_STAGE(PG8_SB(0, 1), cB + hstep, voffB); PG8_STAGE(PG8_SA(0, 0), cA, voffA); PG8_STAGE(PG8_SA(0, 1), cA + hstep, voffA);
;         if (wr == 1) PG8_BAR;
;         PG8_WAIT_V(2); PG8_BAR;
;         PG8_STAGE(PG8_SB(1, 0), cB + kstep, voffB); PG8_STAGE(PG8_SB(1, 1), cB + hstep + kstep, voffB);
;         PG8_WAIT_V(4); PG8_BAR;
.LBB0_416:
	s_add_u32 s8, s8, 0x35000000
	v_lshrrev_b32_e32 v12, 1, v10
	s_addc_u32 s9, s9, 0
	v_and_b32_e32 v12, 24, v12
	s_lshl_b32 s11, s11, 5
	v_and_b32_e32 v11, 15, v10
	v_lshlrev_b32_e32 v13, 1, v12
	v_lshlrev_b32_e32 v10, 2, v10
	s_and_b32 s37, s11, 0x60
	s_add_i32 m0, s23, 0x18000
	v_lshl_add_u64 v[0:1], v[0:1], 0, s[26:27]
	v_lshl_or_b32 v142, s16, 6, v11
	v_lshl_or_b32 v11, v11, 6, v13
	s_lshl_b32 s16, s16, 13
	v_and_b32_e32 v10, 32, v10
	s_lshl_b32 s11, s37, 7
	s_waitcnt vmcnt(2)
	s_barrier
	global_load_lds_dwordx4 v[0:1], off
	s_add_i32 m0, s23, 0x1a000
	v_bitop3_b32 v13, v11, s16, v10 bitop3:0xde
	s_add_u32 s16, s44, 0x80080
	v_lshl_add_u64 v[0:1], v[2:3], 0, s[26:27]
	s_addc_u32 s17, s45, 0
	global_load_lds_dwordx4 v[0:1], off
	s_add_i32 m0, s23, 0x1c000
	v_lshl_add_u64 v[0:1], s[16:17], 0, v[204:205]
	global_load_lds_dwordx4 v[0:1], off
	v_lshl_add_u64 v[0:1], s[16:17], 0, v[128:129]
	s_add_i32 m0, s23, 0x1e000
	v_readlane_b32 s16, v255, 20
	global_load_lds_dwordx4 v[0:1], off
	v_lshlrev_b32_e32 v0, 15, v8
	v_and_b32_e32 v0, 0xffff0000, v0
	v_lshl_add_u32 v0, v7, 12, v0
	v_and_b32_e32 v1, 1, v8
	v_lshl_or_b32 v0, v1, 6, v0
	v_lshl_add_u32 v134, v9, 1, v0
	v_lshlrev_b32_e32 v0, 15, v4
	v_and_b32_e32 v0, 0xffff0000, v0
	s_waitcnt vmcnt(4)
	v_lshl_add_u32 v0, v5, 12, v0
	v_and_b32_e32 v1, 1, v4
	v_readlane_b32 s17, v255, 21
	s_cmpk_lt_u32 s10, 0x100
	v_lshl_or_b32 v0, v1, 6, v0
	s_mov_b32 s57, s16
	v_readlane_b32 s16, v255, 7
	v_mov_b32_e32 v133, v205
	v_mov_b32_e32 v131, v205
	v_bitop3_b32 v143, v11, s11, v10 bitop3:0xde
	s_cselect_b64 s[10:11], -1, 0
	v_or_b32_e32 v144, s37, v12
	v_mov_b32_e32 v135, v205
	v_lshl_add_u32 v136, v6, 1, v0
	v_mov_b32_e32 v137, v205
	s_mov_b32 s37, 0
	v_add_u32_e32 v145, 0, v13
	v_readlane_b32 s75, v254, 60
	v_readlane_b32 s17, v255, 8
	s_barrier
	v_add_u32_e32 v174, 0x14000, v143
	ds_read_b128 v[162:165], v174
	ds_read_b128 v[166:169], v174 offset:1024
	ds_read_b128 v[170:173], v174 offset:2048
	ds_read_b128 v[174:177], v174 offset:3072
	ds_read_b128 v[178:181], v145
	ds_read_b128 v[182:185], v145 offset:1024
	ds_read_b128 v[186:189], v145 offset:2048
	ds_read_b128 v[190:193], v145 offset:3072
	ds_read_b128 v[194:197], v145 offset:4096
	ds_read_b128 v[198:201], v145 offset:5120
	ds_read_b128 v[206:209], v145 offset:6144
	ds_read_b128 v[218:221], v145 offset:7168
	v_add_u32_e32 v158, 0x10000, v143
	ds_read_b128 v[146:149], v158
	ds_read_b128 v[150:153], v158 offset:1024
	ds_read_b128 v[154:157], v158 offset:2048
	ds_read_b128 v[158:161], v158 offset:3072
	s_branch .LBB0_419

; #define PG8_STAGE(bufoff, gbase, voff) do { _Pragma("unroll") for (int _i = 0; _i < 2; ++_i) \
;         __builtin_amdgcn_global_load_lds((const unsigned*)((const char*)(gbase) + (voff)[_i]), (PG8_LAS unsigned*)(lds + (bufoff) + ldsw + _i * 8192), 16, 0, 0); } while (0)
; #define PG8_LDA(dst, b, h) do { _Pragma("unroll") for (int m = 0; m < 4; ++m) _Pragma("unroll") for (int k = 0; k < 2; ++k) dst[m][k] = *(const PG8_LAS bf16x8*)(lds + PG8_SA(b, h) + aoff + m * 2048 + k * 1024); } while (0)
; #define PG8_LDB(dst, b, h) do { _Pragma("unroll") for (int n = 0; n < 2; ++n) _Pragma("unroll") for (int k = 0; k < 2; ++k) dst[n][k] = *(const PG8_LAS bf16x8*)(lds + PG8_SB(b, h) + boff + n * 2048 + k * 1024); } while (0)
; #define PG8_WAIT_V(n) asm volatile("s_waitcnt vmcnt(" #n ")" ::: "memory")
; #define PG8_WAIT_L(n) asm volatile("s_waitcnt lgkmcnt(" #n ")" ::: "memory")
; #define PG8_BAR __builtin_amdgcn_s_barrier()
; #define PG8_SCHED __builtin_amdgcn_sched_barrier(0)
; template <class Epi, class Sched, bool ALIGN_EPI = false, bool SP2 = false>
; __device__ __forceinline__ void gemm_phase(PG8_LAS unsigned char* lds, const Gemm g, const Sched& S, const Epi& E) {
;     ...
;         const bool has_next = S.next(ui + 1, nxt);
;         const char* nA = has_next ? (const char*)g.A + (size_t)nxt.pm * tstep : cA; const char* nB = has_next ? (const char*)g.Bt + (size_t)nxt.pn * tstep : cB;
;         for (int t = 0; t < nt; t += 2) {
;             const bool last = (t == nt - 2);
;             const char* a1 = cA + (size_t)(t + 1) * kstep;
;             const char* a2 = last ? nA : cA + (size_t)(t + 2) * kstep; const char* b2 = last ? nB : cB + (size_t)(t + 2) * kstep;
;             const char* a3 = a2 + kstep; const char* b3 = b2 + kstep;
;             if (last && has_next) S.a_ready(nxt);
;             if constexpr (SP2) {
;             PG8_LDB(B0, 0, 0); PG8_LDB(B1, 0, 1); PG8_SCHED; PG8_LDA(At, 0, 0); PG8_STAGE(PG8_SA(1, 0), a1, voffA); PG8_STAGE(PG8_SA(1, 1), a1 + hstep, voffA);
;             PG8_WAIT_V(8); PG8_WAIT_L(0); PG8_BAR; PG8_MMA(0, 0, At, B0); PG8_MMA(0, 1, At, B1); PG8_BAR; PG8_SCHED;
;             PG8_LDA(At, 0, 1); PG8_STAGE(PG8_SB(0, 0), b2, voffB); PG8_STAGE(PG8_SB(0, 1), b2 + hstep, voffB);
;             PG8_WAIT_V(6); PG8_WAIT_L(0); PG8_BAR; PG8_MMA(1, 0, At, B0); PG8_MMA(1, 1, At, B1); PG8_BAR; PG8_SCHED;
.LBB0_425:
	s_ashr_i32 s47, s46, 31
	s_lshl_b64 s[52:53], s[46:47], 20
	s_add_u32 s72, s98, s52
	s_addc_u32 s73, s99, s53
	s_and_b64 s[52:53], s[38:39], exec
	s_cselect_b32 s47, s73, s17
	s_cselect_b32 s68, s72, s16
	s_ashr_i32 s43, s42, 31
	s_lshl_b64 s[52:53], s[42:43], 20
	s_add_u32 s76, s20, s52
	s_addc_u32 s77, s21, s53
	s_and_b64 s[52:53], s[38:39], exec
	s_cselect_b32 s43, s77, s45
	s_cselect_b32 s69, s76, s44
	s_add_u32 s70, s44, 0x100
	s_addc_u32 s71, s45, 0
	v_lshl_add_u64 v[138:139], s[16:17], 0, v[134:135]
	v_lshl_add_u64 v[140:141], s[16:17], 0, v[136:137]
	s_mov_b32 s52, -2
	s_mov_b64 s[88:89], 0
	s_add_u32 s44, s16, s88
	s_addc_u32 s45, s17, s89
	s_add_u32 s53, s44, 0x100
	s_addc_u32 s78, s45, 0
	s_add_u32 s44, s70, s88
	s_addc_u32 s45, s71, s89
	s_add_i32 s79, 0, 0x10000
	s_cmpk_eq_i32 s88, 0xf00
	s_cselect_b32 s45, s43, s45
	s_cselect_b32 s44, s69, s44
	s_cselect_b32 s95, s47, s78
	s_cselect_b32 s94, s68, s53
	s_add_i32 s53, 0, 0x14000
	v_lshl_add_u64 v[202:203], v[138:139], 0, s[88:89]
	v_lshl_add_u64 v[222:223], v[202:203], 0, s[26:27]
	s_add_i32 m0, s23, 0x8000
	global_load_lds_dwordx4 v[222:223], off
	v_lshl_add_u64 v[222:223], v[140:141], 0, s[88:89]
	v_lshl_add_u64 v[232:233], v[222:223], 0, s[26:27]
	s_add_i32 m0, s23, 0xa000
	v_lshl_add_u64 v[202:203], v[202:203], 0, s[28:29]
	global_load_lds_dwordx4 v[232:233], off
	s_add_i32 m0, s23, 0xc000
	s_nop 0
	global_load_lds_dwordx4 v[202:203], off
	v_lshl_add_u64 v[202:203], v[222:223], 0, s[28:29]
	s_add_i32 m0, s23, 0xe000
	s_nop 0
	global_load_lds_dwordx4 v[202:203], off
	s_waitcnt vmcnt(8)
	s_waitcnt lgkmcnt(0)
	s_barrier
	v_mfma_f32_16x16x32_bf16 v[124:127], v[146:149], v[178:181], 0
	v_mfma_f32_16x16x32_bf16 v[120:123], v[154:157], v[178:181], 0
	v_mfma_f32_16x16x32_bf16 v[116:119], v[146:149], v[186:189], 0
	v_mfma_f32_16x16x32_bf16 v[108:111], v[154:157], v[186:189], 0
	v_mfma_f32_16x16x32_bf16 v[100:103], v[146:149], v[194:197], 0
	v_mfma_f32_16x16x32_bf16 v[92:95], v[154:157], v[194:197], 0
	v_mfma_f32_16x16x32_bf16 v[84:87], v[146:149], v[206:209], 0
	v_mfma_f32_16x16x32_bf16 v[76:79], v[154:157], v[206:209], 0
	v_mfma_f32_16x16x32_bf16 v[124:127], v[150:153], v[182:185], v[124:127]
	v_mfma_f32_16x16x32_bf16 v[120:123], v[158:161], v[182:185], v[120:123]
	v_mfma_f32_16x16x32_bf16 v[116:119], v[150:153], v[190:193], v[116:119]
	v_mfma_f32_16x16x32_bf16 v[108:111], v[158:161], v[190:193], v[108:111]
	v_mfma_f32_16x16x32_bf16 v[100:103], v[150:153], v[198:201], v[100:103]
	v_mfma_f32_16x16x32_bf16 v[92:95], v[158:161], v[198:201], v[92:95]
	v_mfma_f32_16x16x32_bf16 v[84:87], v[150:153], v[218:221], v[84:87]
	v_mfma_f32_16x16x32_bf16 v[76:79], v[158:161], v[218:221], v[76:79]
	v_mfma_f32_16x16x32_bf16 v[112:115], v[162:165], v[178:181], 0
	v_mfma_f32_16x16x32_bf16 v[104:107], v[170:173], v[178:181], 0
	v_mfma_f32_16x16x32_bf16 v[96:99], v[162:165], v[186:189], 0
	v_mfma_f32_16x16x32_bf16 v[88:91], v[170:173], v[186:189], 0
	v_mfma_f32_16x16x32_bf16 v[80:83], v[162:165], v[194:197], 0
	v_mfma_f32_16x16x32_bf16 v[72:75], v[170:173], v[194:197], 0
	v_mfma_f32_16x16x32_bf16 v[68:71], v[162:165], v[206:209], 0
	v_mfma_f32_16x16x32_bf16 v[64:67], v[170:173], v[206:209], 0
	v_mfma_f32_16x16x32_bf16 v[112:115], v[166:169], v[182:185], v[112:115]
	v_mfma_f32_16x16x32_bf16 v[104:107], v[174:177], v[182:185], v[104:107]
	v_mfma_f32_16x16x32_bf16 v[96:99], v[166:169], v[190:193], v[96:99]
	v_mfma_f32_16x16x32_bf16 v[88:91], v[174:177], v[190:193], v[88:91]
	v_mfma_f32_16x16x32_bf16 v[80:83], v[166:169], v[198:201], v[80:83]
	v_mfma_f32_16x16x32_bf16 v[72:75], v[174:177], v[198:201], v[72:75]
	v_mfma_f32_16x16x32_bf16 v[68:71], v[166:169], v[218:221], v[68:71]
	v_mfma_f32_16x16x32_bf16 v[64:67], v[174:177], v[218:221], v[64:67]
	s_barrier
	s_add_i32 s78, s79, s22
	v_lshl_add_u64 v[202:203], s[44:45], 0, v[204:205]
	s_mov_b32 m0, s78
	ds_read_b128 v[178:181], v145 offset:16384
	ds_read_b128 v[182:185], v145 offset:17408
	ds_read_b128 v[186:189], v145 offset:18432
	ds_read_b128 v[190:193], v145 offset:19456
	ds_read_b128 v[194:197], v145 offset:20480
	ds_read_b128 v[198:201], v145 offset:21504
	ds_read_b128 v[206:209], v145 offset:22528
	ds_read_b128 v[218:221], v145 offset:23552
	global_load_lds_dwordx4 v[202:203], off
	s_add_i32 m0, s78, 0x2000
	s_add_u32 s78, s44, 0x80000
	v_lshl_add_u64 v[222:223], s[44:45], 0, v[128:129]
	s_addc_u32 s79, s45, 0
	s_add_i32 s53, s53, s22
	global_load_lds_dwordx4 v[222:223], off
	v_lshl_add_u64 v[232:233], s[78:79], 0, v[204:205]
	s_mov_b32 m0, s53
	s_nop 0
	global_load_lds_dwordx4 v[232:233], off
	v_lshl_add_u64 v[232:233], s[78:79], 0, v[128:129]
	s_add_i32 m0, s53, 0x2000
	s_nop 0
	global_load_lds_dwordx4 v[232:233], off
	s_waitcnt vmcnt(6)
	s_waitcnt lgkmcnt(0)
	s_barrier
	v_mfma_f32_16x16x32_bf16 v[60:63], v[146:149], v[178:181], 0
	v_mfma_f32_16x16x32_bf16 v[56:59], v[154:157], v[178:181], 0
	v_mfma_f32_16x16x32_bf16 v[52:55], v[146:149], v[186:189], 0
	v_mfma_f32_16x16x32_bf16 v[44:47], v[154:157], v[186:189], 0
	v_mfma_f32_16x16x32_bf16 v[36:39], v[146:149], v[194:197], 0
	v_mfma_f32_16x16x32_bf16 v[28:31], v[154:157], v[194:197], 0
	v_mfma_f32_16x16x32_bf16 v[20:23], v[146:149], v[206:209], 0
	v_mfma_f32_16x16x32_bf16 v[12:15], v[154:157], v[206:209], 0
	v_mfma_f32_16x16x32_bf16 v[60:63], v[150:153], v[182:185], v[60:63]
	v_mfma_f32_16x16x32_bf16 v[56:59], v[158:161], v[182:185], v[56:59]
	v_mfma_f32_16x16x32_bf16 v[52:55], v[150:153], v[190:193], v[52:55]
	v_mfma_f32_16x16x32_bf16 v[44:47], v[158:161], v[190:193], v[44:47]
	v_mfma_f32_16x16x32_bf16 v[36:39], v[150:153], v[198:201], v[36:39]
	v_mfma_f32_16x16x32_bf16 v[28:31], v[158:161], v[198:201], v[28:31]
	v_mfma_f32_16x16x32_bf16 v[20:23], v[150:153], v[218:221], v[20:23]
	v_mfma_f32_16x16x32_bf16 v[12:15], v[158:161], v[218:221], v[12:15]
	v_mfma_f32_16x16x32_bf16 v[48:51], v[162:165], v[178:181], 0
	v_mfma_f32_16x16x32_bf16 v[40:43], v[170:173], v[178:181], 0
	v_mfma_f32_16x16x32_bf16 v[32:35], v[162:165], v[186:189], 0
	v_mfma_f32_16x16x32_bf16 v[24:27], v[170:173], v[186:189], 0
	v_mfma_f32_16x16x32_bf16 v[16:19], v[162:165], v[194:197], 0
	v_mfma_f32_16x16x32_bf16 v[8:11], v[170:173], v[194:197], 0
	v_mfma_f32_16x16x32_bf16 v[4:7], v[162:165], v[206:209], 0
	v_mfma_f32_16x16x32_bf16 v[0:3], v[170:173], v[206:209], 0
	v_mfma_f32_16x16x32_bf16 v[48:51], v[166:169], v[182:185], v[48:51]
	v_mfma_f32_16x16x32_bf16 v[40:43], v[174:177], v[182:185], v[40:43]
	v_mfma_f32_16x16x32_bf16 v[32:35], v[166:169], v[190:193], v[32:35]
	v_mfma_f32_16x16x32_bf16 v[24:27], v[174:177], v[190:193], v[24:27]
	v_mfma_f32_16x16x32_bf16 v[16:19], v[166:169], v[198:201], v[16:19]
	v_mfma_f32_16x16x32_bf16 v[8:11], v[174:177], v[198:201], v[8:11]
	v_mfma_f32_16x16x32_bf16 v[4:7], v[166:169], v[218:221], v[4:7]
	v_mfma_f32_16x16x32_bf16 v[0:3], v[174:177], v[218:221], v[0:3]
	s_barrier
	s_branch .Lpl_o

; __device__ __forceinline__ unsigned cvt_pk_bf16(float lo, float hi) { unsigned r; asm volatile("v_cvt_pk_bf16_f32 %0, %1, %2" : "=v"(r) : "v"(lo), "v"(hi)); return r; }
; #define PG8_STAGE(bufoff, gbase, voff) do { _Pragma("unroll") for (int _i = 0; _i < 2; ++_i) \
;         __builtin_amdgcn_global_load_lds((const unsigned*)((const char*)(gbase) + (voff)[_i]), (PG8_LAS unsigned*)(lds + (bufoff) + ldsw + _i * 8192), 16, 0, 0); } while (0)
;     __device__ __forceinline__ void operator()(const f32x4 (&acc)[2][2][4][2], const Unit& u, int wr, int wc, int fr, int fq) const {
;         const int row0 = u.pm * BM + wr * 64 + fr; const int colt = u.pn * BM;
;         const float sc = (colt < scale_cols) ? scale0 : 1.f;
;         const int col0 = colt + wc * 32 + 8 * fq;
;         f32x4 cs[2][2];
; #pragma unroll
;         for (int bj = 0; bj < 2; ++bj) { cs[bj][0] = (f32x4){1.f, 1.f, 1.f, 1.f}; cs[bj][1] = cs[bj][0]; if (rsmode == 2) { cs[bj][0] = *(const f32x4*)(rs + col0 + bj * HALF); cs[bj][1] = *(const f32x4*)(rs + col0 + bj * HALF + 4); } }
; #pragma unroll
;         for (int ai = 0; ai < 2; ++ai)
; #pragma unroll
;             for (int m = 0; m < 4; ++m) { bf16_t* rowp = O + (size_t)(row0 + ai * HALF + m * 16) * ldc + col0;
;                 float rsc = sc; if (rsmode == 1) { const float r_ = rs[row0 + ai * HALF + m * 16]; rsc = sc * (ACT == 2 ? r_ * r_ : r_); }
; #pragma unroll
;                 for (int bj = 0; bj < 2; ++bj) { f32x4 v0 = acc[ai][bj][m][0], v1 = acc[ai][bj][m][1];
;                     if (ACT == 2) {
; #pragma unroll
;                         for (int e = 0; e < 4; ++e) { const float a0 = fmaxf(v0[e], 0.f), a1 = fmaxf(v1[e], 0.f); v0[e] = a0 * a0; v1[e] = a1 * a1; } }
;                     v0 = v0 * cs[bj][0] * rsc; v1 = v1 * cs[bj][1] * rsc; u32x4 w; w.x = cvt_pk_bf16(v0[0], v0[1]); w.y = cvt_pk_bf16(v0[2], v0[3]); w.z = cvt_pk_bf16(v1[0], v1[1]); w.w = cvt_pk_bf16(v1[2], v1[3]);
;                     *(u32x4*)(rowp + bj * HALF) = w; } }
; template <class Epi, class Sched, bool ALIGN_EPI = false, bool SP2 = false>
; __device__ __forceinline__ void gemm_phase(PG8_LAS unsigned char* lds, const Gemm g, const Sched& S, const Epi& E) {
;     ...
;             PG8_LDB(B0, 0, 0); PG8_LDB(B1, 0, 1); PG8_SCHED; PG8_LDA(At, 0, 0); PG8_STAGE(PG8_SA(1, 0), a1, voffA); PG8_STAGE(PG8_SA(1, 1), a1 + hstep, voffA);
.LBB0_429:
	v_add_u32_e32 v174, 0x14000, v143
	ds_read_b128 v[162:165], v174
	ds_read_b128 v[166:169], v174 offset:1024
	ds_read_b128 v[170:173], v174 offset:2048
	ds_read_b128 v[174:177], v174 offset:3072
	ds_read_b128 v[178:181], v145
	ds_read_b128 v[182:185], v145 offset:1024
	ds_read_b128 v[186:189], v145 offset:2048
	ds_read_b128 v[190:193], v145 offset:3072
	ds_read_b128 v[194:197], v145 offset:4096
	ds_read_b128 v[198:201], v145 offset:5120
	ds_read_b128 v[206:209], v145 offset:6144
	ds_read_b128 v[218:221], v145 offset:7168
	v_lshl_add_u32 v140, s57, 8, v142
	v_lshl_or_b32 v138, s75, 8, v144
	v_ashrrev_i32_e32 v141, 31, v140
	v_ashrrev_i32_e32 v139, 31, v138
	v_lshlrev_b64 v[146:147], 12, v[140:141]
	v_lshl_add_u64 v[146:147], s[8:9], 0, v[146:147]
	v_lshlrev_b64 v[148:149], 1, v[138:139]
	v_lshl_add_u64 v[138:139], v[146:147], 0, v[148:149]
	v_cvt_pk_bf16_f32 v124, v124, v125
	v_cvt_pk_bf16_f32 v125, v126, v127
	v_cvt_pk_bf16_f32 v126, v120, v121
	v_cvt_pk_bf16_f32 v127, v122, v123
	global_store_dwordx4 v[138:139], v[124:127], off
	v_cvt_pk_bf16_f32 v112, v112, v113
	v_cvt_pk_bf16_f32 v113, v114, v115
	v_cvt_pk_bf16_f32 v114, v104, v105
	v_or_b32_e32 v104, 16, v140
	v_ashrrev_i32_e32 v105, 31, v104
	v_lshlrev_b64 v[104:105], 12, v[104:105]
	v_lshl_add_u64 v[104:105], s[8:9], 0, v[104:105]
	v_cvt_pk_bf16_f32 v115, v106, v107
	global_store_dwordx4 v[138:139], v[112:115], off offset:256
	s_mov_b64 s[16:17], 0x90000
	s_mov_b64 s[0:1], 0xa0000
	v_lshl_add_u64 v[112:113], v[104:105], 0, v[148:149]
	v_cvt_pk_bf16_f32 v104, v116, v117
	v_cvt_pk_bf16_f32 v105, v118, v119
	v_cvt_pk_bf16_f32 v106, v108, v109
	v_cvt_pk_bf16_f32 v107, v110, v111
	global_store_dwordx4 v[112:113], v[104:107], off
	v_cvt_pk_bf16_f32 v96, v96, v97
	v_cvt_pk_bf16_f32 v97, v98, v99
	v_cvt_pk_bf16_f32 v98, v88, v89
	v_or_b32_e32 v88, 32, v140
	v_ashrrev_i32_e32 v89, 31, v88
	v_lshlrev_b64 v[88:89], 12, v[88:89]
	v_lshl_add_u64 v[88:89], s[8:9], 0, v[88:89]
	v_cvt_pk_bf16_f32 v99, v90, v91
	global_store_dwordx4 v[112:113], v[96:99], off offset:256
	s_nop 1
	v_lshl_add_u64 v[96:97], v[88:89], 0, v[148:149]
	v_cvt_pk_bf16_f32 v88, v100, v101
	v_cvt_pk_bf16_f32 v89, v102, v103
	v_cvt_pk_bf16_f32 v90, v92, v93
	v_cvt_pk_bf16_f32 v91, v94, v95
	global_store_dwordx4 v[96:97], v[88:91], off
	v_cvt_pk_bf16_f32 v80, v80, v81
	v_cvt_pk_bf16_f32 v81, v82, v83
	v_cvt_pk_bf16_f32 v82, v72, v73
	v_or_b32_e32 v72, 48, v140
	v_ashrrev_i32_e32 v73, 31, v72
	v_lshlrev_b64 v[72:73], 12, v[72:73]
	v_lshl_add_u64 v[72:73], s[8:9], 0, v[72:73]
	v_cvt_pk_bf16_f32 v83, v74, v75
	global_store_dwordx4 v[96:97], v[80:83], off offset:256
	s_nop 1
	v_lshl_add_u64 v[80:81], v[72:73], 0, v[148:149]
	v_cvt_pk_bf16_f32 v72, v84, v85
	v_cvt_pk_bf16_f32 v73, v86, v87
	v_cvt_pk_bf16_f32 v74, v76, v77
	v_cvt_pk_bf16_f32 v75, v78, v79
	global_store_dwordx4 v[80:81], v[72:75], off
	v_cvt_pk_bf16_f32 v68, v68, v69
	v_cvt_pk_bf16_f32 v69, v70, v71
	v_cvt_pk_bf16_f32 v70, v64, v65
	v_cvt_pk_bf16_f32 v71, v66, v67
	global_store_dwordx4 v[80:81], v[68:71], off offset:256
	v_cvt_pk_bf16_f32 v60, v60, v61
	v_cvt_pk_bf16_f32 v61, v62, v63
	v_cvt_pk_bf16_f32 v62, v56, v57
	v_add_co_u32_e32 v56, vcc, s85, v138
	v_lshl_add_u64 v[64:65], v[138:139], 0, s[24:25]
	s_nop 0
	v_addc_co_u32_e32 v57, vcc, 0, v139, vcc
	v_cvt_pk_bf16_f32 v63, v58, v59
	global_store_dwordx4 v[56:57], v[60:63], off
	v_cvt_pk_bf16_f32 v48, v48, v49
	v_cvt_pk_bf16_f32 v49, v50, v51
	v_cvt_pk_bf16_f32 v50, v40, v41
	v_cvt_pk_bf16_f32 v51, v42, v43
	global_store_dwordx4 v[64:65], v[48:51], off offset:256
	v_cvt_pk_bf16_f32 v40, v52, v53
	v_cvt_pk_bf16_f32 v41, v54, v55
	v_cvt_pk_bf16_f32 v42, v44, v45
	v_cvt_pk_bf16_f32 v43, v46, v47
	s_nop 1
	v_lshl_add_u64 v[48:49], v[138:139], 0, s[16:17]
	s_mov_b32 s16, 0x90000
	v_add_co_u32_e32 v44, vcc, s16, v138
	s_mov_b32 s16, 0xa0000
	s_nop 0
	v_addc_co_u32_e32 v45, vcc, 0, v139, vcc
	global_store_dwordx4 v[44:45], v[40:43], off
	v_cvt_pk_bf16_f32 v32, v32, v33
	v_cvt_pk_bf16_f32 v33, v34, v35
	v_cvt_pk_bf16_f32 v34, v24, v25
	v_cvt_pk_bf16_f32 v35, v26, v27
	global_store_dwordx4 v[48:49], v[32:35], off offset:256
	v_cvt_pk_bf16_f32 v24, v36, v37
	v_cvt_pk_bf16_f32 v25, v38, v39
	v_cvt_pk_bf16_f32 v26, v28, v29
	v_add_co_u32_e32 v28, vcc, s16, v138
	s_nop 0
	v_lshl_add_u64 v[32:33], v[138:139], 0, s[0:1]
	v_addc_co_u32_e32 v29, vcc, 0, v139, vcc
	v_cvt_pk_bf16_f32 v27, v30, v31
	global_store_dwordx4 v[28:29], v[24:27], off
	v_cvt_pk_bf16_f32 v16, v16, v17
	v_cvt_pk_bf16_f32 v17, v18, v19
	v_cvt_pk_bf16_f32 v18, v8, v9
	v_cvt_pk_bf16_f32 v19, v10, v11
	global_store_dwordx4 v[32:33], v[16:19], off offset:256
	v_cvt_pk_bf16_f32 v8, v20, v21
	v_cvt_pk_bf16_f32 v9, v22, v23
	v_cvt_pk_bf16_f32 v10, v12, v13
	v_add_co_u32_e32 v12, vcc, s81, v138
	s_nop 0
	v_lshl_add_u64 v[16:17], v[138:139], 0, s[54:55]
	v_addc_co_u32_e32 v13, vcc, 0, v139, vcc
	s_andn2_b64 vcc, exec, s[38:39]
	s_mov_b64 s[16:17], -1
	v_cvt_pk_bf16_f32 v11, v14, v15
	global_store_dwordx4 v[12:13], v[8:11], off
	v_cvt_pk_bf16_f32 v4, v4, v5
	v_cvt_pk_bf16_f32 v5, v6, v7
	v_cvt_pk_bf16_f32 v6, v0, v1
	v_cvt_pk_bf16_f32 v7, v2, v3
	global_store_dwordx4 v[16:17], v[4:7], off offset:256
	v_add_u32_e32 v158, 0x10000, v143
	ds_read_b128 v[146:149], v158
	ds_read_b128 v[150:153], v158 offset:1024
	ds_read_b128 v[154:157], v158 offset:2048
	ds_read_b128 v[158:161], v158 offset:3072
	s_cbranch_vccnz .LBB0_418
	s_andn2_b64 vcc, exec, s[6:7]
	s_cbranch_vccnz .LBB0_417
	s_barrier
	s_branch .LBB0_417

; #define PG8_STAGE(bufoff, gbase, voff) do { _Pragma("unroll") for (int _i = 0; _i < 2; ++_i) \
;         __builtin_amdgcn_global_load_lds((const unsigned*)((const char*)(gbase) + (voff)[_i]), (PG8_LAS unsigned*)(lds + (bufoff) + ldsw + _i * 8192), 16, 0, 0); } while (0)
; #define PG8_WAIT_V(n) asm volatile("s_waitcnt vmcnt(" #n ")" ::: "memory")
; #define PG8_BAR __builtin_amdgcn_s_barrier()
; template <class Epi, class Sched, bool ALIGN_EPI = false, bool SP2 = false>
; __device__ __forceinline__ void gemm_phase(PG8_LAS unsigned char* lds, const Gemm g, const Sched& S, const Epi& E) {
;     ...
;     const int tid = tid_, wid = __builtin_amdgcn_readfirstlane(tid >> 6), lane = tid & 63, wr = wid >> 2, wc = wid & 3, fr = lane & 15, fq = lane >> 4;
;     const int K = g.K, nt = K / BK;
;     unsigned voffA[2], voffB[2];
; #pragma unroll
;     for (int i = 0; i < 2; ++i) { int R, C; stage_rc(tid * 16 + i * 8192, R, C); const int Rb = Epi::PERM ? ((R & ~31) + perm32(R & 31)) : R;
;         voffA[i] = (unsigned)(R * K + C) * 2u; voffB[i] = (unsigned)(Rb * K + C) * 2u; }
;     const size_t kstep = (size_t)(BK * 2);
;     const size_t hstep = (size_t)HALF * K * 2;
;     const size_t tstep = 2 * hstep;
;     const unsigned ldsw = (unsigned)wid * 1024u;
;     const int aoff = lds_byte(wr * 64 + fr, fq * 8), boff = lds_byte(wc * 32 + fr, fq * 8);
;     ...
;         PG8_STAGE(PG8_SB(0, 0), cB, voffB); PG8_STAGE(PG8_SB(0, 1), cB + hstep, voffB); PG8_STAGE(PG8_SA(0, 0), cA, voffA); PG8_STAGE(PG8_SA(0, 1), cA + hstep, voffA);
;         if (wr == 1) PG8_BAR;
;         PG8_WAIT_V(2); PG8_BAR;
;         PG8_STAGE(PG8_SB(1, 0), cB + kstep, voffB); PG8_STAGE(PG8_SB(1, 1), cB + hstep + kstep, voffB);
;         PG8_WAIT_V(4); PG8_BAR;
.LBB0_595:
	s_add_u32 s72, s7, 0x25000000
	s_addc_u32 s73, s16, 0
	s_add_u32 s88, s7, 0x300000
	v_lshrrev_b32_e32 v12, 1, v10
	s_addc_u32 s89, s16, 0
	v_and_b32_e32 v12, 24, v12
	s_lshl_b32 s4, s4, 5
	v_and_b32_e32 v11, 15, v10
	v_lshlrev_b32_e32 v13, 1, v12
	v_lshlrev_b32_e32 v10, 2, v10
	s_and_b32 s7, s4, 0x60
	s_add_i32 m0, s37, 0x18000
	v_lshl_add_u64 v[0:1], v[0:1], 0, s[26:27]
	v_lshl_or_b32 v142, s5, 6, v11
	v_lshl_or_b32 v11, v11, 6, v13
	s_lshl_b32 s5, s5, 13
	v_and_b32_e32 v10, 32, v10
	s_lshl_b32 s4, s7, 7
	s_waitcnt vmcnt(2)
	s_barrier
	global_load_lds_dwordx4 v[0:1], off
	s_add_i32 m0, s37, 0x1a000
	v_bitop3_b32 v143, v11, s4, v10 bitop3:0xde
	s_add_u32 s4, s10, 0x80080
	v_bitop3_b32 v13, v11, s5, v10 bitop3:0xde
	v_lshl_add_u64 v[0:1], v[2:3], 0, s[26:27]
	s_addc_u32 s5, s11, 0
	global_load_lds_dwordx4 v[0:1], off
	s_add_i32 m0, s37, 0x1c000
	v_lshl_add_u64 v[0:1], s[4:5], 0, v[204:205]
	global_load_lds_dwordx4 v[0:1], off
	v_lshl_add_u64 v[0:1], s[4:5], 0, v[128:129]
	s_add_i32 m0, s37, 0x1e000
	s_cmpk_lt_u32 s6, 0x100
	global_load_lds_dwordx4 v[0:1], off
	v_lshlrev_b32_e32 v0, 15, v4
	v_and_b32_e32 v0, 0xffff0000, v0
	v_lshl_add_u32 v0, v5, 12, v0
	v_and_b32_e32 v1, 1, v4
	v_lshl_or_b32 v0, v1, 6, v0
	v_lshl_add_u32 v134, v6, 1, v0
	v_lshlrev_b32_e32 v0, 15, v8
	v_and_b32_e32 v0, 0xffff0000, v0
	s_waitcnt vmcnt(4)
	v_lshl_add_u32 v0, v7, 12, v0
	v_and_b32_e32 v1, 1, v8
	v_or_b32_e32 v144, s7, v12
	v_lshl_or_b32 v0, v1, 6, v0
	v_readlane_b32 s6, v255, 16
	v_mov_b32_e32 v133, v205
	v_mov_b32_e32 v131, v205
	s_cselect_b64 s[4:5], -1, 0
	v_mov_b32_e32 v135, v205
	v_lshl_add_u32 v136, v9, 1, v0
	v_mov_b32_e32 v137, v205
	s_mov_b32 s97, 0
	v_add_u32_e32 v145, 0, v13
	v_readlane_b32 s34, v255, 11
	s_mov_b32 s35, s6
	s_bitset1_b32 s35, 2
	s_lshl_b32 s34, s34, 1
	s_add_i32 s34, s34, s32
	s_barrier
	v_readlane_b32 s7, v255, 17
	v_add_u32_e32 v174, 0x14000, v143
	ds_read_b128 v[162:165], v174
	ds_read_b128 v[166:169], v174 offset:1024
	ds_read_b128 v[170:173], v174 offset:2048
	ds_read_b128 v[174:177], v174 offset:3072
	ds_read_b128 v[178:181], v145
	ds_read_b128 v[182:185], v145 offset:1024
	ds_read_b128 v[186:189], v145 offset:2048
	ds_read_b128 v[190:193], v145 offset:3072
	ds_read_b128 v[194:197], v145 offset:4096
	ds_read_b128 v[198:201], v145 offset:5120
	ds_read_b128 v[206:209], v145 offset:6144
	ds_read_b128 v[218:221], v145 offset:7168
	v_add_u32_e32 v158, 0x10000, v143
	ds_read_b128 v[146:149], v158
	ds_read_b128 v[150:153], v158 offset:1024
	ds_read_b128 v[154:157], v158 offset:2048
	ds_read_b128 v[158:161], v158 offset:3072
	s_branch .LBB0_598

; #define PG8_STAGE(bufoff, gbase, voff) do { _Pragma("unroll") for (int _i = 0; _i < 2; ++_i) \
;         __builtin_amdgcn_global_load_lds((const unsigned*)((const char*)(gbase) + (voff)[_i]), (PG8_LAS unsigned*)(lds + (bufoff) + ldsw + _i * 8192), 16, 0, 0); } while (0)
; #define PG8_LDA(dst, b, h) do { _Pragma("unroll") for (int m = 0; m < 4; ++m) _Pragma("unroll") for (int k = 0; k < 2; ++k) dst[m][k] = *(const PG8_LAS bf16x8*)(lds + PG8_SA(b, h) + aoff + m * 2048 + k * 1024); } while (0)
; #define PG8_LDB(dst, b, h) do { _Pragma("unroll") for (int n = 0; n < 2; ++n) _Pragma("unroll") for (int k = 0; k < 2; ++k) dst[n][k] = *(const PG8_LAS bf16x8*)(lds + PG8_SB(b, h) + boff + n * 2048 + k * 1024); } while (0)
; #define PG8_MMA(ai, bj, At, Bt) do { __builtin_amdgcn_s_setprio(1); _Pragma("unroll") for (int m = 0; m < 4; ++m) _Pragma("unroll") for (int n = 0; n < 2; ++n) _Pragma("unroll") for (int k = 0; k < 2; ++k) \
;         acc[ai][bj][m][n] = __builtin_amdgcn_mfma_f32_16x16x32_bf16(Bt[n][k], At[m][k], acc[ai][bj][m][n], 0, 0, 0); __builtin_amdgcn_s_setprio(0); } while (0)
; #define PG8_WAIT_V(n) asm volatile("s_waitcnt vmcnt(" #n ")" ::: "memory")
; #define PG8_WAIT_L(n) asm volatile("s_waitcnt lgkmcnt(" #n ")" ::: "memory")
; template <class Epi, class Sched, bool ALIGN_EPI = false, bool SP2 = false>
; __device__ __forceinline__ void gemm_phase(PG8_LAS unsigned char* lds, const Gemm g, const Sched& S, const Epi& E) {
;     ...
;         const bool has_next = S.next(ui + 1, nxt);
;         const char* nA = has_next ? (const char*)g.A + (size_t)nxt.pm * tstep : cA; const char* nB = has_next ? (const char*)g.Bt + (size_t)nxt.pn * tstep : cB;
;         for (int t = 0; t < nt; t += 2) {
;             const bool last = (t == nt - 2);
;             const char* a1 = cA + (size_t)(t + 1) * kstep;
;             const char* a2 = last ? nA : cA + (size_t)(t + 2) * kstep; const char* b2 = last ? nB : cB + (size_t)(t + 2) * kstep;
;             const char* a3 = a2 + kstep; const char* b3 = b2 + kstep;
;             if (last && has_next) S.a_ready(nxt);
;             if constexpr (SP2) {
;             PG8_LDB(B0, 0, 0); PG8_LDB(B1, 0, 1); PG8_SCHED; PG8_LDA(At, 0, 0); PG8_STAGE(PG8_SA(1, 0), a1, voffA); PG8_STAGE(PG8_SA(1, 1), a1 + hstep, voffA);
;             PG8_WAIT_V(8); PG8_WAIT_L(0); PG8_BAR; PG8_MMA(0, 0, At, B0); PG8_MMA(0, 1, At, B1); PG8_BAR; PG8_SCHED;
.LBB0_604:
	s_ashr_i32 s95, s94, 31
	s_lshl_b64 s[16:17], s[94:95], 20
	s_add_u32 s16, s20, s16
	s_addc_u32 s17, s21, s17
	s_and_b64 s[44:45], s[42:43], exec
	s_cselect_b32 s95, s17, s9
	s_cselect_b32 s70, s16, s8
	s_ashr_i32 s7, s6, 31
	s_lshl_b64 s[44:45], s[6:7], 20
	s_add_u32 s44, s22, s44
	s_addc_u32 s45, s23, s45
	s_and_b64 s[52:53], s[42:43], exec
	s_cselect_b32 s7, s45, s11
	s_cselect_b32 s71, s44, s10
	s_add_u32 s79, s10, 0x100
	v_lshl_add_u64 v[138:139], s[8:9], 0, v[134:135]
	v_lshl_add_u64 v[140:141], s[8:9], 0, v[136:137]
	s_addc_u32 s52, s11, 0
	s_mov_b32 s53, -2
	s_mov_b64 vcc, 0
	v_lshl_add_u32 v240, s35, 8, v142
	v_ashrrev_i32_e32 v241, 31, v240
	v_lshl_add_u64 v[240:241], v[240:241], 2, s[88:89]
	global_load_dword v242, v[240:241], off
	global_load_dword v243, v[240:241], off offset:64
	global_load_dword v244, v[240:241], off offset:128
	global_load_dword v245, v[240:241], off offset:192
	global_load_dword v246, v[240:241], off offset:512
	global_load_dword v247, v[240:241], off offset:576
	global_load_dword v248, v[240:241], off offset:640
	global_load_dword v249, v[240:241], off offset:704
	s_add_u32 s10, s8, vcc_lo
	s_addc_u32 s11, s9, vcc_hi
	s_add_u32 s38, s10, 0x100
	s_addc_u32 s39, s11, 0
	s_add_u32 s10, s79, vcc_lo
	s_addc_u32 s11, s52, vcc_hi
	s_add_i32 s78, 0, 0x10000
	s_cmpk_eq_i32 vcc_lo, 0xf00
	s_cselect_b32 s11, s7, s11
	s_cselect_b32 s10, s71, s10
	s_cselect_b32 s69, s95, s39
	s_cselect_b32 s68, s70, s38
	s_add_i32 s92, 0, 0x14000
	v_lshl_add_u64 v[202:203], v[140:141], 0, vcc
	v_lshl_add_u64 v[222:223], v[202:203], 0, s[26:27]
	s_add_i32 m0, s37, 0x8000
	global_load_lds_dwordx4 v[222:223], off
	v_lshl_add_u64 v[222:223], v[138:139], 0, vcc
	v_lshl_add_u64 v[232:233], v[222:223], 0, s[26:27]
	s_add_i32 m0, s37, 0xa000
	v_lshl_add_u64 v[202:203], v[202:203], 0, s[28:29]
	global_load_lds_dwordx4 v[232:233], off
	s_add_i32 m0, s37, 0xc000
	s_nop 0
	global_load_lds_dwordx4 v[202:203], off
	v_lshl_add_u64 v[202:203], v[222:223], 0, s[28:29]
	s_add_i32 m0, s37, 0xe000
	s_nop 0
	global_load_lds_dwordx4 v[202:203], off
	s_waitcnt vmcnt(8)
	s_waitcnt lgkmcnt(0)
	s_barrier
	v_mfma_f32_16x16x32_bf16 v[124:127], v[146:149], v[178:181], 0
	v_mfma_f32_16x16x32_bf16 v[120:123], v[154:157], v[178:181], 0
	v_mfma_f32_16x16x32_bf16 v[108:111], v[146:149], v[186:189], 0
	v_mfma_f32_16x16x32_bf16 v[104:107], v[154:157], v[186:189], 0
	v_mfma_f32_16x16x32_bf16 v[92:95], v[146:149], v[194:197], 0
	v_mfma_f32_16x16x32_bf16 v[88:91], v[154:157], v[194:197], 0
	v_mfma_f32_16x16x32_bf16 v[76:79], v[146:149], v[206:209], 0
	v_mfma_f32_16x16x32_bf16 v[72:75], v[154:157], v[206:209], 0
	v_mfma_f32_16x16x32_bf16 v[124:127], v[150:153], v[182:185], v[124:127]
	v_mfma_f32_16x16x32_bf16 v[120:123], v[158:161], v[182:185], v[120:123]
	v_mfma_f32_16x16x32_bf16 v[108:111], v[150:153], v[190:193], v[108:111]
	v_mfma_f32_16x16x32_bf16 v[104:107], v[158:161], v[190:193], v[104:107]
	v_mfma_f32_16x16x32_bf16 v[92:95], v[150:153], v[198:201], v[92:95]
	v_mfma_f32_16x16x32_bf16 v[88:91], v[158:161], v[198:201], v[88:91]
	v_mfma_f32_16x16x32_bf16 v[76:79], v[150:153], v[218:221], v[76:79]
	v_mfma_f32_16x16x32_bf16 v[72:75], v[158:161], v[218:221], v[72:75]
	v_mfma_f32_16x16x32_bf16 v[116:119], v[162:165], v[178:181], 0
	v_mfma_f32_16x16x32_bf16 v[112:115], v[170:173], v[178:181], 0
	v_mfma_f32_16x16x32_bf16 v[100:103], v[162:165], v[186:189], 0
	v_mfma_f32_16x16x32_bf16 v[96:99], v[170:173], v[186:189], 0
	v_mfma_f32_16x16x32_bf16 v[84:87], v[162:165], v[194:197], 0
	v_mfma_f32_16x16x32_bf16 v[80:83], v[170:173], v[194:197], 0
	v_mfma_f32_16x16x32_bf16 v[68:71], v[162:165], v[206:209], 0
	v_mfma_f32_16x16x32_bf16 v[64:67], v[170:173], v[206:209], 0
	v_mfma_f32_16x16x32_bf16 v[116:119], v[166:169], v[182:185], v[116:119]
	v_mfma_f32_16x16x32_bf16 v[112:115], v[174:177], v[182:185], v[112:115]
	v_mfma_f32_16x16x32_bf16 v[100:103], v[166:169], v[190:193], v[100:103]
	v_mfma_f32_16x16x32_bf16 v[96:99], v[174:177], v[190:193], v[96:99]
	v_mfma_f32_16x16x32_bf16 v[84:87], v[166:169], v[198:201], v[84:87]
	v_mfma_f32_16x16x32_bf16 v[80:83], v[174:177], v[198:201], v[80:83]
	v_mfma_f32_16x16x32_bf16 v[68:71], v[166:169], v[218:221], v[68:71]
	v_mfma_f32_16x16x32_bf16 v[64:67], v[174:177], v[218:221], v[64:67]
	s_barrier
; #define PG8_STAGE(bufoff, gbase, voff) do { _Pragma("unroll") for (int _i = 0; _i < 2; ++_i) \
;         __builtin_amdgcn_global_load_lds((const unsigned*)((const char*)(gbase) + (voff)[_i]), (PG8_LAS unsigned*)(lds + (bufoff) + ldsw + _i * 8192), 16, 0, 0); } while (0)
; #define PG8_LDA(dst, b, h) do { _Pragma("unroll") for (int m = 0; m < 4; ++m) _Pragma("unroll") for (int k = 0; k < 2; ++k) dst[m][k] = *(const PG8_LAS bf16x8*)(lds + PG8_SA(b, h) + aoff + m * 2048 + k * 1024); } while (0)
; #define PG8_MMA(ai, bj, At, Bt) do { __builtin_amdgcn_s_setprio(1); _Pragma("unroll") for (int m = 0; m < 4; ++m) _Pragma("unroll") for (int n = 0; n < 2; ++n) _Pragma("unroll") for (int k = 0; k < 2; ++k) \
;         acc[ai][bj][m][n] = __builtin_amdgcn_mfma_f32_16x16x32_bf16(Bt[n][k], At[m][k], acc[ai][bj][m][n], 0, 0, 0); __builtin_amdgcn_s_setprio(0); } while (0)
; #define PG8_WAIT_V(n) asm volatile("s_waitcnt vmcnt(" #n ")" ::: "memory")
; #define PG8_WAIT_L(n) asm volatile("s_waitcnt lgkmcnt(" #n ")" ::: "memory")
; #define PG8_BAR __builtin_amdgcn_s_barrier()
; #define PG8_SCHED __builtin_amdgcn_sched_barrier(0)
; template <class Epi, class Sched, bool ALIGN_EPI = false, bool SP2 = false>
; __device__ __forceinline__ void gemm_phase(PG8_LAS unsigned char* lds, const Gemm g, const Sched& S, const Epi& E) {
;     ...
;             PG8_LDA(At, 0, 1); PG8_STAGE(PG8_SB(0, 0), b2, voffB); PG8_STAGE(PG8_SB(0, 1), b2 + hstep, voffB);
;             PG8_WAIT_V(6); PG8_WAIT_L(0); PG8_BAR; PG8_MMA(1, 0, At, B0); PG8_MMA(1, 1, At, B1); PG8_BAR; PG8_SCHED;
	s_add_i32 s38, s78, s36
	v_lshl_add_u64 v[202:203], s[10:11], 0, v[204:205]
	s_mov_b32 m0, s38
	ds_read_b128 v[178:181], v145 offset:16384
	ds_read_b128 v[182:185], v145 offset:17408
	ds_read_b128 v[186:189], v145 offset:18432
	ds_read_b128 v[190:193], v145 offset:19456
	ds_read_b128 v[194:197], v145 offset:20480
	ds_read_b128 v[198:201], v145 offset:21504
	ds_read_b128 v[206:209], v145 offset:22528
	ds_read_b128 v[218:221], v145 offset:23552
	global_load_lds_dwordx4 v[202:203], off
	s_add_i32 m0, s38, 0x2000
	s_add_u32 s38, s10, 0x80000
	v_lshl_add_u64 v[222:223], s[10:11], 0, v[128:129]
	s_addc_u32 s39, s11, 0
	s_add_i32 s78, s92, s36
	global_load_lds_dwordx4 v[222:223], off
	v_lshl_add_u64 v[232:233], s[38:39], 0, v[204:205]
	s_mov_b32 m0, s78
	s_nop 0
	global_load_lds_dwordx4 v[232:233], off
	v_lshl_add_u64 v[232:233], s[38:39], 0, v[128:129]
	s_add_i32 m0, s78, 0x2000
	s_nop 0
	global_load_lds_dwordx4 v[232:233], off
	s_waitcnt vmcnt(6)
	s_waitcnt lgkmcnt(0)
	s_barrier
	v_mfma_f32_16x16x32_bf16 v[60:63], v[146:149], v[178:181], 0
	v_mfma_f32_16x16x32_bf16 v[56:59], v[154:157], v[178:181], 0
	v_mfma_f32_16x16x32_bf16 v[44:47], v[146:149], v[186:189], 0
	v_mfma_f32_16x16x32_bf16 v[40:43], v[154:157], v[186:189], 0
	v_mfma_f32_16x16x32_bf16 v[28:31], v[146:149], v[194:197], 0
	v_mfma_f32_16x16x32_bf16 v[24:27], v[154:157], v[194:197], 0
	v_mfma_f32_16x16x32_bf16 v[12:15], v[146:149], v[206:209], 0
	v_mfma_f32_16x16x32_bf16 v[8:11], v[154:157], v[206:209], 0
	v_mfma_f32_16x16x32_bf16 v[60:63], v[150:153], v[182:185], v[60:63]
	v_mfma_f32_16x16x32_bf16 v[56:59], v[158:161], v[182:185], v[56:59]
	v_mfma_f32_16x16x32_bf16 v[44:47], v[150:153], v[190:193], v[44:47]
	v_mfma_f32_16x16x32_bf16 v[40:43], v[158:161], v[190:193], v[40:43]
	v_mfma_f32_16x16x32_bf16 v[28:31], v[150:153], v[198:201], v[28:31]
	v_mfma_f32_16x16x32_bf16 v[24:27], v[158:161], v[198:201], v[24:27]
	v_mfma_f32_16x16x32_bf16 v[12:15], v[150:153], v[218:221], v[12:15]
	v_mfma_f32_16x16x32_bf16 v[8:11], v[158:161], v[218:221], v[8:11]
	v_mfma_f32_16x16x32_bf16 v[52:55], v[162:165], v[178:181], 0
	v_mfma_f32_16x16x32_bf16 v[48:51], v[170:173], v[178:181], 0
	v_mfma_f32_16x16x32_bf16 v[36:39], v[162:165], v[186:189], 0
	v_mfma_f32_16x16x32_bf16 v[32:35], v[170:173], v[186:189], 0
	v_mfma_f32_16x16x32_bf16 v[20:23], v[162:165], v[194:197], 0
	v_mfma_f32_16x16x32_bf16 v[16:19], v[170:173], v[194:197], 0
	v_mfma_f32_16x16x32_bf16 v[4:7], v[162:165], v[206:209], 0
	v_mfma_f32_16x16x32_bf16 v[0:3], v[170:173], v[206:209], 0
	v_mfma_f32_16x16x32_bf16 v[52:55], v[166:169], v[182:185], v[52:55]
	v_mfma_f32_16x16x32_bf16 v[48:51], v[174:177], v[182:185], v[48:51]
	v_mfma_f32_16x16x32_bf16 v[36:39], v[166:169], v[190:193], v[36:39]
	v_mfma_f32_16x16x32_bf16 v[32:35], v[174:177], v[190:193], v[32:35]
	v_mfma_f32_16x16x32_bf16 v[20:23], v[166:169], v[198:201], v[20:23]
	v_mfma_f32_16x16x32_bf16 v[16:19], v[174:177], v[198:201], v[16:19]
	v_mfma_f32_16x16x32_bf16 v[4:7], v[166:169], v[218:221], v[4:7]
	v_mfma_f32_16x16x32_bf16 v[0:3], v[174:177], v[218:221], v[0:3]
	s_barrier
	s_branch .Lpl_up

; __device__ __forceinline__ unsigned cvt_pk_bf16(float lo, float hi) { unsigned r; asm volatile("v_cvt_pk_bf16_f32 %0, %1, %2" : "=v"(r) : "v"(lo), "v"(hi)); return r; }
;     __device__ __forceinline__ void operator()(const f32x4 (&acc)[2][2][4][2], const Unit& u, int wr, int wc, int fr, int fq) const {
;         const int row0 = u.pm * BM + wr * 64 + fr; const int colt = u.pn * BM;
;         const float sc = (colt < scale_cols) ? scale0 : 1.f;
;         const int col0 = colt + wc * 32 + 8 * fq;
;         f32x4 cs[2][2];
; #pragma unroll
;         for (int bj = 0; bj < 2; ++bj) { cs[bj][0] = (f32x4){1.f, 1.f, 1.f, 1.f}; cs[bj][1] = cs[bj][0]; if (rsmode == 2) { cs[bj][0] = *(const f32x4*)(rs + col0 + bj * HALF); cs[bj][1] = *(const f32x4*)(rs + col0 + bj * HALF + 4); } }
; #pragma unroll
;         for (int ai = 0; ai < 2; ++ai)
; #pragma unroll
;             for (int m = 0; m < 4; ++m) { bf16_t* rowp = O + (size_t)(row0 + ai * HALF + m * 16) * ldc + col0;
;                 float rsc = sc; if (rsmode == 1) { const float r_ = rs[row0 + ai * HALF + m * 16]; rsc = sc * (ACT == 2 ? r_ * r_ : r_); }
; #pragma unroll
;                 for (int bj = 0; bj < 2; ++bj) { f32x4 v0 = acc[ai][bj][m][0], v1 = acc[ai][bj][m][1];
;                     if (ACT == 2) {
; #pragma unroll
;                         for (int e = 0; e < 4; ++e) { const float a0 = fmaxf(v0[e], 0.f), a1 = fmaxf(v1[e], 0.f); v0[e] = a0 * a0; v1[e] = a1 * a1; } }
;                     v0 = v0 * cs[bj][0] * rsc; v1 = v1 * cs[bj][1] * rsc; u32x4 w; w.x = cvt_pk_bf16(v0[0], v0[1]); w.y = cvt_pk_bf16(v0[2], v0[3]); w.z = cvt_pk_bf16(v1[0], v1[1]); w.w = cvt_pk_bf16(v1[2], v1[3]);
;                     *(u32x4*)(rowp + bj * HALF) = w; } }
.LBB0_608:
	v_add_u32_e32 v174, 0x14000, v143
	ds_read_b128 v[162:165], v174
	ds_read_b128 v[166:169], v174 offset:1024
	ds_read_b128 v[170:173], v174 offset:2048
	ds_read_b128 v[174:177], v174 offset:3072
	ds_read_b128 v[178:181], v145
	ds_read_b128 v[182:185], v145 offset:1024
	ds_read_b128 v[186:189], v145 offset:2048
	ds_read_b128 v[190:193], v145 offset:3072
	ds_read_b128 v[194:197], v145 offset:4096
	ds_read_b128 v[198:201], v145 offset:5120
	ds_read_b128 v[206:209], v145 offset:6144
	ds_read_b128 v[218:221], v145 offset:7168
	v_lshl_add_u32 v140, s35, 8, v142
	v_ashrrev_i32_e32 v141, 31, v140
	v_lshl_add_u64 v[138:139], v[140:141], 2, s[88:89]
	s_nop 0
	v_lshl_or_b32 v146, s34, 8, v144
	v_max_f32_e32 v152, v118, v118
	v_max_f32_e32 v153, v119, v119
	v_max_f32_e32 v118, 0, v126
	v_max_f32_e32 v119, 0, v127
	v_max_f32_e32 v148, v116, v116
	v_max_f32_e32 v149, v112, v112
	v_max_f32_e32 v150, v117, v117
	v_max_f32_e32 v151, v113, v113
	v_ashrrev_i32_e32 v147, 31, v146
	v_max_f32_e32 v112, 0, v124
	v_max_f32_e32 v116, 0, v120
	v_max_f32_e32 v113, 0, v125
	v_max_f32_e32 v117, 0, v121
	v_max_f32_e32 v120, 0, v122
	v_max_f32_e32 v121, 0, v123
	v_max_f32_e32 v126, 0, v152
	v_max_f32_e32 v127, 0, v153
	v_lshlrev_b64 v[152:153], 14, v[140:141]
	v_pk_mul_f32 v[118:119], v[118:119], v[118:119]
	v_max_f32_e32 v122, 0, v148
	v_max_f32_e32 v124, 0, v149
	v_max_f32_e32 v123, 0, v150
	v_max_f32_e32 v125, 0, v151
	v_max_f32_e32 v148, 0, v114
	v_max_f32_e32 v149, 0, v115
	v_or_b32_e32 v150, 16, v140
	v_lshlrev_b64 v[114:115], 1, v[146:147]
	v_pk_mul_f32 v[146:147], v[112:113], v[112:113]
	v_pk_mul_f32 v[116:117], v[116:117], v[116:117]
	v_pk_mul_f32 v[120:121], v[120:121], v[120:121]
	v_lshl_add_u64 v[112:113], s[72:73], 0, v[152:153]
	v_pk_mul_f32 v[122:123], v[122:123], v[122:123]
	v_pk_mul_f32 v[126:127], v[126:127], v[126:127]
	v_pk_mul_f32 v[124:125], v[124:125], v[124:125]
	v_pk_mul_f32 v[148:149], v[148:149], v[148:149]
	v_ashrrev_i32_e32 v151, 31, v150
	v_lshl_add_u64 v[112:113], v[112:113], 0, v[114:115]
	v_lshl_add_u64 v[152:153], v[150:151], 2, s[88:89]
	v_mul_f32_e32 v154, v242, v242
	v_pk_mul_f32 v[118:119], v[118:119], v[154:155] op_sel_hi:[1,0]
	v_pk_mul_f32 v[146:147], v[146:147], v[154:155] op_sel_hi:[1,0]
	v_pk_mul_f32 v[120:121], v[120:121], v[154:155] op_sel_hi:[1,0]
	v_pk_mul_f32 v[156:157], v[116:117], v[154:155] op_sel_hi:[1,0]
	v_cvt_pk_bf16_f32 v116, v146, v147
	v_cvt_pk_bf16_f32 v117, v118, v119
	v_pk_mul_f32 v[126:127], v[126:127], v[154:155] op_sel_hi:[1,0]
	v_cvt_pk_bf16_f32 v118, v156, v157
	v_cvt_pk_bf16_f32 v119, v120, v121
	v_pk_mul_f32 v[122:123], v[122:123], v[154:155] op_sel_hi:[1,0]
	v_pk_mul_f32 v[148:149], v[148:149], v[154:155] op_sel_hi:[1,0]
	v_pk_mul_f32 v[124:125], v[124:125], v[154:155] op_sel_hi:[1,0]
	global_store_dwordx4 v[112:113], v[116:119], off
	v_max_f32_e32 v121, v98, v98
	v_max_f32_e32 v98, 0, v104
	v_cvt_pk_bf16_f32 v116, v122, v123
	v_cvt_pk_bf16_f32 v117, v126, v127
	v_cvt_pk_bf16_f32 v118, v124, v125
	v_cvt_pk_bf16_f32 v119, v148, v149
	global_store_dwordx4 v[112:113], v[116:119], off offset:256
	s_nop 0
	v_max_f32_e32 v124, v99, v99
	v_max_f32_e32 v117, v96, v96
	v_max_f32_e32 v118, v101, v101
	v_max_f32_e32 v119, v97, v97
	v_max_f32_e32 v96, 0, v108
	v_max_f32_e32 v97, 0, v109
	v_max_f32_e32 v99, 0, v105
	v_max_f32_e32 v116, v100, v100
	v_max_f32_e32 v120, v102, v102
	v_max_f32_e32 v123, v103, v103
	v_max_f32_e32 v100, 0, v110
	v_max_f32_e32 v102, 0, v106
	v_max_f32_e32 v101, 0, v111
	v_max_f32_e32 v103, 0, v107
	v_max_f32_e32 v105, 0, v118
	v_max_f32_e32 v107, 0, v119
	v_pk_mul_f32 v[96:97], v[96:97], v[96:97]
	v_pk_mul_f32 v[98:99], v[98:99], v[98:99]
	v_lshlrev_b64 v[118:119], 14, v[150:151]
	v_max_f32_e32 v104, 0, v116
	v_max_f32_e32 v106, 0, v117
	v_max_f32_e32 v108, 0, v120
	v_max_f32_e32 v110, 0, v121
	v_max_f32_e32 v109, 0, v123
	v_max_f32_e32 v111, 0, v124
	v_or_b32_e32 v116, 32, v140
	v_pk_mul_f32 v[100:101], v[100:101], v[100:101]
	v_pk_mul_f32 v[102:103], v[102:103], v[102:103]
	v_lshl_add_u64 v[118:119], s[72:73], 0, v[118:119]
	v_pk_mul_f32 v[104:105], v[104:105], v[104:105]
	v_pk_mul_f32 v[108:109], v[108:109], v[108:109]
	v_pk_mul_f32 v[106:107], v[106:107], v[106:107]
	v_pk_mul_f32 v[110:111], v[110:111], v[110:111]
	v_ashrrev_i32_e32 v117, 31, v116
	v_lshl_add_u64 v[118:119], v[118:119], 0, v[114:115]
	v_lshl_add_u64 v[120:121], v[116:117], 2, s[88:89]
	s_mov_b32 s7, 0x200000
	s_mov_b64 s[8:9], 0x200000
	v_mul_f32_e32 v122, v243, v243
	v_pk_mul_f32 v[96:97], v[96:97], v[122:123] op_sel_hi:[1,0]
	v_pk_mul_f32 v[98:99], v[98:99], v[122:123] op_sel_hi:[1,0]
	v_pk_mul_f32 v[100:101], v[100:101], v[122:123] op_sel_hi:[1,0]
	v_pk_mul_f32 v[102:103], v[102:103], v[122:123] op_sel_hi:[1,0]
	v_cvt_pk_bf16_f32 v96, v96, v97
	v_cvt_pk_bf16_f32 v97, v100, v101
	v_cvt_pk_bf16_f32 v98, v98, v99
	v_pk_mul_f32 v[108:109], v[108:109], v[122:123] op_sel_hi:[1,0]
	v_cvt_pk_bf16_f32 v99, v102, v103
	v_pk_mul_f32 v[104:105], v[104:105], v[122:123] op_sel_hi:[1,0]
	v_pk_mul_f32 v[110:111], v[110:111], v[122:123] op_sel_hi:[1,0]
	v_pk_mul_f32 v[106:107], v[106:107], v[122:123] op_sel_hi:[1,0]
	global_store_dwordx4 v[118:119], v[96:99], off
	v_max_f32_e32 v101, v82, v82
	v_max_f32_e32 v82, 0, v88
	v_cvt_pk_bf16_f32 v96, v104, v105
	v_cvt_pk_bf16_f32 v97, v108, v109
	v_cvt_pk_bf16_f32 v98, v106, v107
	v_cvt_pk_bf16_f32 v99, v110, v111
	global_store_dwordx4 v[118:119], v[96:99], off offset:256
	s_nop 0
	v_max_f32_e32 v104, v83, v83
	v_max_f32_e32 v97, v80, v80
	v_max_f32_e32 v98, v85, v85
	v_max_f32_e32 v99, v81, v81
	v_max_f32_e32 v80, 0, v92
	v_max_f32_e32 v81, 0, v93
	v_max_f32_e32 v83, 0, v89
; __device__ __forceinline__ unsigned cvt_pk_bf16(float lo, float hi) { unsigned r; asm volatile("v_cvt_pk_bf16_f32 %0, %1, %2" : "=v"(r) : "v"(lo), "v"(hi)); return r; }
;     __device__ __forceinline__ void operator()(const f32x4 (&acc)[2][2][4][2], const Unit& u, int wr, int wc, int fr, int fq) const {
;     ...
;             for (int m = 0; m < 4; ++m) { bf16_t* rowp = O + (size_t)(row0 + ai * HALF + m * 16) * ldc + col0;
;                 float rsc = sc; if (rsmode == 1) { const float r_ = rs[row0 + ai * HALF + m * 16]; rsc = sc * (ACT == 2 ? r_ * r_ : r_); }
; #pragma unroll
;                 for (int bj = 0; bj < 2; ++bj) { f32x4 v0 = acc[ai][bj][m][0], v1 = acc[ai][bj][m][1];
;                     if (ACT == 2) {
; #pragma unroll
;                         for (int e = 0; e < 4; ++e) { const float a0 = fmaxf(v0[e], 0.f), a1 = fmaxf(v1[e], 0.f); v0[e] = a0 * a0; v1[e] = a1 * a1; } }
;                     v0 = v0 * cs[bj][0] * rsc; v1 = v1 * cs[bj][1] * rsc; u32x4 w; w.x = cvt_pk_bf16(v0[0], v0[1]); w.y = cvt_pk_bf16(v0[2], v0[3]); w.z = cvt_pk_bf16(v1[0], v1[1]); w.w = cvt_pk_bf16(v1[2], v1[3]);
;                     *(u32x4*)(rowp + bj * HALF) = w; } }
	v_max_f32_e32 v96, v84, v84
	v_max_f32_e32 v100, v86, v86
	v_max_f32_e32 v103, v87, v87
	v_max_f32_e32 v84, 0, v94
	v_max_f32_e32 v86, 0, v90
	v_max_f32_e32 v85, 0, v95
	v_max_f32_e32 v87, 0, v91
	v_max_f32_e32 v89, 0, v98
	v_max_f32_e32 v91, 0, v99
	v_pk_mul_f32 v[80:81], v[80:81], v[80:81]
	v_pk_mul_f32 v[82:83], v[82:83], v[82:83]
	v_lshlrev_b64 v[98:99], 14, v[116:117]
	v_max_f32_e32 v88, 0, v96
	v_max_f32_e32 v90, 0, v97
	v_max_f32_e32 v92, 0, v100
	v_max_f32_e32 v94, 0, v101
	v_max_f32_e32 v93, 0, v103
	v_max_f32_e32 v95, 0, v104
	v_or_b32_e32 v96, 48, v140
	v_pk_mul_f32 v[84:85], v[84:85], v[84:85]
	v_pk_mul_f32 v[86:87], v[86:87], v[86:87]
	v_lshl_add_u64 v[98:99], s[72:73], 0, v[98:99]
	v_pk_mul_f32 v[88:89], v[88:89], v[88:89]
	v_pk_mul_f32 v[92:93], v[92:93], v[92:93]
	v_pk_mul_f32 v[90:91], v[90:91], v[90:91]
	v_pk_mul_f32 v[94:95], v[94:95], v[94:95]
	v_ashrrev_i32_e32 v97, 31, v96
	v_lshl_add_u64 v[98:99], v[98:99], 0, v[114:115]
	v_lshl_add_u64 v[100:101], v[96:97], 2, s[88:89]
	v_mul_f32_e32 v102, v244, v244
	v_pk_mul_f32 v[80:81], v[80:81], v[102:103] op_sel_hi:[1,0]
	v_pk_mul_f32 v[82:83], v[82:83], v[102:103] op_sel_hi:[1,0]
	v_pk_mul_f32 v[84:85], v[84:85], v[102:103] op_sel_hi:[1,0]
	v_pk_mul_f32 v[86:87], v[86:87], v[102:103] op_sel_hi:[1,0]
	v_cvt_pk_bf16_f32 v80, v80, v81
	v_cvt_pk_bf16_f32 v81, v84, v85
	v_cvt_pk_bf16_f32 v82, v82, v83
	v_pk_mul_f32 v[92:93], v[92:93], v[102:103] op_sel_hi:[1,0]
	v_cvt_pk_bf16_f32 v83, v86, v87
	v_pk_mul_f32 v[88:89], v[88:89], v[102:103] op_sel_hi:[1,0]
	v_pk_mul_f32 v[94:95], v[94:95], v[102:103] op_sel_hi:[1,0]
	v_pk_mul_f32 v[90:91], v[90:91], v[102:103] op_sel_hi:[1,0]
	global_store_dwordx4 v[98:99], v[80:83], off
	v_max_f32_e32 v84, v65, v65
	v_max_f32_e32 v86, v66, v66
	v_cvt_pk_bf16_f32 v80, v88, v89
	v_cvt_pk_bf16_f32 v81, v92, v93
	v_cvt_pk_bf16_f32 v82, v90, v91
	v_cvt_pk_bf16_f32 v83, v94, v95
	global_store_dwordx4 v[98:99], v[80:83], off offset:256
	s_nop 0
	v_max_f32_e32 v88, v67, v67
	v_max_f32_e32 v80, v68, v68
	v_max_f32_e32 v81, v64, v64
	v_max_f32_e32 v64, 0, v76
	v_max_f32_e32 v66, 0, v72
	v_max_f32_e32 v65, 0, v77
	v_max_f32_e32 v67, 0, v73
	v_max_f32_e32 v83, v69, v69
	v_max_f32_e32 v85, v70, v70
	v_max_f32_e32 v87, v71, v71
	v_max_f32_e32 v68, 0, v78
	v_max_f32_e32 v70, 0, v74
	v_max_f32_e32 v69, 0, v79
	v_max_f32_e32 v71, 0, v75
	v_max_f32_e32 v72, 0, v80
	v_max_f32_e32 v74, 0, v81
	v_pk_mul_f32 v[64:65], v[64:65], v[64:65]
	v_pk_mul_f32 v[66:67], v[66:67], v[66:67]
	v_lshlrev_b64 v[80:81], 14, v[96:97]
	v_max_f32_e32 v73, 0, v83
	v_max_f32_e32 v75, 0, v84
	v_max_f32_e32 v76, 0, v85
	v_max_f32_e32 v78, 0, v86
	v_max_f32_e32 v77, 0, v87
	v_max_f32_e32 v79, 0, v88
	v_pk_mul_f32 v[68:69], v[68:69], v[68:69]
	v_pk_mul_f32 v[70:71], v[70:71], v[70:71]
	v_lshl_add_u64 v[80:81], s[72:73], 0, v[80:81]
	v_pk_mul_f32 v[72:73], v[72:73], v[72:73]
	v_pk_mul_f32 v[76:77], v[76:77], v[76:77]
	v_pk_mul_f32 v[74:75], v[74:75], v[74:75]
	v_pk_mul_f32 v[78:79], v[78:79], v[78:79]
	v_lshl_add_u64 v[80:81], v[80:81], 0, v[114:115]
	v_mul_f32_e32 v82, v245, v245
	v_pk_mul_f32 v[64:65], v[64:65], v[82:83] op_sel_hi:[1,0]
	v_pk_mul_f32 v[66:67], v[66:67], v[82:83] op_sel_hi:[1,0]
	v_pk_mul_f32 v[68:69], v[68:69], v[82:83] op_sel_hi:[1,0]
	v_pk_mul_f32 v[70:71], v[70:71], v[82:83] op_sel_hi:[1,0]
	v_cvt_pk_bf16_f32 v64, v64, v65
	v_cvt_pk_bf16_f32 v65, v68, v69
	v_cvt_pk_bf16_f32 v66, v66, v67
	v_pk_mul_f32 v[76:77], v[76:77], v[82:83] op_sel_hi:[1,0]
	v_cvt_pk_bf16_f32 v67, v70, v71
	v_pk_mul_f32 v[72:73], v[72:73], v[82:83] op_sel_hi:[1,0]
	v_pk_mul_f32 v[78:79], v[78:79], v[82:83] op_sel_hi:[1,0]
	v_pk_mul_f32 v[74:75], v[74:75], v[82:83] op_sel_hi:[1,0]
	global_store_dwordx4 v[80:81], v[64:67], off
	v_max_f32_e32 v70, v50, v50
	v_max_f32_e32 v50, 0, v56
	v_cvt_pk_bf16_f32 v64, v72, v73
	v_cvt_pk_bf16_f32 v65, v76, v77
	v_cvt_pk_bf16_f32 v66, v74, v75
	v_cvt_pk_bf16_f32 v67, v78, v79
	global_store_dwordx4 v[80:81], v[64:67], off offset:256
	s_nop 0
	v_max_f32_e32 v72, v51, v51
	v_max_f32_e32 v65, v48, v48
	v_max_f32_e32 v67, v49, v49
	v_max_f32_e32 v48, 0, v60
	v_max_f32_e32 v49, 0, v61
	v_max_f32_e32 v51, 0, v57
	v_max_f32_e32 v64, v52, v52
	v_max_f32_e32 v66, v53, v53
	v_max_f32_e32 v69, v54, v54
	v_max_f32_e32 v71, v55, v55
	v_max_f32_e32 v52, 0, v62
	v_max_f32_e32 v54, 0, v58
	v_max_f32_e32 v53, 0, v63
	v_max_f32_e32 v55, 0, v59
	v_pk_mul_f32 v[48:49], v[48:49], v[48:49]
	v_pk_mul_f32 v[50:51], v[50:51], v[50:51]
	v_max_f32_e32 v56, 0, v64
	v_max_f32_e32 v58, 0, v65
	v_max_f32_e32 v57, 0, v66
	v_max_f32_e32 v59, 0, v67
	v_max_f32_e32 v60, 0, v69
	v_max_f32_e32 v62, 0, v70
	v_max_f32_e32 v61, 0, v71
	v_max_f32_e32 v63, 0, v72
	v_pk_mul_f32 v[52:53], v[52:53], v[52:53]
	v_pk_mul_f32 v[54:55], v[54:55], v[54:55]
	v_add_co_u32_e32 v66, vcc, s7, v112
	v_pk_mul_f32 v[56:57], v[56:57], v[56:57]
	v_pk_mul_f32 v[60:61], v[60:61], v[60:61]
	v_pk_mul_f32 v[58:59], v[58:59], v[58:59]
	v_pk_mul_f32 v[62:63], v[62:63], v[62:63]
	v_lshl_add_u64 v[64:65], v[112:113], 0, s[8:9]
	v_addc_co_u32_e32 v67, vcc, 0, v113, vcc
	s_mov_b32 s7, 0x240000
	s_mov_b64 s[8:9], 0x240000
	v_mul_f32_e32 v68, v246, v246
	v_pk_mul_f32 v[48:49], v[48:49], v[68:69] op_sel_hi:[1,0]
	v_pk_mul_f32 v[50:51], v[50:51], v[68:69] op_sel_hi:[1,0]
	v_pk_mul_f32 v[52:53], v[52:53], v[68:69] op_sel_hi:[1,0]
	v_pk_mul_f32 v[54:55], v[54:55], v[68:69] op_sel_hi:[1,0]
	v_cvt_pk_bf16_f32 v48, v48, v49
	v_cvt_pk_bf16_f32 v49, v52, v53
	v_cvt_pk_bf16_f32 v50, v50, v51
	v_pk_mul_f32 v[60:61], v[60:61], v[68:69] op_sel_hi:[1,0]
	v_cvt_pk_bf16_f32 v51, v54, v55
	v_pk_mul_f32 v[56:57], v[56:57], v[68:69] op_sel_hi:[1,0]
; __device__ __forceinline__ unsigned cvt_pk_bf16(float lo, float hi) { unsigned r; asm volatile("v_cvt_pk_bf16_f32 %0, %1, %2" : "=v"(r) : "v"(lo), "v"(hi)); return r; }
; #define PG8_STAGE(bufoff, gbase, voff) do { _Pragma("unroll") for (int _i = 0; _i < 2; ++_i) \
;         __builtin_amdgcn_global_load_lds((const unsigned*)((const char*)(gbase) + (voff)[_i]), (PG8_LAS unsigned*)(lds + (bufoff) + ldsw + _i * 8192), 16, 0, 0); } while (0)
; #define PG8_LDA(dst, b, h) do { _Pragma("unroll") for (int m = 0; m < 4; ++m) _Pragma("unroll") for (int k = 0; k < 2; ++k) dst[m][k] = *(const PG8_LAS bf16x8*)(lds + PG8_SA(b, h) + aoff + m * 2048 + k * 1024); } while (0)
; #define PG8_LDB(dst, b, h) do { _Pragma("unroll") for (int n = 0; n < 2; ++n) _Pragma("unroll") for (int k = 0; k < 2; ++k) dst[n][k] = *(const PG8_LAS bf16x8*)(lds + PG8_SB(b, h) + boff + n * 2048 + k * 1024); } while (0)
; #define PG8_SCHED __builtin_amdgcn_sched_barrier(0)
;     __device__ __forceinline__ void operator()(const f32x4 (&acc)[2][2][4][2], const Unit& u, int wr, int wc, int fr, int fq) const {
;     ...
;             for (int m = 0; m < 4; ++m) { bf16_t* rowp = O + (size_t)(row0 + ai * HALF + m * 16) * ldc + col0;
;                 float rsc = sc; if (rsmode == 1) { const float r_ = rs[row0 + ai * HALF + m * 16]; rsc = sc * (ACT == 2 ? r_ * r_ : r_); }
; #pragma unroll
;                 for (int bj = 0; bj < 2; ++bj) { f32x4 v0 = acc[ai][bj][m][0], v1 = acc[ai][bj][m][1];
;                     if (ACT == 2) {
; #pragma unroll
;                         for (int e = 0; e < 4; ++e) { const float a0 = fmaxf(v0[e], 0.f), a1 = fmaxf(v1[e], 0.f); v0[e] = a0 * a0; v1[e] = a1 * a1; } }
;                     v0 = v0 * cs[bj][0] * rsc; v1 = v1 * cs[bj][1] * rsc; u32x4 w; w.x = cvt_pk_bf16(v0[0], v0[1]); w.y = cvt_pk_bf16(v0[2], v0[3]); w.z = cvt_pk_bf16(v1[0], v1[1]); w.w = cvt_pk_bf16(v1[2], v1[3]);
;                     *(u32x4*)(rowp + bj * HALF) = w; } }
; template <class Epi, class Sched, bool ALIGN_EPI = false, bool SP2 = false>
; __device__ __forceinline__ void gemm_phase(PG8_LAS unsigned char* lds, const Gemm g, const Sched& S, const Epi& E) {
;     ...
;             PG8_LDB(B0, 0, 0); PG8_LDB(B1, 0, 1); PG8_SCHED; PG8_LDA(At, 0, 0); PG8_STAGE(PG8_SA(1, 0), a1, voffA); PG8_STAGE(PG8_SA(1, 1), a1 + hstep, voffA);
	v_pk_mul_f32 v[62:63], v[62:63], v[68:69] op_sel_hi:[1,0]
	v_pk_mul_f32 v[58:59], v[58:59], v[68:69] op_sel_hi:[1,0]
	global_store_dwordx4 v[66:67], v[48:51], off
	v_max_f32_e32 v54, v34, v34
	v_max_f32_e32 v34, 0, v40
	v_cvt_pk_bf16_f32 v48, v56, v57
	v_cvt_pk_bf16_f32 v49, v60, v61
	v_cvt_pk_bf16_f32 v50, v58, v59
	v_cvt_pk_bf16_f32 v51, v62, v63
	global_store_dwordx4 v[64:65], v[48:51], off offset:256
	s_nop 0
	v_max_f32_e32 v56, v35, v35
	v_max_f32_e32 v49, v32, v32
	v_max_f32_e32 v51, v33, v33
	v_max_f32_e32 v32, 0, v44
	v_max_f32_e32 v33, 0, v45
	v_max_f32_e32 v35, 0, v41
	v_max_f32_e32 v48, v36, v36
	v_max_f32_e32 v50, v37, v37
	v_max_f32_e32 v53, v38, v38
	v_max_f32_e32 v55, v39, v39
	v_max_f32_e32 v36, 0, v46
	v_max_f32_e32 v38, 0, v42
	v_max_f32_e32 v37, 0, v47
	v_max_f32_e32 v39, 0, v43
	v_pk_mul_f32 v[32:33], v[32:33], v[32:33]
	v_pk_mul_f32 v[34:35], v[34:35], v[34:35]
	v_max_f32_e32 v40, 0, v48
	v_max_f32_e32 v42, 0, v49
	v_max_f32_e32 v41, 0, v50
	v_max_f32_e32 v43, 0, v51
	v_max_f32_e32 v44, 0, v53
	v_max_f32_e32 v46, 0, v54
	v_max_f32_e32 v45, 0, v55
	v_max_f32_e32 v47, 0, v56
	v_pk_mul_f32 v[36:37], v[36:37], v[36:37]
	v_pk_mul_f32 v[38:39], v[38:39], v[38:39]
	v_add_co_u32_e32 v50, vcc, s7, v112
	v_pk_mul_f32 v[40:41], v[40:41], v[40:41]
	v_pk_mul_f32 v[44:45], v[44:45], v[44:45]
	v_pk_mul_f32 v[42:43], v[42:43], v[42:43]
	v_pk_mul_f32 v[46:47], v[46:47], v[46:47]
	v_lshl_add_u64 v[48:49], v[112:113], 0, s[8:9]
	v_addc_co_u32_e32 v51, vcc, 0, v113, vcc
	s_mov_b32 s7, 0x280000
	s_mov_b64 s[8:9], 0x280000
	v_mul_f32_e32 v52, v247, v247
	v_pk_mul_f32 v[32:33], v[32:33], v[52:53] op_sel_hi:[1,0]
	v_pk_mul_f32 v[34:35], v[34:35], v[52:53] op_sel_hi:[1,0]
	v_pk_mul_f32 v[36:37], v[36:37], v[52:53] op_sel_hi:[1,0]
	v_pk_mul_f32 v[38:39], v[38:39], v[52:53] op_sel_hi:[1,0]
	v_cvt_pk_bf16_f32 v32, v32, v33
	v_cvt_pk_bf16_f32 v33, v36, v37
	v_cvt_pk_bf16_f32 v34, v34, v35
	v_pk_mul_f32 v[44:45], v[44:45], v[52:53] op_sel_hi:[1,0]
	v_cvt_pk_bf16_f32 v35, v38, v39
	v_pk_mul_f32 v[40:41], v[40:41], v[52:53] op_sel_hi:[1,0]
	v_pk_mul_f32 v[46:47], v[46:47], v[52:53] op_sel_hi:[1,0]
	v_pk_mul_f32 v[42:43], v[42:43], v[52:53] op_sel_hi:[1,0]
	global_store_dwordx4 v[50:51], v[32:35], off
	v_max_f32_e32 v38, v18, v18
	v_max_f32_e32 v18, 0, v24
	v_cvt_pk_bf16_f32 v32, v40, v41
	v_cvt_pk_bf16_f32 v33, v44, v45
	v_cvt_pk_bf16_f32 v34, v42, v43
	v_cvt_pk_bf16_f32 v35, v46, v47
	global_store_dwordx4 v[48:49], v[32:35], off offset:256
	s_nop 0
	v_max_f32_e32 v40, v19, v19
	v_max_f32_e32 v33, v16, v16
	v_max_f32_e32 v35, v17, v17
	v_max_f32_e32 v16, 0, v28
	v_max_f32_e32 v17, 0, v29
	v_max_f32_e32 v19, 0, v25
	v_max_f32_e32 v32, v20, v20
	v_max_f32_e32 v34, v21, v21
	v_max_f32_e32 v37, v22, v22
	v_max_f32_e32 v39, v23, v23
	v_max_f32_e32 v20, 0, v30
	v_max_f32_e32 v22, 0, v26
	v_max_f32_e32 v21, 0, v31
	v_max_f32_e32 v23, 0, v27
	v_pk_mul_f32 v[16:17], v[16:17], v[16:17]
	v_pk_mul_f32 v[18:19], v[18:19], v[18:19]
	v_max_f32_e32 v24, 0, v32
	v_max_f32_e32 v26, 0, v33
	v_max_f32_e32 v25, 0, v34
	v_max_f32_e32 v27, 0, v35
	v_max_f32_e32 v28, 0, v37
	v_max_f32_e32 v30, 0, v38
	v_max_f32_e32 v29, 0, v39
	v_max_f32_e32 v31, 0, v40
	v_pk_mul_f32 v[20:21], v[20:21], v[20:21]
	v_pk_mul_f32 v[22:23], v[22:23], v[22:23]
	v_add_co_u32_e32 v34, vcc, s7, v112
	v_pk_mul_f32 v[24:25], v[24:25], v[24:25]
	v_pk_mul_f32 v[28:29], v[28:29], v[28:29]
	v_pk_mul_f32 v[26:27], v[26:27], v[26:27]
	v_pk_mul_f32 v[30:31], v[30:31], v[30:31]
	v_lshl_add_u64 v[32:33], v[112:113], 0, s[8:9]
	v_addc_co_u32_e32 v35, vcc, 0, v113, vcc
	s_mov_b32 s7, 0x2c0000
	s_andn2_b64 vcc, exec, s[42:43]
	s_mov_b64 s[8:9], 0x2c0000
	v_mul_f32_e32 v36, v248, v248
	v_pk_mul_f32 v[16:17], v[16:17], v[36:37] op_sel_hi:[1,0]
	v_pk_mul_f32 v[18:19], v[18:19], v[36:37] op_sel_hi:[1,0]
	v_pk_mul_f32 v[20:21], v[20:21], v[36:37] op_sel_hi:[1,0]
	v_pk_mul_f32 v[22:23], v[22:23], v[36:37] op_sel_hi:[1,0]
	v_cvt_pk_bf16_f32 v16, v16, v17
	v_cvt_pk_bf16_f32 v17, v20, v21
	v_cvt_pk_bf16_f32 v18, v18, v19
	v_pk_mul_f32 v[28:29], v[28:29], v[36:37] op_sel_hi:[1,0]
	v_cvt_pk_bf16_f32 v19, v22, v23
	v_pk_mul_f32 v[24:25], v[24:25], v[36:37] op_sel_hi:[1,0]
	v_pk_mul_f32 v[30:31], v[30:31], v[36:37] op_sel_hi:[1,0]
	v_pk_mul_f32 v[26:27], v[26:27], v[36:37] op_sel_hi:[1,0]
	global_store_dwordx4 v[34:35], v[16:19], off
	v_max_f32_e32 v22, v2, v2
	v_max_f32_e32 v2, 0, v8
	v_cvt_pk_bf16_f32 v16, v24, v25
	v_cvt_pk_bf16_f32 v17, v28, v29
	v_cvt_pk_bf16_f32 v18, v26, v27
	v_cvt_pk_bf16_f32 v19, v30, v31
	global_store_dwordx4 v[32:33], v[16:19], off offset:256
	s_nop 0
	v_max_f32_e32 v24, v3, v3
	v_max_f32_e32 v17, v0, v0
	v_max_f32_e32 v19, v1, v1
	v_max_f32_e32 v0, 0, v12
	v_max_f32_e32 v1, 0, v13
	v_max_f32_e32 v3, 0, v9
	v_max_f32_e32 v16, v4, v4
	v_max_f32_e32 v18, v5, v5
	v_max_f32_e32 v21, v6, v6
	v_max_f32_e32 v23, v7, v7
	v_max_f32_e32 v4, 0, v14
	v_max_f32_e32 v6, 0, v10
	v_max_f32_e32 v5, 0, v15
	v_max_f32_e32 v7, 0, v11
	v_pk_mul_f32 v[0:1], v[0:1], v[0:1]
	v_pk_mul_f32 v[2:3], v[2:3], v[2:3]
	v_max_f32_e32 v8, 0, v16
	v_max_f32_e32 v10, 0, v17
	v_max_f32_e32 v9, 0, v18
	v_max_f32_e32 v11, 0, v19
	v_max_f32_e32 v12, 0, v21
	v_max_f32_e32 v14, 0, v22
	v_max_f32_e32 v13, 0, v23
	v_max_f32_e32 v15, 0, v24
	v_pk_mul_f32 v[4:5], v[4:5], v[4:5]
	v_pk_mul_f32 v[6:7], v[6:7], v[6:7]
	v_add_co_u32_e64 v18, s[42:43], s7, v112
	v_pk_mul_f32 v[8:9], v[8:9], v[8:9]
	v_pk_mul_f32 v[12:13], v[12:13], v[12:13]
	v_pk_mul_f32 v[10:11], v[10:11], v[10:11]
	v_pk_mul_f32 v[14:15], v[14:15], v[14:15]
	v_lshl_add_u64 v[16:17], v[112:113], 0, s[8:9]
	v_addc_co_u32_e64 v19, s[42:43], 0, v113, s[42:43]
	s_mov_b64 s[8:9], -1
	v_mul_f32_e32 v20, v249, v249
	v_pk_mul_f32 v[0:1], v[0:1], v[20:21] op_sel_hi:[1,0]
	v_pk_mul_f32 v[2:3], v[2:3], v[20:21] op_sel_hi:[1,0]
	v_pk_mul_f32 v[4:5], v[4:5], v[20:21] op_sel_hi:[1,0]
	v_pk_mul_f32 v[6:7], v[6:7], v[20:21] op_sel_hi:[1,0]
	v_cvt_pk_bf16_f32 v0, v0, v1
	v_cvt_pk_bf16_f32 v1, v4, v5
	v_cvt_pk_bf16_f32 v2, v2, v3
	v_pk_mul_f32 v[12:13], v[12:13], v[20:21] op_sel_hi:[1,0]
	v_cvt_pk_bf16_f32 v3, v6, v7
	v_pk_mul_f32 v[8:9], v[8:9], v[20:21] op_sel_hi:[1,0]
	v_pk_mul_f32 v[14:15], v[14:15], v[20:21] op_sel_hi:[1,0]
	v_pk_mul_f32 v[10:11], v[10:11], v[20:21] op_sel_hi:[1,0]
	global_store_dwordx4 v[18:19], v[0:3], off
	s_nop 1
	v_cvt_pk_bf16_f32 v0, v8, v9
	v_cvt_pk_bf16_f32 v1, v12, v13
	v_cvt_pk_bf16_f32 v2, v10, v11
	v_cvt_pk_bf16_f32 v3, v14, v15
	global_store_dwordx4 v[16:17], v[0:3], off offset:256
	v_add_u32_e32 v158, 0x10000, v143
	ds_read_b128 v[146:149], v158
	ds_read_b128 v[150:153], v158 offset:1024
	ds_read_b128 v[154:157], v158 offset:2048
	ds_read_b128 v[158:161], v158 offset:3072
	s_cbranch_vccnz .LBB0_597
	s_andn2_b64 vcc, exec, s[76:77]
	s_cbranch_vccnz .LBB0_596
	s_barrier
	s_branch .LBB0_596

; #define PG8_STAGE(bufoff, gbase, voff) do { _Pragma("unroll") for (int _i = 0; _i < 2; ++_i) \
;         __builtin_amdgcn_global_load_lds((const unsigned*)((const char*)(gbase) + (voff)[_i]), (PG8_LAS unsigned*)(lds + (bufoff) + ldsw + _i * 8192), 16, 0, 0); } while (0)
; #define PG8_WAIT_V(n) asm volatile("s_waitcnt vmcnt(" #n ")" ::: "memory")
; #define PG8_BAR __builtin_amdgcn_s_barrier()
; template <class Epi, class Sched, bool ALIGN_EPI = false, bool SP2 = false>
; __device__ __forceinline__ void gemm_phase(PG8_LAS unsigned char* lds, const Gemm g, const Sched& S, const Epi& E) {
;     ...
;     const int tid = tid_, wid = __builtin_amdgcn_readfirstlane(tid >> 6), lane = tid & 63, wr = wid >> 2, wc = wid & 3, fr = lane & 15, fq = lane >> 4;
;     const int K = g.K, nt = K / BK;
;     unsigned voffA[2], voffB[2];
; #pragma unroll
;     for (int i = 0; i < 2; ++i) { int R, C; stage_rc(tid * 16 + i * 8192, R, C); const int Rb = Epi::PERM ? ((R & ~31) + perm32(R & 31)) : R;
;         voffA[i] = (unsigned)(R * K + C) * 2u; voffB[i] = (unsigned)(Rb * K + C) * 2u; }
;     const size_t kstep = (size_t)(BK * 2);
;     const size_t hstep = (size_t)HALF * K * 2;
;     const size_t tstep = 2 * hstep;
;     const unsigned ldsw = (unsigned)wid * 1024u;
;     const int aoff = lds_byte(wr * 64 + fr, fq * 8), boff = lds_byte(wc * 32 + fr, fq * 8);
;     ...
;         PG8_STAGE(PG8_SB(0, 0), cB, voffB); PG8_STAGE(PG8_SB(0, 1), cB + hstep, voffB); PG8_STAGE(PG8_SA(0, 0), cA, voffA); PG8_STAGE(PG8_SA(0, 1), cA + hstep, voffA);
;         if (wr == 1) PG8_BAR;
;         PG8_WAIT_V(2); PG8_BAR;
;         PG8_STAGE(PG8_SB(1, 0), cB + kstep, voffB); PG8_STAGE(PG8_SB(1, 1), cB + hstep + kstep, voffB);
;         PG8_WAIT_V(4); PG8_BAR;
.LBB0_692:
	s_add_u32 s8, s8, 0x35000000
	v_lshrrev_b32_e32 v12, 1, v10
	s_addc_u32 s9, s9, 0
	v_and_b32_e32 v11, 15, v10
	v_and_b32_e32 v12, 24, v12
	s_lshl_b32 s11, s11, 5
	v_lshl_or_b32 v142, s40, 6, v11
	v_lshlrev_b32_e32 v13, 1, v12
	s_lshl_b32 s38, s40, 13
	v_lshlrev_b32_e32 v10, 2, v10
	s_and_b32 s40, s11, 0x60
	s_add_i32 m0, s36, 0x18000
	v_lshl_add_u64 v[0:1], v[0:1], 0, s[26:27]
	v_lshl_or_b32 v11, v11, 6, v13
	v_and_b32_e32 v10, 32, v10
	s_lshl_b32 s11, s40, 7
	s_waitcnt vmcnt(2)
	s_barrier
	global_load_lds_dwordx4 v[0:1], off
	s_add_i32 m0, s36, 0x1a000
	v_bitop3_b32 v13, v11, s38, v10 bitop3:0xde
	s_add_u32 s38, s44, 0x200080
	v_lshl_add_u64 v[0:1], v[2:3], 0, s[26:27]
	s_addc_u32 s39, s45, 0
	global_load_lds_dwordx4 v[0:1], off
	s_add_i32 m0, s36, 0x1c000
	v_lshl_add_u64 v[0:1], s[38:39], 0, v[204:205]
	global_load_lds_dwordx4 v[0:1], off
	v_lshl_add_u64 v[0:1], s[38:39], 0, v[128:129]
	s_add_i32 m0, s36, 0x1e000
	s_cmpk_lt_u32 s10, 0x100
	global_load_lds_dwordx4 v[0:1], off
	v_lshlrev_b32_e32 v0, 17, v8
	v_and_b32_e32 v0, 0xfffc0000, v0
	v_lshl_add_u32 v0, v7, 14, v0
	v_and_b32_e32 v1, 1, v8
	v_lshl_or_b32 v0, v1, 6, v0
	v_lshl_add_u32 v134, v9, 1, v0
	v_lshlrev_b32_e32 v0, 17, v4
	v_and_b32_e32 v0, 0xfffc0000, v0
	s_waitcnt vmcnt(4)
	v_lshl_add_u32 v0, v5, 14, v0
	v_and_b32_e32 v1, 1, v4
	v_lshl_or_b32 v0, v1, 6, v0
	v_readlane_b32 s38, v255, 20
	v_mov_b32_e32 v133, v205
	v_mov_b32_e32 v131, v205
	v_bitop3_b32 v143, v11, s11, v10 bitop3:0xde
	s_cselect_b64 s[10:11], -1, 0
	v_or_b32_e32 v144, s40, v12
	v_mov_b32_e32 v135, v205
	v_lshl_add_u32 v136, v6, 1, v0
	v_mov_b32_e32 v137, v205
	s_mov_b32 s84, 0
	v_add_u32_e32 v145, 0, v13
	v_readlane_b32 s95, v254, 60
	s_nop 3
	s_bfe_u32 s32, s38, 0x10002
	s_lshl_b32 s95, s95, 1
	s_add_i32 s95, s95, s32
	s_bitset0_b32 s38, 2
	s_mov_b32 s94, s38
	s_barrier
	v_readlane_b32 s39, v255, 21
	v_add_u32_e32 v174, 0x14000, v143
	ds_read_b128 v[162:165], v174
	ds_read_b128 v[166:169], v174 offset:1024
	ds_read_b128 v[170:173], v174 offset:2048
	ds_read_b128 v[174:177], v174 offset:3072
	ds_read_b128 v[178:181], v145
	ds_read_b128 v[182:185], v145 offset:1024
	ds_read_b128 v[186:189], v145 offset:2048
	ds_read_b128 v[190:193], v145 offset:3072
	ds_read_b128 v[194:197], v145 offset:4096
	ds_read_b128 v[198:201], v145 offset:5120
	ds_read_b128 v[206:209], v145 offset:6144
	ds_read_b128 v[218:221], v145 offset:7168
	v_add_u32_e32 v158, 0x10000, v143
	ds_read_b128 v[146:149], v158
	ds_read_b128 v[150:153], v158 offset:1024
	ds_read_b128 v[154:157], v158 offset:2048
	ds_read_b128 v[158:161], v158 offset:3072
	s_branch .LBB0_695

; #define PG8_STAGE(bufoff, gbase, voff) do { _Pragma("unroll") for (int _i = 0; _i < 2; ++_i) \
;         __builtin_amdgcn_global_load_lds((const unsigned*)((const char*)(gbase) + (voff)[_i]), (PG8_LAS unsigned*)(lds + (bufoff) + ldsw + _i * 8192), 16, 0, 0); } while (0)
; #define PG8_LDA(dst, b, h) do { _Pragma("unroll") for (int m = 0; m < 4; ++m) _Pragma("unroll") for (int k = 0; k < 2; ++k) dst[m][k] = *(const PG8_LAS bf16x8*)(lds + PG8_SA(b, h) + aoff + m * 2048 + k * 1024); } while (0)
; #define PG8_LDB(dst, b, h) do { _Pragma("unroll") for (int n = 0; n < 2; ++n) _Pragma("unroll") for (int k = 0; k < 2; ++k) dst[n][k] = *(const PG8_LAS bf16x8*)(lds + PG8_SB(b, h) + boff + n * 2048 + k * 1024); } while (0)
; #define PG8_WAIT_V(n) asm volatile("s_waitcnt vmcnt(" #n ")" ::: "memory")
; #define PG8_WAIT_L(n) asm volatile("s_waitcnt lgkmcnt(" #n ")" ::: "memory")
; #define PG8_BAR __builtin_amdgcn_s_barrier()
; #define PG8_SCHED __builtin_amdgcn_sched_barrier(0)
; template <class Epi, class Sched, bool ALIGN_EPI = false, bool SP2 = false>
; __device__ __forceinline__ void gemm_phase(PG8_LAS unsigned char* lds, const Gemm g, const Sched& S, const Epi& E) {
;     ...
;         const bool has_next = S.next(ui + 1, nxt);
;         const char* nA = has_next ? (const char*)g.A + (size_t)nxt.pm * tstep : cA; const char* nB = has_next ? (const char*)g.Bt + (size_t)nxt.pn * tstep : cB;
;         for (int t = 0; t < nt; t += 2) {
;             const bool last = (t == nt - 2);
;             const char* a1 = cA + (size_t)(t + 1) * kstep;
;             const char* a2 = last ? nA : cA + (size_t)(t + 2) * kstep; const char* b2 = last ? nB : cB + (size_t)(t + 2) * kstep;
;             const char* a3 = a2 + kstep; const char* b3 = b2 + kstep;
;             if (last && has_next) S.a_ready(nxt);
;             if constexpr (SP2) {
;             PG8_LDB(B0, 0, 0); PG8_LDB(B1, 0, 1); PG8_SCHED; PG8_LDA(At, 0, 0); PG8_STAGE(PG8_SA(1, 0), a1, voffA); PG8_STAGE(PG8_SA(1, 1), a1 + hstep, voffA);
;             PG8_WAIT_V(8); PG8_WAIT_L(0); PG8_BAR; PG8_MMA(0, 0, At, B0); PG8_MMA(0, 1, At, B1); PG8_BAR; PG8_SCHED;
;             PG8_LDA(At, 0, 1); PG8_STAGE(PG8_SB(0, 0), b2, voffB); PG8_STAGE(PG8_SB(0, 1), b2 + hstep, voffB);
;             PG8_WAIT_V(6); PG8_WAIT_L(0); PG8_BAR; PG8_MMA(1, 0, At, B0); PG8_MMA(1, 1, At, B1); PG8_BAR; PG8_SCHED;
.LBB0_701:
	s_ashr_i32 s47, s46, 31
	s_lshl_b64 s[38:39], s[46:47], 22
	s_add_u32 s72, s20, s38
	s_addc_u32 s73, s21, s39
	s_and_b64 s[38:39], s[40:41], exec
	s_cselect_b32 s47, s73, s17
	s_cselect_b32 s70, s72, s16
	s_ashr_i32 s43, s42, 31
	s_lshl_b64 s[38:39], s[42:43], 22
	s_add_u32 s76, s23, s38
	s_addc_u32 s77, s34, s39
	s_and_b64 s[38:39], s[40:41], exec
	s_cselect_b32 s43, s77, s45
	s_cselect_b32 s71, s76, s44
	s_add_u32 s97, s44, 0x100
	s_addc_u32 vcc_lo, s45, 0
	v_lshl_add_u64 v[138:139], s[16:17], 0, v[134:135]
	v_lshl_add_u64 v[140:141], s[16:17], 0, v[136:137]
	s_mov_b32 s52, -2
	s_mov_b64 s[88:89], 0
	s_add_u32 s38, s16, s88
	s_addc_u32 s39, s17, s89
	s_add_u32 s38, s38, 0x100
	s_addc_u32 s39, s39, 0
	s_add_u32 s44, s97, s88
	s_addc_u32 s45, vcc_lo, s89
	s_add_i32 s53, 0, 0x10000
	s_cmpk_eq_i32 s88, 0x3f00
	s_cselect_b32 s45, s43, s45
	s_cselect_b32 s44, s71, s44
	s_cselect_b32 s69, s47, s39
	s_cselect_b32 s68, s70, s38
	s_add_i32 s78, 0, 0x14000
	v_lshl_add_u64 v[202:203], v[138:139], 0, s[88:89]
	v_lshl_add_u64 v[222:223], v[202:203], 0, s[26:27]
	s_add_i32 m0, s36, 0x8000
	global_load_lds_dwordx4 v[222:223], off
	v_lshl_add_u64 v[222:223], v[140:141], 0, s[88:89]
	v_lshl_add_u64 v[232:233], v[222:223], 0, s[26:27]
	s_add_i32 m0, s36, 0xa000
	v_lshl_add_u64 v[202:203], v[202:203], 0, s[90:91]
	global_load_lds_dwordx4 v[232:233], off
	s_add_i32 m0, s36, 0xc000
	s_nop 0
	global_load_lds_dwordx4 v[202:203], off
	v_lshl_add_u64 v[202:203], v[222:223], 0, s[90:91]
	s_add_i32 m0, s36, 0xe000
	s_nop 0
	global_load_lds_dwordx4 v[202:203], off
	s_waitcnt vmcnt(8)
	s_waitcnt lgkmcnt(0)
	s_barrier
	v_mfma_f32_16x16x32_bf16 v[124:127], v[146:149], v[178:181], 0
	v_mfma_f32_16x16x32_bf16 v[120:123], v[154:157], v[178:181], 0
	v_mfma_f32_16x16x32_bf16 v[116:119], v[146:149], v[186:189], 0
	v_mfma_f32_16x16x32_bf16 v[108:111], v[154:157], v[186:189], 0
	v_mfma_f32_16x16x32_bf16 v[100:103], v[146:149], v[194:197], 0
	v_mfma_f32_16x16x32_bf16 v[92:95], v[154:157], v[194:197], 0
	v_mfma_f32_16x16x32_bf16 v[84:87], v[146:149], v[206:209], 0
	v_mfma_f32_16x16x32_bf16 v[76:79], v[154:157], v[206:209], 0
	v_mfma_f32_16x16x32_bf16 v[124:127], v[150:153], v[182:185], v[124:127]
	v_mfma_f32_16x16x32_bf16 v[120:123], v[158:161], v[182:185], v[120:123]
	v_mfma_f32_16x16x32_bf16 v[116:119], v[150:153], v[190:193], v[116:119]
	v_mfma_f32_16x16x32_bf16 v[108:111], v[158:161], v[190:193], v[108:111]
	v_mfma_f32_16x16x32_bf16 v[100:103], v[150:153], v[198:201], v[100:103]
	v_mfma_f32_16x16x32_bf16 v[92:95], v[158:161], v[198:201], v[92:95]
	v_mfma_f32_16x16x32_bf16 v[84:87], v[150:153], v[218:221], v[84:87]
	v_mfma_f32_16x16x32_bf16 v[76:79], v[158:161], v[218:221], v[76:79]
	v_mfma_f32_16x16x32_bf16 v[112:115], v[162:165], v[178:181], 0
	v_mfma_f32_16x16x32_bf16 v[104:107], v[170:173], v[178:181], 0
	v_mfma_f32_16x16x32_bf16 v[96:99], v[162:165], v[186:189], 0
	v_mfma_f32_16x16x32_bf16 v[88:91], v[170:173], v[186:189], 0
	v_mfma_f32_16x16x32_bf16 v[80:83], v[162:165], v[194:197], 0
	v_mfma_f32_16x16x32_bf16 v[72:75], v[170:173], v[194:197], 0
	v_mfma_f32_16x16x32_bf16 v[68:71], v[162:165], v[206:209], 0
	v_mfma_f32_16x16x32_bf16 v[64:67], v[170:173], v[206:209], 0
	v_mfma_f32_16x16x32_bf16 v[112:115], v[166:169], v[182:185], v[112:115]
	v_mfma_f32_16x16x32_bf16 v[104:107], v[174:177], v[182:185], v[104:107]
	v_mfma_f32_16x16x32_bf16 v[96:99], v[166:169], v[190:193], v[96:99]
	v_mfma_f32_16x16x32_bf16 v[88:91], v[174:177], v[190:193], v[88:91]
	v_mfma_f32_16x16x32_bf16 v[80:83], v[166:169], v[198:201], v[80:83]
	v_mfma_f32_16x16x32_bf16 v[72:75], v[174:177], v[198:201], v[72:75]
	v_mfma_f32_16x16x32_bf16 v[68:71], v[166:169], v[218:221], v[68:71]
	v_mfma_f32_16x16x32_bf16 v[64:67], v[174:177], v[218:221], v[64:67]
	s_barrier
	s_add_i32 s38, s53, s35
	v_lshl_add_u64 v[202:203], s[44:45], 0, v[204:205]
	s_mov_b32 m0, s38
	ds_read_b128 v[178:181], v145 offset:16384
	ds_read_b128 v[182:185], v145 offset:17408
	ds_read_b128 v[186:189], v145 offset:18432
	ds_read_b128 v[190:193], v145 offset:19456
	ds_read_b128 v[194:197], v145 offset:20480
	ds_read_b128 v[198:201], v145 offset:21504
	ds_read_b128 v[206:209], v145 offset:22528
	ds_read_b128 v[218:221], v145 offset:23552
	global_load_lds_dwordx4 v[202:203], off
	s_add_i32 m0, s38, 0x2000
	s_add_u32 s38, s44, 0x200000
	v_lshl_add_u64 v[222:223], s[44:45], 0, v[128:129]
	s_addc_u32 s39, s45, 0
	s_add_i32 s53, s78, s35
	global_load_lds_dwordx4 v[222:223], off
	v_lshl_add_u64 v[232:233], s[38:39], 0, v[204:205]
	s_mov_b32 m0, s53
	s_nop 0
	global_load_lds_dwordx4 v[232:233], off
	v_lshl_add_u64 v[232:233], s[38:39], 0, v[128:129]
	s_add_i32 m0, s53, 0x2000
	s_nop 0
	global_load_lds_dwordx4 v[232:233], off
	s_waitcnt vmcnt(6)
	s_waitcnt lgkmcnt(0)
	s_barrier
	v_mfma_f32_16x16x32_bf16 v[60:63], v[146:149], v[178:181], 0
	v_mfma_f32_16x16x32_bf16 v[56:59], v[154:157], v[178:181], 0
	v_mfma_f32_16x16x32_bf16 v[52:55], v[146:149], v[186:189], 0
	v_mfma_f32_16x16x32_bf16 v[44:47], v[154:157], v[186:189], 0
	v_mfma_f32_16x16x32_bf16 v[36:39], v[146:149], v[194:197], 0
	v_mfma_f32_16x16x32_bf16 v[28:31], v[154:157], v[194:197], 0
	v_mfma_f32_16x16x32_bf16 v[20:23], v[146:149], v[206:209], 0
	v_mfma_f32_16x16x32_bf16 v[12:15], v[154:157], v[206:209], 0
	v_mfma_f32_16x16x32_bf16 v[60:63], v[150:153], v[182:185], v[60:63]
	v_mfma_f32_16x16x32_bf16 v[56:59], v[158:161], v[182:185], v[56:59]
	v_mfma_f32_16x16x32_bf16 v[52:55], v[150:153], v[190:193], v[52:55]
	v_mfma_f32_16x16x32_bf16 v[44:47], v[158:161], v[190:193], v[44:47]
	v_mfma_f32_16x16x32_bf16 v[36:39], v[150:153], v[198:201], v[36:39]
	v_mfma_f32_16x16x32_bf16 v[28:31], v[158:161], v[198:201], v[28:31]
	v_mfma_f32_16x16x32_bf16 v[20:23], v[150:153], v[218:221], v[20:23]
	v_mfma_f32_16x16x32_bf16 v[12:15], v[158:161], v[218:221], v[12:15]
	v_mfma_f32_16x16x32_bf16 v[48:51], v[162:165], v[178:181], 0
	v_mfma_f32_16x16x32_bf16 v[40:43], v[170:173], v[178:181], 0
	v_mfma_f32_16x16x32_bf16 v[32:35], v[162:165], v[186:189], 0
	v_mfma_f32_16x16x32_bf16 v[24:27], v[170:173], v[186:189], 0
	v_mfma_f32_16x16x32_bf16 v[16:19], v[162:165], v[194:197], 0
	v_mfma_f32_16x16x32_bf16 v[8:11], v[170:173], v[194:197], 0
	v_mfma_f32_16x16x32_bf16 v[4:7], v[162:165], v[206:209], 0
	v_mfma_f32_16x16x32_bf16 v[0:3], v[170:173], v[206:209], 0
	v_mfma_f32_16x16x32_bf16 v[48:51], v[166:169], v[182:185], v[48:51]
	v_mfma_f32_16x16x32_bf16 v[40:43], v[174:177], v[182:185], v[40:43]
	v_mfma_f32_16x16x32_bf16 v[32:35], v[166:169], v[190:193], v[32:35]
	v_mfma_f32_16x16x32_bf16 v[24:27], v[174:177], v[190:193], v[24:27]
	v_mfma_f32_16x16x32_bf16 v[16:19], v[166:169], v[198:201], v[16:19]
	v_mfma_f32_16x16x32_bf16 v[8:11], v[174:177], v[198:201], v[8:11]
	v_mfma_f32_16x16x32_bf16 v[4:7], v[166:169], v[218:221], v[4:7]
	v_mfma_f32_16x16x32_bf16 v[0:3], v[174:177], v[218:221], v[0:3]
	s_barrier
	s_branch .Lpl_down

; __device__ __forceinline__ unsigned cvt_pk_bf16(float lo, float hi) { unsigned r; asm volatile("v_cvt_pk_bf16_f32 %0, %1, %2" : "=v"(r) : "v"(lo), "v"(hi)); return r; }
; #define PG8_STAGE(bufoff, gbase, voff) do { _Pragma("unroll") for (int _i = 0; _i < 2; ++_i) \
;         __builtin_amdgcn_global_load_lds((const unsigned*)((const char*)(gbase) + (voff)[_i]), (PG8_LAS unsigned*)(lds + (bufoff) + ldsw + _i * 8192), 16, 0, 0); } while (0)
;     __device__ __forceinline__ void operator()(const f32x4 (&acc)[2][2][4][2], const Unit& u, int wr, int wc, int fr, int fq) const {
;         const int row0 = u.pm * BM + wr * 64 + fr; const int colt = u.pn * BM;
;         const float sc = (colt < scale_cols) ? scale0 : 1.f;
;         const int col0 = colt + wc * 32 + 8 * fq;
;         f32x4 cs[2][2];
; #pragma unroll
;         for (int bj = 0; bj < 2; ++bj) { cs[bj][0] = (f32x4){1.f, 1.f, 1.f, 1.f}; cs[bj][1] = cs[bj][0]; if (rsmode == 2) { cs[bj][0] = *(const f32x4*)(rs + col0 + bj * HALF); cs[bj][1] = *(const f32x4*)(rs + col0 + bj * HALF + 4); } }
; #pragma unroll
;         for (int ai = 0; ai < 2; ++ai)
; #pragma unroll
;             for (int m = 0; m < 4; ++m) { bf16_t* rowp = O + (size_t)(row0 + ai * HALF + m * 16) * ldc + col0;
;                 float rsc = sc; if (rsmode == 1) { const float r_ = rs[row0 + ai * HALF + m * 16]; rsc = sc * (ACT == 2 ? r_ * r_ : r_); }
; #pragma unroll
;                 for (int bj = 0; bj < 2; ++bj) { f32x4 v0 = acc[ai][bj][m][0], v1 = acc[ai][bj][m][1];
;                     if (ACT == 2) {
; #pragma unroll
;                         for (int e = 0; e < 4; ++e) { const float a0 = fmaxf(v0[e], 0.f), a1 = fmaxf(v1[e], 0.f); v0[e] = a0 * a0; v1[e] = a1 * a1; } }
;                     v0 = v0 * cs[bj][0] * rsc; v1 = v1 * cs[bj][1] * rsc; u32x4 w; w.x = cvt_pk_bf16(v0[0], v0[1]); w.y = cvt_pk_bf16(v0[2], v0[3]); w.z = cvt_pk_bf16(v1[0], v1[1]); w.w = cvt_pk_bf16(v1[2], v1[3]);
;                     *(u32x4*)(rowp + bj * HALF) = w; } }
; template <class Epi, class Sched, bool ALIGN_EPI = false, bool SP2 = false>
; __device__ __forceinline__ void gemm_phase(PG8_LAS unsigned char* lds, const Gemm g, const Sched& S, const Epi& E) {
;     ...
;             PG8_LDB(B0, 0, 0); PG8_LDB(B1, 0, 1); PG8_SCHED; PG8_LDA(At, 0, 0); PG8_STAGE(PG8_SA(1, 0), a1, voffA); PG8_STAGE(PG8_SA(1, 1), a1 + hstep, voffA);
.LBB0_705:
	v_add_u32_e32 v174, 0x14000, v143
	ds_read_b128 v[162:165], v174
	ds_read_b128 v[166:169], v174 offset:1024
	ds_read_b128 v[170:173], v174 offset:2048
	ds_read_b128 v[174:177], v174 offset:3072
	ds_read_b128 v[178:181], v145
	ds_read_b128 v[182:185], v145 offset:1024
	ds_read_b128 v[186:189], v145 offset:2048
	ds_read_b128 v[190:193], v145 offset:3072
	ds_read_b128 v[194:197], v145 offset:4096
	ds_read_b128 v[198:201], v145 offset:5120
	ds_read_b128 v[206:209], v145 offset:6144
	ds_read_b128 v[218:221], v145 offset:7168
	v_lshl_add_u32 v140, s94, 8, v142
	v_lshl_or_b32 v138, s95, 8, v144
	v_ashrrev_i32_e32 v141, 31, v140
	v_ashrrev_i32_e32 v139, 31, v138
	v_lshlrev_b64 v[146:147], 12, v[140:141]
	v_lshl_add_u64 v[146:147], s[8:9], 0, v[146:147]
	v_lshlrev_b64 v[148:149], 1, v[138:139]
	v_lshl_add_u64 v[138:139], v[146:147], 0, v[148:149]
	v_cvt_pk_bf16_f32 v124, v124, v125
	v_cvt_pk_bf16_f32 v125, v126, v127
	v_cvt_pk_bf16_f32 v126, v120, v121
	v_cvt_pk_bf16_f32 v127, v122, v123
	global_store_dwordx4 v[138:139], v[124:127], off
	v_cvt_pk_bf16_f32 v112, v112, v113
	v_cvt_pk_bf16_f32 v113, v114, v115
	v_cvt_pk_bf16_f32 v114, v104, v105
	v_or_b32_e32 v104, 16, v140
	v_ashrrev_i32_e32 v105, 31, v104
	v_lshlrev_b64 v[104:105], 12, v[104:105]
	v_lshl_add_u64 v[104:105], s[8:9], 0, v[104:105]
	v_cvt_pk_bf16_f32 v115, v106, v107
	global_store_dwordx4 v[138:139], v[112:115], off offset:256
	s_mov_b64 s[16:17], 0x90000
	s_nop 0
	v_lshl_add_u64 v[112:113], v[104:105], 0, v[148:149]
	v_cvt_pk_bf16_f32 v104, v116, v117
	v_cvt_pk_bf16_f32 v105, v118, v119
	v_cvt_pk_bf16_f32 v106, v108, v109
	v_cvt_pk_bf16_f32 v107, v110, v111
	global_store_dwordx4 v[112:113], v[104:107], off
	v_cvt_pk_bf16_f32 v96, v96, v97
	v_cvt_pk_bf16_f32 v97, v98, v99
	v_cvt_pk_bf16_f32 v98, v88, v89
	v_or_b32_e32 v88, 32, v140
	v_ashrrev_i32_e32 v89, 31, v88
	v_lshlrev_b64 v[88:89], 12, v[88:89]
	v_lshl_add_u64 v[88:89], s[8:9], 0, v[88:89]
	v_cvt_pk_bf16_f32 v99, v90, v91
	global_store_dwordx4 v[112:113], v[96:99], off offset:256
	s_nop 1
	v_lshl_add_u64 v[96:97], v[88:89], 0, v[148:149]
	v_cvt_pk_bf16_f32 v88, v100, v101
	v_cvt_pk_bf16_f32 v89, v102, v103
	v_cvt_pk_bf16_f32 v90, v92, v93
	v_cvt_pk_bf16_f32 v91, v94, v95
	global_store_dwordx4 v[96:97], v[88:91], off
	v_cvt_pk_bf16_f32 v80, v80, v81
	v_cvt_pk_bf16_f32 v81, v82, v83
	v_cvt_pk_bf16_f32 v82, v72, v73
	v_or_b32_e32 v72, 48, v140
	v_ashrrev_i32_e32 v73, 31, v72
	v_lshlrev_b64 v[72:73], 12, v[72:73]
	v_lshl_add_u64 v[72:73], s[8:9], 0, v[72:73]
	v_cvt_pk_bf16_f32 v83, v74, v75
	global_store_dwordx4 v[96:97], v[80:83], off offset:256
	s_nop 1
	v_lshl_add_u64 v[80:81], v[72:73], 0, v[148:149]
	v_cvt_pk_bf16_f32 v72, v84, v85
	v_cvt_pk_bf16_f32 v73, v86, v87
	v_cvt_pk_bf16_f32 v74, v76, v77
	v_cvt_pk_bf16_f32 v75, v78, v79
	global_store_dwordx4 v[80:81], v[72:75], off
	v_cvt_pk_bf16_f32 v68, v68, v69
	v_cvt_pk_bf16_f32 v69, v70, v71
	v_cvt_pk_bf16_f32 v70, v64, v65
	v_cvt_pk_bf16_f32 v71, v66, v67
	global_store_dwordx4 v[80:81], v[68:71], off offset:256
	v_cvt_pk_bf16_f32 v60, v60, v61
	v_cvt_pk_bf16_f32 v61, v62, v63
	v_cvt_pk_bf16_f32 v62, v56, v57
	v_add_co_u32_e32 v56, vcc, s85, v138
	v_lshl_add_u64 v[64:65], v[138:139], 0, s[24:25]
	s_nop 0
	v_addc_co_u32_e32 v57, vcc, 0, v139, vcc
	v_cvt_pk_bf16_f32 v63, v58, v59
	global_store_dwordx4 v[56:57], v[60:63], off
	v_cvt_pk_bf16_f32 v48, v48, v49
	v_cvt_pk_bf16_f32 v49, v50, v51
	v_cvt_pk_bf16_f32 v50, v40, v41
	v_cvt_pk_bf16_f32 v51, v42, v43
	global_store_dwordx4 v[64:65], v[48:51], off offset:256
	v_cvt_pk_bf16_f32 v40, v52, v53
	v_cvt_pk_bf16_f32 v41, v54, v55
	v_cvt_pk_bf16_f32 v42, v44, v45
	v_cvt_pk_bf16_f32 v43, v46, v47
	s_nop 1
	v_lshl_add_u64 v[48:49], v[138:139], 0, s[16:17]
	s_mov_b32 s16, 0x90000
	v_add_co_u32_e32 v44, vcc, s16, v138
	s_mov_b64 s[16:17], 0xa0000
	s_nop 0
	v_addc_co_u32_e32 v45, vcc, 0, v139, vcc
	global_store_dwordx4 v[44:45], v[40:43], off
	v_cvt_pk_bf16_f32 v32, v32, v33
	v_cvt_pk_bf16_f32 v33, v34, v35
	v_cvt_pk_bf16_f32 v34, v24, v25
	v_cvt_pk_bf16_f32 v35, v26, v27
	global_store_dwordx4 v[48:49], v[32:35], off offset:256
	v_cvt_pk_bf16_f32 v24, v36, v37
	v_cvt_pk_bf16_f32 v25, v38, v39
	v_cvt_pk_bf16_f32 v26, v28, v29
	v_cvt_pk_bf16_f32 v27, v30, v31
	s_nop 1
	v_lshl_add_u64 v[32:33], v[138:139], 0, s[16:17]
	s_mov_b32 s16, 0xa0000
	v_add_co_u32_e32 v28, vcc, s16, v138
	s_mov_b64 s[16:17], -1
	s_nop 0
	v_addc_co_u32_e32 v29, vcc, 0, v139, vcc
	global_store_dwordx4 v[28:29], v[24:27], off
	v_cvt_pk_bf16_f32 v16, v16, v17
	v_cvt_pk_bf16_f32 v17, v18, v19
	v_cvt_pk_bf16_f32 v18, v8, v9
	v_cvt_pk_bf16_f32 v19, v10, v11
	global_store_dwordx4 v[32:33], v[16:19], off offset:256
	v_cvt_pk_bf16_f32 v8, v20, v21
	v_cvt_pk_bf16_f32 v9, v22, v23
	v_cvt_pk_bf16_f32 v10, v12, v13
	v_add_co_u32_e32 v12, vcc, s81, v138
	s_nop 0
	v_lshl_add_u64 v[16:17], v[138:139], 0, s[54:55]
	v_addc_co_u32_e32 v13, vcc, 0, v139, vcc
	s_andn2_b64 vcc, exec, s[40:41]
	v_cvt_pk_bf16_f32 v11, v14, v15
	global_store_dwordx4 v[12:13], v[8:11], off
	v_cvt_pk_bf16_f32 v4, v4, v5
	v_cvt_pk_bf16_f32 v5, v6, v7
	v_cvt_pk_bf16_f32 v6, v0, v1
	v_cvt_pk_bf16_f32 v7, v2, v3
	global_store_dwordx4 v[16:17], v[4:7], off offset:256
	v_add_u32_e32 v158, 0x10000, v143
	ds_read_b128 v[146:149], v158
	ds_read_b128 v[150:153], v158 offset:1024
	ds_read_b128 v[154:157], v158 offset:2048
	ds_read_b128 v[158:161], v158 offset:3072
	s_cbranch_vccnz .LBB0_694
	s_andn2_b64 vcc, exec, s[6:7]
	s_cbranch_vccnz .LBB0_693
	s_barrier
	s_branch .LBB0_693
